# GDN scan rewrite + GEMM K-loops: LDS-DMA staging rebalanced 2+6 -> 4+4 pieces per load segment (A stage issued one segment later, tighter counted waits)
# speedup vs baseline: 1.0087x; 1.0087x over previous
.LBB0_166:
	s_lshl_b32 s8, s8, 5
	s_and_b32 s14, s8, 0x60
	s_mov_b64 s[8:9], 0x80
	s_add_i32 m0, s38, 0x18000
	v_lshl_add_u64 v[8:9], v[8:9], 0, s[8:9]
	s_lshl_b32 s11, s10, 13
	s_lshl_b32 s15, s14, 7
	s_waitcnt vmcnt(2)
	s_barrier
	global_load_lds_dwordx4 v[8:9], off
	v_lshl_add_u64 v[6:7], v[6:7], 0, s[8:9]
	s_add_i32 m0, s38, 0x1a000
	s_add_i32 s43, s38, 0x8000
	s_add_i32 s44, s38, 0xa000
	global_load_lds_dwordx4 v[6:7], off
	v_lshl_add_u64 v[2:3], v[2:3], 0, s[8:9]
	s_mov_b32 m0, s43
	s_add_u32 s12, s30, 0x100080
	global_load_lds_dwordx4 v[2:3], off
	v_lshl_add_u64 v[2:3], v[4:5], 0, s[8:9]
	s_mov_b32 m0, s44
	s_addc_u32 s13, s31, 0
	global_load_lds_dwordx4 v[2:3], off
	s_add_i32 m0, s38, 0x1c000
	v_lshl_add_u64 v[2:3], s[12:13], 0, v[134:135]
	global_load_lds_dwordx4 v[2:3], off
	v_lshl_add_u64 v[2:3], s[12:13], 0, v[130:131]
	s_add_i32 m0, s38, 0x1e000
	v_lshlrev_b32_e32 v4, 2, v0
	global_load_lds_dwordx4 v[2:3], off
	v_and_b32_e32 v2, 15, v0
	v_lshlrev_b32_e32 v3, 1, v14
	v_lshl_or_b32 v1, s10, 6, v2
	v_lshl_or_b32 v2, v2, 6, v3
	v_and_b32_e32 v4, 32, v4
	s_sext_i32_i16 s52, s4
	v_bitop3_b32 v5, v2, s11, v4 bitop3:0xde
	v_lshlrev_b32_e32 v2, 6, v0
	s_movk_i32 s4, 0x3c0
	v_and_or_b32 v2, v2, s4, v3
	s_cmpk_lt_u32 s5, 0x100
	v_or_b32_e32 v164, s14, v14
	v_readlane_b32 s4, v247, 31
	v_bitop3_b32 v163, s15, v2, v4 bitop3:0xf6
	v_lshlrev_b32_e32 v2, 2, v164
	v_mov_b32_e32 v3, v135
	v_readlane_b32 s5, v247, 32
	s_waitcnt vmcnt(6)
	s_cselect_b64 s[10:11], -1, 0
	s_add_i32 s46, 0, 0x10000
	v_lshl_add_u64 v[138:139], s[4:5], 0, v[2:3]
	v_lshlrev_b32_e32 v2, 10, v0
	v_and_b32_e32 v2, 0x60000, v2
	v_lshlrev_b32_e32 v3, 13, v13
	v_or3_b32 v2, v11, v2, v3
	v_add_u32_e32 v140, v2, v12
	v_lshlrev_b32_e32 v2, 6, v10
	v_and_b32_e32 v2, 0xe0000, v2
	v_or3_b32 v2, v11, v2, v3
	s_add_i32 s47, 0, 0x14000
	s_ashr_i32 s45, s96, 31
	v_mov_b32_e32 v141, v135
	v_add_u32_e32 v142, v2, v12
	v_mov_b32_e32 v143, v135
	v_mov_b64_e32 v[144:145], 0x6a0
	v_mov_b64_e32 v[146:147], 0x69f
	v_add_u32_e32 v165, s46, v163
	v_add_u32_e32 v166, s47, v163
	v_add_u32_e32 v167, 0, v5
	s_mov_b64 s[12:13], 0x24000
	s_mov_b32 s48, 0x24000
	s_mov_b64 s[14:15], 0x28000
	s_mov_b32 s49, 0x28000
	s_mov_b64 s[16:17], 0x2c000
	s_mov_b32 s50, 0x2c000
	s_movk_i32 s51, 0x6800
	s_barrier
	s_mov_b32 s32, 0
	s_branch .LBB0_169

.LBB0_172:
	ds_read_b128 v[148:151], v165
	ds_read_b128 v[152:155], v165 offset:1024
	ds_read_b128 v[156:159], v165 offset:2048
	ds_read_b128 v[168:171], v165 offset:3072
	ds_read_b128 v[172:175], v166
	ds_read_b128 v[176:179], v166 offset:1024
	ds_read_b128 v[180:183], v166 offset:2048
	ds_read_b128 v[184:187], v166 offset:3072
	s_add_u32 s30, s28, 0xfff00080
	s_addc_u32 s31, s29, -1
	s_cmp_eq_u32 s56, 60
	s_cselect_b32 s35, s21, s31
	s_cselect_b32 s34, s27, s30
	s_cselect_b32 s31, s19, s55
	s_cselect_b32 s30, s53, s54
	v_lshl_add_u64 v[160:161], s[28:29], 0, v[140:141]
	s_add_i32 m0, s38, 0xc000
	ds_read_b128 v[188:191], v167
	ds_read_b128 v[192:195], v167 offset:1024
	ds_read_b128 v[196:199], v167 offset:2048
	ds_read_b128 v[200:203], v167 offset:3072
	ds_read_b128 v[204:207], v167 offset:4096
	ds_read_b128 v[208:211], v167 offset:5120
	ds_read_b128 v[212:215], v167 offset:6144
	ds_read_b128 v[216:219], v167 offset:7168
	s_cmp_lg_u32 s32, 0
	s_cbranch_scc0 .Lrebal_skip_172
	s_mov_b32 m0, s43
	s_nop 0
	global_load_lds_dwordx4 v[222:223], off
	s_mov_b32 m0, s44
	s_nop 0
	global_load_lds_dwordx4 v[224:225], off
.Lrebal_skip_172:
	s_add_i32 m0, s38, 0xc000
	s_nop 0
	global_load_lds_dwordx4 v[160:161], off
	v_lshl_add_u64 v[160:161], s[28:29], 0, v[142:143]
	s_add_i32 m0, s38, 0xe000
	s_nop 0
	global_load_lds_dwordx4 v[160:161], off
	s_waitcnt vmcnt(8)
	s_waitcnt lgkmcnt(0)
	s_barrier
	s_setprio 1
	s_waitcnt lgkmcnt(0)
	v_mfma_f32_16x16x32_bf16 v[126:129], v[148:151], v[188:191], v[126:129]
	v_mfma_f32_16x16x32_bf16 v[122:125], v[156:159], v[188:191], v[122:125]
	v_mfma_f32_16x16x32_bf16 v[110:113], v[148:151], v[196:199], v[110:113]
	v_mfma_f32_16x16x32_bf16 v[106:109], v[156:159], v[196:199], v[106:109]
	v_mfma_f32_16x16x32_bf16 v[94:97], v[148:151], v[204:207], v[94:97]
	v_mfma_f32_16x16x32_bf16 v[90:93], v[156:159], v[204:207], v[90:93]
	v_mfma_f32_16x16x32_bf16 v[86:89], v[148:151], v[212:215], v[86:89]
	v_mfma_f32_16x16x32_bf16 v[78:81], v[156:159], v[212:215], v[78:81]
	v_mfma_f32_16x16x32_bf16 v[126:129], v[152:155], v[192:195], v[126:129]
	v_mfma_f32_16x16x32_bf16 v[122:125], v[168:171], v[192:195], v[122:125]
	v_mfma_f32_16x16x32_bf16 v[110:113], v[152:155], v[200:203], v[110:113]
	v_mfma_f32_16x16x32_bf16 v[106:109], v[168:171], v[200:203], v[106:109]
	v_mfma_f32_16x16x32_bf16 v[94:97], v[152:155], v[208:211], v[94:97]
	v_mfma_f32_16x16x32_bf16 v[90:93], v[168:171], v[208:211], v[90:93]
	v_mfma_f32_16x16x32_bf16 v[86:89], v[152:155], v[216:219], v[86:89]
	v_mfma_f32_16x16x32_bf16 v[78:81], v[168:171], v[216:219], v[78:81]
	s_setprio 0
	s_setprio 1
	v_mfma_f32_16x16x32_bf16 v[118:121], v[172:175], v[188:191], v[118:121]
	v_mfma_f32_16x16x32_bf16 v[114:117], v[180:183], v[188:191], v[114:117]
	v_mfma_f32_16x16x32_bf16 v[102:105], v[172:175], v[196:199], v[102:105]
	v_mfma_f32_16x16x32_bf16 v[98:101], v[180:183], v[196:199], v[98:101]
	v_mfma_f32_16x16x32_bf16 v[82:85], v[172:175], v[204:207], v[82:85]
	v_mfma_f32_16x16x32_bf16 v[74:77], v[180:183], v[204:207], v[74:77]
	v_mfma_f32_16x16x32_bf16 v[70:73], v[172:175], v[212:215], v[70:73]
	v_mfma_f32_16x16x32_bf16 v[66:69], v[180:183], v[212:215], v[66:69]
	v_mfma_f32_16x16x32_bf16 v[118:121], v[176:179], v[192:195], v[118:121]
	v_mfma_f32_16x16x32_bf16 v[114:117], v[184:187], v[192:195], v[114:117]
	v_mfma_f32_16x16x32_bf16 v[102:105], v[176:179], v[200:203], v[102:105]
	v_mfma_f32_16x16x32_bf16 v[98:101], v[184:187], v[200:203], v[98:101]
	v_mfma_f32_16x16x32_bf16 v[82:85], v[176:179], v[208:211], v[82:85]
	v_mfma_f32_16x16x32_bf16 v[74:77], v[184:187], v[208:211], v[74:77]
	v_mfma_f32_16x16x32_bf16 v[70:73], v[176:179], v[216:219], v[70:73]
	v_mfma_f32_16x16x32_bf16 v[66:69], v[184:187], v[216:219], v[66:69]
	s_setprio 0
	s_barrier
	s_add_i32 s57, s46, s33
	v_lshl_add_u64 v[160:161], s[30:31], 0, v[134:135]
	s_mov_b32 m0, s57
	ds_read_b128 v[188:191], v167 offset:16384
	ds_read_b128 v[192:195], v167 offset:17408
	ds_read_b128 v[196:199], v167 offset:18432
	ds_read_b128 v[200:203], v167 offset:19456
	ds_read_b128 v[204:207], v167 offset:20480
	ds_read_b128 v[208:211], v167 offset:21504
	ds_read_b128 v[212:215], v167 offset:22528
	ds_read_b128 v[216:219], v167 offset:23552
	global_load_lds_dwordx4 v[160:161], off
	s_add_i32 m0, s57, 0x2000
	s_add_u32 s58, s30, 0x100000
	v_lshl_add_u64 v[220:221], s[30:31], 0, v[130:131]
	s_addc_u32 s59, s31, 0
	s_add_i32 s57, s47, s33
	global_load_lds_dwordx4 v[220:221], off
	v_lshl_add_u64 v[222:223], s[58:59], 0, v[134:135]
	s_mov_b32 m0, s57
	v_lshl_add_u64 v[224:225], s[34:35], 0, v[132:133]
	global_load_lds_dwordx4 v[222:223], off
	v_lshl_add_u64 v[222:223], s[58:59], 0, v[130:131]
	s_add_i32 m0, s57, 0x2000
	s_nop 0
	global_load_lds_dwordx4 v[222:223], off
	v_lshl_add_u64 v[222:223], s[34:35], 0, v[136:137]
	s_waitcnt vmcnt(6)
	s_waitcnt lgkmcnt(0)
	s_barrier
	s_setprio 1
	s_waitcnt lgkmcnt(0)
	v_mfma_f32_16x16x32_bf16 v[62:65], v[148:151], v[188:191], v[62:65]
	v_mfma_f32_16x16x32_bf16 v[58:61], v[156:159], v[188:191], v[58:61]
	v_mfma_f32_16x16x32_bf16 v[46:49], v[148:151], v[196:199], v[46:49]
	v_mfma_f32_16x16x32_bf16 v[42:45], v[156:159], v[196:199], v[42:45]
	v_mfma_f32_16x16x32_bf16 v[30:33], v[148:151], v[204:207], v[30:33]
	v_mfma_f32_16x16x32_bf16 v[26:29], v[156:159], v[204:207], v[26:29]
	v_mfma_f32_16x16x32_bf16 v[14:17], v[148:151], v[212:215], v[14:17]
	v_mfma_f32_16x16x32_bf16 v[10:13], v[156:159], v[212:215], v[10:13]
	v_mfma_f32_16x16x32_bf16 v[62:65], v[152:155], v[192:195], v[62:65]
	v_mfma_f32_16x16x32_bf16 v[58:61], v[168:171], v[192:195], v[58:61]
	v_mfma_f32_16x16x32_bf16 v[46:49], v[152:155], v[200:203], v[46:49]
	v_mfma_f32_16x16x32_bf16 v[42:45], v[168:171], v[200:203], v[42:45]
	v_mfma_f32_16x16x32_bf16 v[30:33], v[152:155], v[208:211], v[30:33]
	v_mfma_f32_16x16x32_bf16 v[26:29], v[168:171], v[208:211], v[26:29]
	v_mfma_f32_16x16x32_bf16 v[14:17], v[152:155], v[216:219], v[14:17]
	v_mfma_f32_16x16x32_bf16 v[10:13], v[168:171], v[216:219], v[10:13]
	s_setprio 0
	s_setprio 1
	v_mfma_f32_16x16x32_bf16 v[54:57], v[172:175], v[188:191], v[54:57]
	v_mfma_f32_16x16x32_bf16 v[50:53], v[180:183], v[188:191], v[50:53]
	v_mfma_f32_16x16x32_bf16 v[38:41], v[172:175], v[196:199], v[38:41]
	v_mfma_f32_16x16x32_bf16 v[34:37], v[180:183], v[196:199], v[34:37]
	v_mfma_f32_16x16x32_bf16 v[22:25], v[172:175], v[204:207], v[22:25]
	v_mfma_f32_16x16x32_bf16 v[18:21], v[180:183], v[204:207], v[18:21]
	v_mfma_f32_16x16x32_bf16 v[6:9], v[172:175], v[212:215], v[6:9]
	v_mfma_f32_16x16x32_bf16 v[2:5], v[180:183], v[212:215], v[2:5]
	v_mfma_f32_16x16x32_bf16 v[54:57], v[176:179], v[192:195], v[54:57]
	v_mfma_f32_16x16x32_bf16 v[50:53], v[184:187], v[192:195], v[50:53]
	v_mfma_f32_16x16x32_bf16 v[38:41], v[176:179], v[200:203], v[38:41]
	v_mfma_f32_16x16x32_bf16 v[34:37], v[184:187], v[200:203], v[34:37]
	v_mfma_f32_16x16x32_bf16 v[22:25], v[176:179], v[208:211], v[22:25]
	v_mfma_f32_16x16x32_bf16 v[18:21], v[184:187], v[208:211], v[18:21]
	v_mfma_f32_16x16x32_bf16 v[6:9], v[176:179], v[216:219], v[6:9]
	v_mfma_f32_16x16x32_bf16 v[2:5], v[184:187], v[216:219], v[2:5]
	s_setprio 0
	s_barrier
	s_add_i32 s57, 0, 0x18000
	s_add_i32 s58, 0, 0x1c000
	v_add_u32_e32 v168, s57, v163
	v_add_u32_e32 v184, s58, v163
	ds_read_b128 v[148:151], v168
	ds_read_b128 v[152:155], v168 offset:1024
	ds_read_b128 v[156:159], v168 offset:2048
	ds_read_b128 v[168:171], v168 offset:3072
	ds_read_b128 v[172:175], v184
	ds_read_b128 v[176:179], v184 offset:1024
	ds_read_b128 v[180:183], v184 offset:2048
	ds_read_b128 v[184:187], v184 offset:3072
	s_add_u32 s34, s34, 0x100000
	s_addc_u32 s35, s35, 0
	s_mov_b32 m0, s40
	v_lshl_add_u64 v[226:227], s[34:35], 0, v[136:137]
	ds_read_b128 v[188:191], v167 offset:32768
	ds_read_b128 v[192:195], v167 offset:33792
	ds_read_b128 v[196:199], v167 offset:34816
	ds_read_b128 v[200:203], v167 offset:35840
	ds_read_b128 v[204:207], v167 offset:36864
	ds_read_b128 v[208:211], v167 offset:37888
	ds_read_b128 v[212:215], v167 offset:38912
	ds_read_b128 v[216:219], v167 offset:39936
	s_mov_b32 m0, s38
	s_nop 0
	global_load_lds_dwordx4 v[222:223], off
	s_mov_b32 m0, s39
	s_nop 0
	global_load_lds_dwordx4 v[224:225], off
	s_mov_b32 m0, s40
	s_nop 0
	global_load_lds_dwordx4 v[226:227], off
	v_lshl_add_u64 v[226:227], s[34:35], 0, v[132:133]
	s_mov_b32 m0, s41
	s_nop 0
	global_load_lds_dwordx4 v[226:227], off
	s_waitcnt vmcnt(8)
	s_waitcnt lgkmcnt(0)
	s_barrier
	s_setprio 1
	s_waitcnt lgkmcnt(0)
	v_mfma_f32_16x16x32_bf16 v[126:129], v[148:151], v[188:191], v[126:129]
	v_mfma_f32_16x16x32_bf16 v[122:125], v[156:159], v[188:191], v[122:125]
	v_mfma_f32_16x16x32_bf16 v[110:113], v[148:151], v[196:199], v[110:113]
	v_mfma_f32_16x16x32_bf16 v[106:109], v[156:159], v[196:199], v[106:109]
	v_mfma_f32_16x16x32_bf16 v[94:97], v[148:151], v[204:207], v[94:97]
	v_mfma_f32_16x16x32_bf16 v[90:93], v[156:159], v[204:207], v[90:93]
	v_mfma_f32_16x16x32_bf16 v[86:89], v[148:151], v[212:215], v[86:89]
	v_mfma_f32_16x16x32_bf16 v[78:81], v[156:159], v[212:215], v[78:81]
	v_mfma_f32_16x16x32_bf16 v[126:129], v[152:155], v[192:195], v[126:129]
	v_mfma_f32_16x16x32_bf16 v[122:125], v[168:171], v[192:195], v[122:125]
	v_mfma_f32_16x16x32_bf16 v[110:113], v[152:155], v[200:203], v[110:113]
	v_mfma_f32_16x16x32_bf16 v[106:109], v[168:171], v[200:203], v[106:109]
	v_mfma_f32_16x16x32_bf16 v[94:97], v[152:155], v[208:211], v[94:97]
	v_mfma_f32_16x16x32_bf16 v[90:93], v[168:171], v[208:211], v[90:93]
	v_mfma_f32_16x16x32_bf16 v[86:89], v[152:155], v[216:219], v[86:89]
	v_mfma_f32_16x16x32_bf16 v[78:81], v[168:171], v[216:219], v[78:81]
	s_setprio 0
	s_setprio 1
	v_mfma_f32_16x16x32_bf16 v[118:121], v[172:175], v[188:191], v[118:121]
	v_mfma_f32_16x16x32_bf16 v[114:117], v[180:183], v[188:191], v[114:117]
	v_mfma_f32_16x16x32_bf16 v[102:105], v[172:175], v[196:199], v[102:105]
	v_mfma_f32_16x16x32_bf16 v[98:101], v[180:183], v[196:199], v[98:101]
	v_mfma_f32_16x16x32_bf16 v[82:85], v[172:175], v[204:207], v[82:85]
	v_mfma_f32_16x16x32_bf16 v[74:77], v[180:183], v[204:207], v[74:77]
	v_mfma_f32_16x16x32_bf16 v[70:73], v[172:175], v[212:215], v[70:73]
	v_mfma_f32_16x16x32_bf16 v[66:69], v[180:183], v[212:215], v[66:69]
	v_mfma_f32_16x16x32_bf16 v[118:121], v[176:179], v[192:195], v[118:121]
	v_mfma_f32_16x16x32_bf16 v[114:117], v[184:187], v[192:195], v[114:117]
	v_mfma_f32_16x16x32_bf16 v[102:105], v[176:179], v[200:203], v[102:105]
	v_mfma_f32_16x16x32_bf16 v[98:101], v[184:187], v[200:203], v[98:101]
	v_mfma_f32_16x16x32_bf16 v[82:85], v[176:179], v[208:211], v[82:85]
	v_mfma_f32_16x16x32_bf16 v[74:77], v[184:187], v[208:211], v[74:77]
	v_mfma_f32_16x16x32_bf16 v[70:73], v[176:179], v[216:219], v[70:73]
	v_mfma_f32_16x16x32_bf16 v[66:69], v[184:187], v[216:219], v[66:69]
	s_setprio 0
	s_barrier
	s_add_i32 s34, s57, s33
	v_lshl_add_u64 v[160:161], v[160:161], 0, s[8:9]
	s_mov_b32 m0, s34
	ds_read_b128 v[188:191], v167 offset:49152
	ds_read_b128 v[192:195], v167 offset:50176
	ds_read_b128 v[196:199], v167 offset:51200
	ds_read_b128 v[200:203], v167 offset:52224
	ds_read_b128 v[204:207], v167 offset:53248
	ds_read_b128 v[208:211], v167 offset:54272
	ds_read_b128 v[212:215], v167 offset:55296
	ds_read_b128 v[216:219], v167 offset:56320
	global_load_lds_dwordx4 v[160:161], off
	s_add_i32 m0, s34, 0x2000
	s_add_u32 s30, s30, 0x100080
	v_lshl_add_u64 v[160:161], v[220:221], 0, s[8:9]
	s_addc_u32 s31, s31, 0
	s_add_i32 s34, s58, s33
	global_load_lds_dwordx4 v[160:161], off
	v_lshl_add_u64 v[160:161], s[30:31], 0, v[134:135]
	s_mov_b32 m0, s34
	s_nop 0
	global_load_lds_dwordx4 v[160:161], off
	v_lshl_add_u64 v[160:161], s[30:31], 0, v[130:131]
	s_add_i32 m0, s34, 0x2000
	s_nop 0
	global_load_lds_dwordx4 v[160:161], off
	v_lshl_add_u64 v[222:223], v[222:223], 0, s[8:9]
	v_lshl_add_u64 v[224:225], v[224:225], 0, s[8:9]
	s_waitcnt vmcnt(6)
	s_waitcnt lgkmcnt(0)
	s_barrier
	s_setprio 1
	s_waitcnt lgkmcnt(0)
	v_mfma_f32_16x16x32_bf16 v[62:65], v[148:151], v[188:191], v[62:65]
	v_mfma_f32_16x16x32_bf16 v[58:61], v[156:159], v[188:191], v[58:61]
	v_mfma_f32_16x16x32_bf16 v[46:49], v[148:151], v[196:199], v[46:49]
	v_mfma_f32_16x16x32_bf16 v[42:45], v[156:159], v[196:199], v[42:45]
	v_mfma_f32_16x16x32_bf16 v[30:33], v[148:151], v[204:207], v[30:33]
	v_mfma_f32_16x16x32_bf16 v[26:29], v[156:159], v[204:207], v[26:29]
	v_mfma_f32_16x16x32_bf16 v[14:17], v[148:151], v[212:215], v[14:17]
	v_mfma_f32_16x16x32_bf16 v[10:13], v[156:159], v[212:215], v[10:13]
	v_mfma_f32_16x16x32_bf16 v[62:65], v[152:155], v[192:195], v[62:65]
	v_mfma_f32_16x16x32_bf16 v[58:61], v[168:171], v[192:195], v[58:61]
	v_mfma_f32_16x16x32_bf16 v[46:49], v[152:155], v[200:203], v[46:49]
	v_mfma_f32_16x16x32_bf16 v[42:45], v[168:171], v[200:203], v[42:45]
	v_mfma_f32_16x16x32_bf16 v[30:33], v[152:155], v[208:211], v[30:33]
	v_mfma_f32_16x16x32_bf16 v[26:29], v[168:171], v[208:211], v[26:29]
	v_mfma_f32_16x16x32_bf16 v[14:17], v[152:155], v[216:219], v[14:17]
	v_mfma_f32_16x16x32_bf16 v[10:13], v[168:171], v[216:219], v[10:13]
	s_setprio 0
	s_setprio 1
	v_mfma_f32_16x16x32_bf16 v[54:57], v[172:175], v[188:191], v[54:57]
	v_mfma_f32_16x16x32_bf16 v[50:53], v[180:183], v[188:191], v[50:53]
	v_mfma_f32_16x16x32_bf16 v[38:41], v[172:175], v[196:199], v[38:41]
	v_mfma_f32_16x16x32_bf16 v[34:37], v[180:183], v[196:199], v[34:37]
	v_mfma_f32_16x16x32_bf16 v[22:25], v[172:175], v[204:207], v[22:25]
	v_mfma_f32_16x16x32_bf16 v[18:21], v[180:183], v[204:207], v[18:21]
	v_mfma_f32_16x16x32_bf16 v[6:9], v[172:175], v[212:215], v[6:9]
	v_mfma_f32_16x16x32_bf16 v[2:5], v[180:183], v[212:215], v[2:5]
	v_mfma_f32_16x16x32_bf16 v[54:57], v[176:179], v[192:195], v[54:57]
	v_mfma_f32_16x16x32_bf16 v[50:53], v[184:187], v[192:195], v[50:53]
	v_mfma_f32_16x16x32_bf16 v[38:41], v[176:179], v[200:203], v[38:41]
	v_mfma_f32_16x16x32_bf16 v[34:37], v[184:187], v[200:203], v[34:37]
	v_mfma_f32_16x16x32_bf16 v[22:25], v[176:179], v[208:211], v[22:25]
	v_mfma_f32_16x16x32_bf16 v[18:21], v[184:187], v[208:211], v[18:21]
	v_mfma_f32_16x16x32_bf16 v[6:9], v[176:179], v[216:219], v[6:9]
	v_mfma_f32_16x16x32_bf16 v[2:5], v[184:187], v[216:219], v[2:5]
	s_setprio 0
	s_barrier
	s_add_i32 s56, s56, 2
	s_mov_b32 s32, 1
	s_add_u32 s28, s28, 0x100
	s_addc_u32 s29, s29, 0
	s_add_u32 s54, s54, 0x100
	s_addc_u32 s55, s55, 0
	s_cmp_gt_u32 s56, 61
	s_cbranch_scc0 .LBB0_172
	s_and_b64 vcc, exec, s[10:11]
	s_cbranch_vccz .LBB0_175
	s_barrier

.LBB0_686:
	s_lshl_b32 s6, s6, 5
	s_and_b32 s12, s6, 0x60
	s_mov_b64 s[6:7], 0x80
	s_add_i32 m0, s21, 0x18000
	v_lshl_add_u64 v[8:9], v[8:9], 0, s[6:7]
	s_lshl_b32 s9, s8, 13
	s_lshl_b32 s13, s12, 7
	s_waitcnt vmcnt(2)
	s_barrier
	global_load_lds_dwordx4 v[8:9], off
	v_lshl_add_u64 v[4:5], v[4:5], 0, s[6:7]
	s_add_i32 m0, s21, 0x1a000
	s_add_i32 s35, s21, 0x8000
	s_add_i32 s36, s21, 0xa000
	global_load_lds_dwordx4 v[4:5], off
	v_lshl_add_u64 v[2:3], v[2:3], 0, s[6:7]
	s_mov_b32 m0, s35
	s_add_u32 s10, s24, 0x100080
	global_load_lds_dwordx4 v[2:3], off
	v_lshl_add_u64 v[2:3], v[6:7], 0, s[6:7]
	s_mov_b32 m0, s36
	s_addc_u32 s11, s25, 0
	global_load_lds_dwordx4 v[2:3], off
	s_add_i32 m0, s21, 0x1c000
	v_lshl_add_u64 v[2:3], s[10:11], 0, v[132:133]
	global_load_lds_dwordx4 v[2:3], off
	v_lshl_add_u64 v[2:3], s[10:11], 0, v[136:137]
	s_add_i32 m0, s21, 0x1e000
	s_sext_i32_i8 s42, s4
	global_load_lds_dwordx4 v[2:3], off
	v_and_b32_e32 v2, 15, v0
	v_lshlrev_b32_e32 v3, 1, v13
	v_lshlrev_b32_e32 v4, 2, v0
	v_lshlrev_b32_e32 v5, 6, v0
	s_movk_i32 s4, 0x3c0
	v_lshl_or_b32 v1, s8, 6, v2
	v_lshl_or_b32 v2, v2, 6, v3
	v_and_b32_e32 v4, 32, v4
	v_and_or_b32 v3, v5, s4, v3
	v_bitop3_b32 v148, s13, v3, v4 bitop3:0xf6
	v_lshlrev_b32_e32 v3, 10, v0
	v_bitop3_b32 v2, v2, s9, v4 bitop3:0xde
	v_and_b32_e32 v3, 0x60000, v3
	v_lshlrev_b32_e32 v4, 13, v12
	v_or3_b32 v3, v10, v3, v4
	v_add_u32_e32 v138, v3, v11
	v_lshlrev_b32_e32 v3, 6, v14
	s_waitcnt vmcnt(6)
	s_cmpk_lt_u32 s5, 0x100
	v_and_b32_e32 v3, 0xe0000, v3
	s_cselect_b64 s[8:9], -1, 0
	v_or3_b32 v3, v10, v3, v4
	s_add_i32 s38, 0, 0x10000
	s_add_i32 s39, 0, 0x14000
	s_ashr_i32 s37, s96, 31
	v_or_b32_e32 v149, s12, v13
	v_mov_b32_e32 v139, v133
	v_add_u32_e32 v140, v3, v11
	v_mov_b32_e32 v141, v133
	v_mov_b64_e32 v[142:143], 0x200
	v_mov_b64_e32 v[144:145], 0x1ff
	v_add_u32_e32 v150, s38, v148
	v_add_u32_e32 v151, s39, v148
	v_add_u32_e32 v152, 0, v2
	s_mov_b32 s40, 0x140000
	s_mov_b64 s[10:11], 0x160000
	s_mov_b32 s41, 0x160000
	s_barrier
	s_mov_b32 s32, 0
	s_branch .LBB0_689

.LBB0_696:
	ds_read_b128 v[154:157], v150
	ds_read_b128 v[158:161], v150 offset:1024
	ds_read_b128 v[164:167], v150 offset:2048
	ds_read_b128 v[168:171], v150 offset:3072
	ds_read_b128 v[172:175], v151
	ds_read_b128 v[176:179], v151 offset:1024
	ds_read_b128 v[180:183], v151 offset:2048
	ds_read_b128 v[184:187], v151 offset:3072
	s_add_u32 s24, s22, 0xfff00080
	s_addc_u32 s25, s23, -1
	s_cmp_eq_u32 s47, 60
	s_cselect_b32 s27, s15, s25
	s_cselect_b32 s26, s43, s24
	s_cselect_b32 s25, s13, s46
	s_cselect_b32 s24, s44, s45
	v_lshl_add_u64 v[146:147], s[22:23], 0, v[138:139]
	s_add_i32 m0, s21, 0xc000
	ds_read_b128 v[188:191], v152
	ds_read_b128 v[192:195], v152 offset:1024
	ds_read_b128 v[196:199], v152 offset:2048
	ds_read_b128 v[200:203], v152 offset:3072
	ds_read_b128 v[204:207], v152 offset:4096
	ds_read_b128 v[208:211], v152 offset:5120
	ds_read_b128 v[212:215], v152 offset:6144
	ds_read_b128 v[216:219], v152 offset:7168
	s_cmp_lg_u32 s32, 0
	s_cbranch_scc0 .Lrebal_skip_696
	s_mov_b32 m0, s35
	s_nop 0
	global_load_lds_dwordx4 v[222:223], off
	s_mov_b32 m0, s36
	s_nop 0
	global_load_lds_dwordx4 v[224:225], off
.Lrebal_skip_696:
	s_add_i32 m0, s21, 0xc000
	s_nop 0
	global_load_lds_dwordx4 v[146:147], off
	v_lshl_add_u64 v[146:147], s[22:23], 0, v[140:141]
	s_add_i32 m0, s21, 0xe000
	s_nop 0
	global_load_lds_dwordx4 v[146:147], off
	s_waitcnt vmcnt(8)
	s_waitcnt lgkmcnt(0)
	s_barrier
	s_setprio 1
	s_waitcnt lgkmcnt(0)
	v_mfma_f32_16x16x32_bf16 v[126:129], v[154:157], v[188:191], v[126:129]
	v_mfma_f32_16x16x32_bf16 v[122:125], v[164:167], v[188:191], v[122:125]
	v_mfma_f32_16x16x32_bf16 v[118:121], v[154:157], v[196:199], v[118:121]
	v_mfma_f32_16x16x32_bf16 v[110:113], v[164:167], v[196:199], v[110:113]
	v_mfma_f32_16x16x32_bf16 v[102:105], v[154:157], v[204:207], v[102:105]
	v_mfma_f32_16x16x32_bf16 v[94:97], v[164:167], v[204:207], v[94:97]
	v_mfma_f32_16x16x32_bf16 v[82:85], v[154:157], v[212:215], v[82:85]
	v_mfma_f32_16x16x32_bf16 v[74:77], v[164:167], v[212:215], v[74:77]
	v_mfma_f32_16x16x32_bf16 v[126:129], v[158:161], v[192:195], v[126:129]
	v_mfma_f32_16x16x32_bf16 v[122:125], v[168:171], v[192:195], v[122:125]
	v_mfma_f32_16x16x32_bf16 v[118:121], v[158:161], v[200:203], v[118:121]
	v_mfma_f32_16x16x32_bf16 v[110:113], v[168:171], v[200:203], v[110:113]
	v_mfma_f32_16x16x32_bf16 v[102:105], v[158:161], v[208:211], v[102:105]
	v_mfma_f32_16x16x32_bf16 v[94:97], v[168:171], v[208:211], v[94:97]
	v_mfma_f32_16x16x32_bf16 v[82:85], v[158:161], v[216:219], v[82:85]
	v_mfma_f32_16x16x32_bf16 v[74:77], v[168:171], v[216:219], v[74:77]
	s_setprio 0
	s_setprio 1
	v_mfma_f32_16x16x32_bf16 v[114:117], v[172:175], v[188:191], v[114:117]
	v_mfma_f32_16x16x32_bf16 v[106:109], v[180:183], v[188:191], v[106:109]
	v_mfma_f32_16x16x32_bf16 v[98:101], v[172:175], v[196:199], v[98:101]
	v_mfma_f32_16x16x32_bf16 v[90:93], v[180:183], v[196:199], v[90:93]
	v_mfma_f32_16x16x32_bf16 v[86:89], v[172:175], v[204:207], v[86:89]
	v_mfma_f32_16x16x32_bf16 v[78:81], v[180:183], v[204:207], v[78:81]
	v_mfma_f32_16x16x32_bf16 v[70:73], v[172:175], v[212:215], v[70:73]
	v_mfma_f32_16x16x32_bf16 v[66:69], v[180:183], v[212:215], v[66:69]
	v_mfma_f32_16x16x32_bf16 v[114:117], v[176:179], v[192:195], v[114:117]
	v_mfma_f32_16x16x32_bf16 v[106:109], v[184:187], v[192:195], v[106:109]
	v_mfma_f32_16x16x32_bf16 v[98:101], v[176:179], v[200:203], v[98:101]
	v_mfma_f32_16x16x32_bf16 v[90:93], v[184:187], v[200:203], v[90:93]
	v_mfma_f32_16x16x32_bf16 v[86:89], v[176:179], v[208:211], v[86:89]
	v_mfma_f32_16x16x32_bf16 v[78:81], v[184:187], v[208:211], v[78:81]
	v_mfma_f32_16x16x32_bf16 v[70:73], v[176:179], v[216:219], v[70:73]
	v_mfma_f32_16x16x32_bf16 v[66:69], v[184:187], v[216:219], v[66:69]
	s_setprio 0
	s_barrier
	s_add_i32 s48, s38, s29
	v_lshl_add_u64 v[146:147], s[24:25], 0, v[132:133]
	s_mov_b32 m0, s48
	ds_read_b128 v[188:191], v152 offset:16384
	ds_read_b128 v[192:195], v152 offset:17408
	ds_read_b128 v[196:199], v152 offset:18432
	ds_read_b128 v[200:203], v152 offset:19456
	ds_read_b128 v[204:207], v152 offset:20480
	ds_read_b128 v[208:211], v152 offset:21504
	ds_read_b128 v[212:215], v152 offset:22528
	ds_read_b128 v[216:219], v152 offset:23552
	global_load_lds_dwordx4 v[146:147], off
	s_add_i32 m0, s48, 0x2000
	s_add_u32 s48, s24, 0x100000
	v_lshl_add_u64 v[220:221], s[24:25], 0, v[136:137]
	s_addc_u32 s49, s25, 0
	s_add_i32 s50, s39, s29
	global_load_lds_dwordx4 v[220:221], off
	v_lshl_add_u64 v[222:223], s[48:49], 0, v[132:133]
	s_mov_b32 m0, s50
	v_lshl_add_u64 v[224:225], s[26:27], 0, v[134:135]
	global_load_lds_dwordx4 v[222:223], off
	v_lshl_add_u64 v[222:223], s[48:49], 0, v[136:137]
	s_add_i32 m0, s50, 0x2000
	s_nop 0
	global_load_lds_dwordx4 v[222:223], off
	v_lshl_add_u64 v[222:223], s[26:27], 0, v[130:131]
	s_waitcnt vmcnt(6)
	s_waitcnt lgkmcnt(0)
	s_barrier
	s_setprio 1
	s_waitcnt lgkmcnt(0)
	v_mfma_f32_16x16x32_bf16 v[62:65], v[154:157], v[188:191], v[62:65]
	v_mfma_f32_16x16x32_bf16 v[58:61], v[164:167], v[188:191], v[58:61]
	v_mfma_f32_16x16x32_bf16 v[54:57], v[154:157], v[196:199], v[54:57]
	v_mfma_f32_16x16x32_bf16 v[46:49], v[164:167], v[196:199], v[46:49]
	v_mfma_f32_16x16x32_bf16 v[38:41], v[154:157], v[204:207], v[38:41]
	v_mfma_f32_16x16x32_bf16 v[30:33], v[164:167], v[204:207], v[30:33]
	v_mfma_f32_16x16x32_bf16 v[22:25], v[154:157], v[212:215], v[22:25]
	v_mfma_f32_16x16x32_bf16 v[14:17], v[164:167], v[212:215], v[14:17]
	v_mfma_f32_16x16x32_bf16 v[62:65], v[158:161], v[192:195], v[62:65]
	v_mfma_f32_16x16x32_bf16 v[58:61], v[168:171], v[192:195], v[58:61]
	v_mfma_f32_16x16x32_bf16 v[54:57], v[158:161], v[200:203], v[54:57]
	v_mfma_f32_16x16x32_bf16 v[46:49], v[168:171], v[200:203], v[46:49]
	v_mfma_f32_16x16x32_bf16 v[38:41], v[158:161], v[208:211], v[38:41]
	v_mfma_f32_16x16x32_bf16 v[30:33], v[168:171], v[208:211], v[30:33]
	v_mfma_f32_16x16x32_bf16 v[22:25], v[158:161], v[216:219], v[22:25]
	v_mfma_f32_16x16x32_bf16 v[14:17], v[168:171], v[216:219], v[14:17]
	s_setprio 0
	s_setprio 1
	v_mfma_f32_16x16x32_bf16 v[50:53], v[172:175], v[188:191], v[50:53]
	v_mfma_f32_16x16x32_bf16 v[42:45], v[180:183], v[188:191], v[42:45]
	v_mfma_f32_16x16x32_bf16 v[34:37], v[172:175], v[196:199], v[34:37]
	v_mfma_f32_16x16x32_bf16 v[26:29], v[180:183], v[196:199], v[26:29]
	v_mfma_f32_16x16x32_bf16 v[18:21], v[172:175], v[204:207], v[18:21]
	v_mfma_f32_16x16x32_bf16 v[10:13], v[180:183], v[204:207], v[10:13]
	v_mfma_f32_16x16x32_bf16 v[6:9], v[172:175], v[212:215], v[6:9]
	v_mfma_f32_16x16x32_bf16 v[2:5], v[180:183], v[212:215], v[2:5]
	v_mfma_f32_16x16x32_bf16 v[50:53], v[176:179], v[192:195], v[50:53]
	v_mfma_f32_16x16x32_bf16 v[42:45], v[184:187], v[192:195], v[42:45]
	v_mfma_f32_16x16x32_bf16 v[34:37], v[176:179], v[200:203], v[34:37]
	v_mfma_f32_16x16x32_bf16 v[26:29], v[184:187], v[200:203], v[26:29]
	v_mfma_f32_16x16x32_bf16 v[18:21], v[176:179], v[208:211], v[18:21]
	v_mfma_f32_16x16x32_bf16 v[10:13], v[184:187], v[208:211], v[10:13]
	v_mfma_f32_16x16x32_bf16 v[6:9], v[176:179], v[216:219], v[6:9]
	v_mfma_f32_16x16x32_bf16 v[2:5], v[184:187], v[216:219], v[2:5]
	s_setprio 0
	s_barrier
	s_add_i32 s48, 0, 0x18000
	v_add_u32_e32 v153, s48, v148
	s_add_i32 s49, 0, 0x1c000
	ds_read_b128 v[154:157], v153
	ds_read_b128 v[158:161], v153 offset:1024
	ds_read_b128 v[164:167], v153 offset:2048
	ds_read_b128 v[168:171], v153 offset:3072
	v_add_u32_e32 v153, s49, v148
	ds_read_b128 v[172:175], v153
	ds_read_b128 v[176:179], v153 offset:1024
	ds_read_b128 v[180:183], v153 offset:2048
	ds_read_b128 v[184:187], v153 offset:3072
	s_add_u32 s26, s26, 0x100000
	s_addc_u32 s27, s27, 0
	s_mov_b32 m0, s31
	v_lshl_add_u64 v[226:227], s[26:27], 0, v[130:131]
	ds_read_b128 v[188:191], v152 offset:32768
	ds_read_b128 v[192:195], v152 offset:33792
	ds_read_b128 v[196:199], v152 offset:34816
	ds_read_b128 v[200:203], v152 offset:35840
	ds_read_b128 v[204:207], v152 offset:36864
	ds_read_b128 v[208:211], v152 offset:37888
	ds_read_b128 v[212:215], v152 offset:38912
	ds_read_b128 v[216:219], v152 offset:39936
	s_mov_b32 m0, s21
	s_nop 0
	global_load_lds_dwordx4 v[222:223], off
	s_mov_b32 m0, s30
	s_nop 0
	global_load_lds_dwordx4 v[224:225], off
	s_mov_b32 m0, s31
	s_nop 0
	global_load_lds_dwordx4 v[226:227], off
	v_lshl_add_u64 v[226:227], s[26:27], 0, v[134:135]
	s_mov_b32 m0, s33
	s_nop 0
	global_load_lds_dwordx4 v[226:227], off
	s_waitcnt vmcnt(8)
	s_waitcnt lgkmcnt(0)
	s_barrier
	s_setprio 1
	s_waitcnt lgkmcnt(0)
	v_mfma_f32_16x16x32_bf16 v[126:129], v[154:157], v[188:191], v[126:129]
	v_mfma_f32_16x16x32_bf16 v[122:125], v[164:167], v[188:191], v[122:125]
	v_mfma_f32_16x16x32_bf16 v[118:121], v[154:157], v[196:199], v[118:121]
	v_mfma_f32_16x16x32_bf16 v[110:113], v[164:167], v[196:199], v[110:113]
	v_mfma_f32_16x16x32_bf16 v[102:105], v[154:157], v[204:207], v[102:105]
	v_mfma_f32_16x16x32_bf16 v[94:97], v[164:167], v[204:207], v[94:97]
	v_mfma_f32_16x16x32_bf16 v[82:85], v[154:157], v[212:215], v[82:85]
	v_mfma_f32_16x16x32_bf16 v[74:77], v[164:167], v[212:215], v[74:77]
	v_mfma_f32_16x16x32_bf16 v[126:129], v[158:161], v[192:195], v[126:129]
	v_mfma_f32_16x16x32_bf16 v[122:125], v[168:171], v[192:195], v[122:125]
	v_mfma_f32_16x16x32_bf16 v[118:121], v[158:161], v[200:203], v[118:121]
	v_mfma_f32_16x16x32_bf16 v[110:113], v[168:171], v[200:203], v[110:113]
	v_mfma_f32_16x16x32_bf16 v[102:105], v[158:161], v[208:211], v[102:105]
	v_mfma_f32_16x16x32_bf16 v[94:97], v[168:171], v[208:211], v[94:97]
	v_mfma_f32_16x16x32_bf16 v[82:85], v[158:161], v[216:219], v[82:85]
	v_mfma_f32_16x16x32_bf16 v[74:77], v[168:171], v[216:219], v[74:77]
	s_setprio 0
	s_setprio 1
	v_mfma_f32_16x16x32_bf16 v[114:117], v[172:175], v[188:191], v[114:117]
	v_mfma_f32_16x16x32_bf16 v[106:109], v[180:183], v[188:191], v[106:109]
	v_mfma_f32_16x16x32_bf16 v[98:101], v[172:175], v[196:199], v[98:101]
	v_mfma_f32_16x16x32_bf16 v[90:93], v[180:183], v[196:199], v[90:93]
	v_mfma_f32_16x16x32_bf16 v[86:89], v[172:175], v[204:207], v[86:89]
	v_mfma_f32_16x16x32_bf16 v[78:81], v[180:183], v[204:207], v[78:81]
	v_mfma_f32_16x16x32_bf16 v[70:73], v[172:175], v[212:215], v[70:73]
	v_mfma_f32_16x16x32_bf16 v[66:69], v[180:183], v[212:215], v[66:69]
	v_mfma_f32_16x16x32_bf16 v[114:117], v[176:179], v[192:195], v[114:117]
	v_mfma_f32_16x16x32_bf16 v[106:109], v[184:187], v[192:195], v[106:109]
	v_mfma_f32_16x16x32_bf16 v[98:101], v[176:179], v[200:203], v[98:101]
	v_mfma_f32_16x16x32_bf16 v[90:93], v[184:187], v[200:203], v[90:93]
	v_mfma_f32_16x16x32_bf16 v[86:89], v[176:179], v[208:211], v[86:89]
	v_mfma_f32_16x16x32_bf16 v[78:81], v[184:187], v[208:211], v[78:81]
	v_mfma_f32_16x16x32_bf16 v[70:73], v[176:179], v[216:219], v[70:73]
	v_mfma_f32_16x16x32_bf16 v[66:69], v[184:187], v[216:219], v[66:69]
	s_setprio 0
	s_barrier
	s_add_i32 s26, s48, s29
	v_lshl_add_u64 v[146:147], v[146:147], 0, s[6:7]
	s_mov_b32 m0, s26
	ds_read_b128 v[188:191], v152 offset:49152
	ds_read_b128 v[192:195], v152 offset:50176
	ds_read_b128 v[196:199], v152 offset:51200
	ds_read_b128 v[200:203], v152 offset:52224
	ds_read_b128 v[204:207], v152 offset:53248
	ds_read_b128 v[208:211], v152 offset:54272
	ds_read_b128 v[212:215], v152 offset:55296
	ds_read_b128 v[216:219], v152 offset:56320
	global_load_lds_dwordx4 v[146:147], off
	s_add_i32 m0, s26, 0x2000
	s_add_u32 s24, s24, 0x100080
	v_lshl_add_u64 v[146:147], v[220:221], 0, s[6:7]
	s_addc_u32 s25, s25, 0
	s_add_i32 s26, s49, s29
	global_load_lds_dwordx4 v[146:147], off
	v_lshl_add_u64 v[146:147], s[24:25], 0, v[132:133]
	s_mov_b32 m0, s26
	s_nop 0
	global_load_lds_dwordx4 v[146:147], off
	v_lshl_add_u64 v[146:147], s[24:25], 0, v[136:137]
	s_add_i32 m0, s26, 0x2000
	s_nop 0
	global_load_lds_dwordx4 v[146:147], off
	v_lshl_add_u64 v[222:223], v[222:223], 0, s[6:7]
	v_lshl_add_u64 v[224:225], v[224:225], 0, s[6:7]
	s_waitcnt vmcnt(6)
	s_waitcnt lgkmcnt(0)
	s_barrier
	s_setprio 1
	s_waitcnt lgkmcnt(0)
	v_mfma_f32_16x16x32_bf16 v[62:65], v[154:157], v[188:191], v[62:65]
	v_mfma_f32_16x16x32_bf16 v[58:61], v[164:167], v[188:191], v[58:61]
	v_mfma_f32_16x16x32_bf16 v[54:57], v[154:157], v[196:199], v[54:57]
	v_mfma_f32_16x16x32_bf16 v[46:49], v[164:167], v[196:199], v[46:49]
	v_mfma_f32_16x16x32_bf16 v[38:41], v[154:157], v[204:207], v[38:41]
	v_mfma_f32_16x16x32_bf16 v[30:33], v[164:167], v[204:207], v[30:33]
	v_mfma_f32_16x16x32_bf16 v[22:25], v[154:157], v[212:215], v[22:25]
	v_mfma_f32_16x16x32_bf16 v[14:17], v[164:167], v[212:215], v[14:17]
	v_mfma_f32_16x16x32_bf16 v[62:65], v[158:161], v[192:195], v[62:65]
	v_mfma_f32_16x16x32_bf16 v[58:61], v[168:171], v[192:195], v[58:61]
	v_mfma_f32_16x16x32_bf16 v[54:57], v[158:161], v[200:203], v[54:57]
	v_mfma_f32_16x16x32_bf16 v[46:49], v[168:171], v[200:203], v[46:49]
	v_mfma_f32_16x16x32_bf16 v[38:41], v[158:161], v[208:211], v[38:41]
	v_mfma_f32_16x16x32_bf16 v[30:33], v[168:171], v[208:211], v[30:33]
	v_mfma_f32_16x16x32_bf16 v[22:25], v[158:161], v[216:219], v[22:25]
	v_mfma_f32_16x16x32_bf16 v[14:17], v[168:171], v[216:219], v[14:17]
	s_setprio 0
	s_setprio 1
	v_mfma_f32_16x16x32_bf16 v[50:53], v[172:175], v[188:191], v[50:53]
	v_mfma_f32_16x16x32_bf16 v[42:45], v[180:183], v[188:191], v[42:45]
	v_mfma_f32_16x16x32_bf16 v[34:37], v[172:175], v[196:199], v[34:37]
	v_mfma_f32_16x16x32_bf16 v[26:29], v[180:183], v[196:199], v[26:29]
	v_mfma_f32_16x16x32_bf16 v[18:21], v[172:175], v[204:207], v[18:21]
	v_mfma_f32_16x16x32_bf16 v[10:13], v[180:183], v[204:207], v[10:13]
	v_mfma_f32_16x16x32_bf16 v[6:9], v[172:175], v[212:215], v[6:9]
	v_mfma_f32_16x16x32_bf16 v[2:5], v[180:183], v[212:215], v[2:5]
	v_mfma_f32_16x16x32_bf16 v[50:53], v[176:179], v[192:195], v[50:53]
	v_mfma_f32_16x16x32_bf16 v[42:45], v[184:187], v[192:195], v[42:45]
	v_mfma_f32_16x16x32_bf16 v[34:37], v[176:179], v[200:203], v[34:37]
	v_mfma_f32_16x16x32_bf16 v[26:29], v[184:187], v[200:203], v[26:29]
	v_mfma_f32_16x16x32_bf16 v[18:21], v[176:179], v[208:211], v[18:21]
	v_mfma_f32_16x16x32_bf16 v[10:13], v[184:187], v[208:211], v[10:13]
	v_mfma_f32_16x16x32_bf16 v[6:9], v[176:179], v[216:219], v[6:9]
	v_mfma_f32_16x16x32_bf16 v[2:5], v[184:187], v[216:219], v[2:5]
	s_setprio 0
	s_barrier
	s_add_i32 s47, s47, 2
	s_mov_b32 s32, 1
	s_add_u32 s22, s22, 0x100
	s_addc_u32 s23, s23, 0
	s_add_u32 s45, s45, 0x100
	s_addc_u32 s46, s46, 0
	s_cmp_gt_u32 s47, 61
	s_cbranch_scc0 .LBB0_696
	s_and_b64 vcc, exec, s[8:9]
	s_cbranch_vccz .LBB0_699
	s_barrier

.LBB0_814:
	s_lshl_b32 s8, s8, 5
	s_and_b32 s14, s8, 0x60
	s_mov_b64 s[8:9], 0x80
	s_add_i32 m0, s23, 0x18000
	v_lshl_add_u64 v[8:9], v[8:9], 0, s[8:9]
	s_lshl_b32 s7, s5, 13
	s_lshl_b32 s12, s14, 7
	s_waitcnt vmcnt(2)
	s_barrier
	global_load_lds_dwordx4 v[8:9], off
	v_lshl_add_u64 v[6:7], v[6:7], 0, s[8:9]
	s_add_i32 m0, s23, 0x1a000
	s_add_i32 s36, s23, 0x8000
	s_add_i32 s37, s23, 0xa000
	global_load_lds_dwordx4 v[6:7], off
	v_lshl_add_u64 v[2:3], v[2:3], 0, s[8:9]
	s_mov_b32 m0, s36
	s_add_u32 s10, s26, 0x100080
	global_load_lds_dwordx4 v[2:3], off
	v_lshl_add_u64 v[2:3], v[4:5], 0, s[8:9]
	s_mov_b32 m0, s37
	s_addc_u32 s11, s27, 0
	global_load_lds_dwordx4 v[2:3], off
	s_add_i32 m0, s23, 0x1c000
	v_lshl_add_u64 v[2:3], s[10:11], 0, v[132:133]
	global_load_lds_dwordx4 v[2:3], off
	v_lshl_add_u64 v[2:3], s[10:11], 0, v[136:137]
	s_add_i32 m0, s23, 0x1e000
	v_lshlrev_b32_e32 v4, 2, v0
	global_load_lds_dwordx4 v[2:3], off
	v_and_b32_e32 v2, 15, v0
	v_lshl_or_b32 v1, s5, 6, v2
	v_lshlrev_b32_e32 v3, 1, v13
	v_lshlrev_b32_e32 v5, 6, v0
	s_movk_i32 s5, 0x3c0
	v_lshl_or_b32 v2, v2, 6, v3
	v_and_b32_e32 v4, 32, v4
	v_and_or_b32 v3, v5, s5, v3
	v_bitop3_b32 v151, s12, v3, v4 bitop3:0xf6
	v_lshlrev_b32_e32 v3, 10, v0
	v_bitop3_b32 v2, v2, s7, v4 bitop3:0xde
	v_and_b32_e32 v3, 0x60000, v3
	v_lshlrev_b32_e32 v4, 13, v12
	s_cmpk_lt_u32 s4, 0x100
	v_or3_b32 v3, v10, v3, v4
	s_cselect_b64 s[10:11], -1, 0
	s_ashr_i32 s38, s96, 31
	s_ashr_i32 s39, s88, 31
	v_add_u32_e32 v138, v3, v11
	v_lshlrev_b32_e32 v3, 6, v14
	s_waitcnt vmcnt(6)
	s_cmp_lg_u64 s[94:95], 0
	v_and_b32_e32 v3, 0xe0000, v3
	s_cselect_b64 s[12:13], -1, 0
	v_or3_b32 v3, v10, v3, v4
	s_add_i32 s41, 0, 0x10000
	s_add_i32 s42, 0, 0x14000
	v_or_b32_e32 v153, s14, v13
	v_mov_b32_e32 v139, v133
	v_add_u32_e32 v140, v3, v11
	v_mov_b32_e32 v141, v133
	v_mov_b64_e32 v[142:143], 0xac0
	v_mov_b64_e32 v[144:145], 0xabf
	s_movk_i32 s40, 0x159
	v_add_u32_e32 v154, s41, v151
	v_add_u32_e32 v155, s42, v151
	v_add_u32_e32 v156, 0, v2
	s_mov_b32 s43, 0xac00
	s_barrier
	s_mov_b32 s32, 0
	s_branch .LBB0_817

.LBB0_820:
	ds_read_b128 v[146:149], v154
	ds_read_b128 v[158:161], v154 offset:1024
	ds_read_b128 v[164:167], v154 offset:2048
	ds_read_b128 v[168:171], v154 offset:3072
	ds_read_b128 v[172:175], v155
	ds_read_b128 v[176:179], v155 offset:1024
	ds_read_b128 v[180:183], v155 offset:2048
	ds_read_b128 v[184:187], v155 offset:3072
	s_add_u32 s26, s24, 0xfff00080
	s_addc_u32 s27, s25, -1
	s_cmp_eq_u32 s47, 60
	s_cselect_b32 s29, s7, s27
	s_cselect_b32 s28, s17, s26
	s_cselect_b32 s27, s15, s46
	s_cselect_b32 s26, s44, s45
	v_lshl_add_u64 v[220:221], s[24:25], 0, v[138:139]
	s_add_i32 m0, s23, 0xc000
	ds_read_b128 v[188:191], v156
	ds_read_b128 v[192:195], v156 offset:1024
	ds_read_b128 v[196:199], v156 offset:2048
	ds_read_b128 v[200:203], v156 offset:3072
	ds_read_b128 v[204:207], v156 offset:4096
	ds_read_b128 v[208:211], v156 offset:5120
	ds_read_b128 v[212:215], v156 offset:6144
	ds_read_b128 v[216:219], v156 offset:7168
	s_cmp_lg_u32 s32, 0
	s_cbranch_scc0 .Lrebal_skip_820
	s_mov_b32 m0, s36
	s_nop 0
	global_load_lds_dwordx4 v[224:225], off
	s_mov_b32 m0, s37
	s_nop 0
	global_load_lds_dwordx4 v[226:227], off
.Lrebal_skip_820:
	s_add_i32 m0, s23, 0xc000
	s_nop 0
	global_load_lds_dwordx4 v[220:221], off
	v_lshl_add_u64 v[220:221], s[24:25], 0, v[140:141]
	s_add_i32 m0, s23, 0xe000
	s_nop 0
	global_load_lds_dwordx4 v[220:221], off
	s_waitcnt vmcnt(8)
	s_waitcnt lgkmcnt(0)
	s_barrier
	s_setprio 1
	s_waitcnt lgkmcnt(0)
	v_mfma_f32_16x16x32_bf16 v[126:129], v[146:149], v[188:191], v[126:129]
	v_mfma_f32_16x16x32_bf16 v[122:125], v[164:167], v[188:191], v[122:125]
	v_mfma_f32_16x16x32_bf16 v[110:113], v[146:149], v[196:199], v[110:113]
	v_mfma_f32_16x16x32_bf16 v[106:109], v[164:167], v[196:199], v[106:109]
	v_mfma_f32_16x16x32_bf16 v[94:97], v[146:149], v[204:207], v[94:97]
	v_mfma_f32_16x16x32_bf16 v[90:93], v[164:167], v[204:207], v[90:93]
	v_mfma_f32_16x16x32_bf16 v[78:81], v[146:149], v[212:215], v[78:81]
	v_mfma_f32_16x16x32_bf16 v[74:77], v[164:167], v[212:215], v[74:77]
	v_mfma_f32_16x16x32_bf16 v[126:129], v[158:161], v[192:195], v[126:129]
	v_mfma_f32_16x16x32_bf16 v[122:125], v[168:171], v[192:195], v[122:125]
	v_mfma_f32_16x16x32_bf16 v[110:113], v[158:161], v[200:203], v[110:113]
	v_mfma_f32_16x16x32_bf16 v[106:109], v[168:171], v[200:203], v[106:109]
	v_mfma_f32_16x16x32_bf16 v[94:97], v[158:161], v[208:211], v[94:97]
	v_mfma_f32_16x16x32_bf16 v[90:93], v[168:171], v[208:211], v[90:93]
	v_mfma_f32_16x16x32_bf16 v[78:81], v[158:161], v[216:219], v[78:81]
	v_mfma_f32_16x16x32_bf16 v[74:77], v[168:171], v[216:219], v[74:77]
	s_setprio 0
	s_setprio 1
	v_mfma_f32_16x16x32_bf16 v[118:121], v[172:175], v[188:191], v[118:121]
	v_mfma_f32_16x16x32_bf16 v[114:117], v[180:183], v[188:191], v[114:117]
	v_mfma_f32_16x16x32_bf16 v[102:105], v[172:175], v[196:199], v[102:105]
	v_mfma_f32_16x16x32_bf16 v[98:101], v[180:183], v[196:199], v[98:101]
	v_mfma_f32_16x16x32_bf16 v[86:89], v[172:175], v[204:207], v[86:89]
	v_mfma_f32_16x16x32_bf16 v[82:85], v[180:183], v[204:207], v[82:85]
	v_mfma_f32_16x16x32_bf16 v[70:73], v[172:175], v[212:215], v[70:73]
	v_mfma_f32_16x16x32_bf16 v[66:69], v[180:183], v[212:215], v[66:69]
	v_mfma_f32_16x16x32_bf16 v[118:121], v[176:179], v[192:195], v[118:121]
	v_mfma_f32_16x16x32_bf16 v[114:117], v[184:187], v[192:195], v[114:117]
	v_mfma_f32_16x16x32_bf16 v[102:105], v[176:179], v[200:203], v[102:105]
	v_mfma_f32_16x16x32_bf16 v[98:101], v[184:187], v[200:203], v[98:101]
	v_mfma_f32_16x16x32_bf16 v[86:89], v[176:179], v[208:211], v[86:89]
	v_mfma_f32_16x16x32_bf16 v[82:85], v[184:187], v[208:211], v[82:85]
	v_mfma_f32_16x16x32_bf16 v[70:73], v[176:179], v[216:219], v[70:73]
	v_mfma_f32_16x16x32_bf16 v[66:69], v[184:187], v[216:219], v[66:69]
	s_setprio 0
	s_barrier
	s_add_i32 s48, s41, s30
	v_lshl_add_u64 v[220:221], s[26:27], 0, v[132:133]
	s_mov_b32 m0, s48
	ds_read_b128 v[188:191], v156 offset:16384
	ds_read_b128 v[192:195], v156 offset:17408
	ds_read_b128 v[196:199], v156 offset:18432
	ds_read_b128 v[200:203], v156 offset:19456
	ds_read_b128 v[204:207], v156 offset:20480
	ds_read_b128 v[208:211], v156 offset:21504
	ds_read_b128 v[212:215], v156 offset:22528
	ds_read_b128 v[216:219], v156 offset:23552
	global_load_lds_dwordx4 v[220:221], off
	s_add_i32 m0, s48, 0x2000
	s_add_u32 s48, s26, 0x100000
	v_lshl_add_u64 v[222:223], s[26:27], 0, v[136:137]
	s_addc_u32 s49, s27, 0
	s_add_i32 s50, s42, s30
	global_load_lds_dwordx4 v[222:223], off
	v_lshl_add_u64 v[224:225], s[48:49], 0, v[132:133]
	s_mov_b32 m0, s50
	v_lshl_add_u64 v[226:227], s[28:29], 0, v[134:135]
	global_load_lds_dwordx4 v[224:225], off
	v_lshl_add_u64 v[224:225], s[48:49], 0, v[136:137]
	s_add_i32 m0, s50, 0x2000
	s_nop 0
	global_load_lds_dwordx4 v[224:225], off
	v_lshl_add_u64 v[224:225], s[28:29], 0, v[130:131]
	s_waitcnt vmcnt(6)
	s_waitcnt lgkmcnt(0)
	s_barrier
	s_setprio 1
	s_waitcnt lgkmcnt(0)
	v_mfma_f32_16x16x32_bf16 v[62:65], v[146:149], v[188:191], v[62:65]
	v_mfma_f32_16x16x32_bf16 v[58:61], v[164:167], v[188:191], v[58:61]
	v_mfma_f32_16x16x32_bf16 v[46:49], v[146:149], v[196:199], v[46:49]
	v_mfma_f32_16x16x32_bf16 v[42:45], v[164:167], v[196:199], v[42:45]
	v_mfma_f32_16x16x32_bf16 v[30:33], v[146:149], v[204:207], v[30:33]
	v_mfma_f32_16x16x32_bf16 v[26:29], v[164:167], v[204:207], v[26:29]
	v_mfma_f32_16x16x32_bf16 v[14:17], v[146:149], v[212:215], v[14:17]
	v_mfma_f32_16x16x32_bf16 v[10:13], v[164:167], v[212:215], v[10:13]
	v_mfma_f32_16x16x32_bf16 v[62:65], v[158:161], v[192:195], v[62:65]
	v_mfma_f32_16x16x32_bf16 v[58:61], v[168:171], v[192:195], v[58:61]
	v_mfma_f32_16x16x32_bf16 v[46:49], v[158:161], v[200:203], v[46:49]
	v_mfma_f32_16x16x32_bf16 v[42:45], v[168:171], v[200:203], v[42:45]
	v_mfma_f32_16x16x32_bf16 v[30:33], v[158:161], v[208:211], v[30:33]
	v_mfma_f32_16x16x32_bf16 v[26:29], v[168:171], v[208:211], v[26:29]
	v_mfma_f32_16x16x32_bf16 v[14:17], v[158:161], v[216:219], v[14:17]
	v_mfma_f32_16x16x32_bf16 v[10:13], v[168:171], v[216:219], v[10:13]
	s_setprio 0
	s_setprio 1
	v_mfma_f32_16x16x32_bf16 v[54:57], v[172:175], v[188:191], v[54:57]
	v_mfma_f32_16x16x32_bf16 v[50:53], v[180:183], v[188:191], v[50:53]
	v_mfma_f32_16x16x32_bf16 v[38:41], v[172:175], v[196:199], v[38:41]
	v_mfma_f32_16x16x32_bf16 v[34:37], v[180:183], v[196:199], v[34:37]
	v_mfma_f32_16x16x32_bf16 v[22:25], v[172:175], v[204:207], v[22:25]
	v_mfma_f32_16x16x32_bf16 v[18:21], v[180:183], v[204:207], v[18:21]
	v_mfma_f32_16x16x32_bf16 v[6:9], v[172:175], v[212:215], v[6:9]
	v_mfma_f32_16x16x32_bf16 v[2:5], v[180:183], v[212:215], v[2:5]
	v_mfma_f32_16x16x32_bf16 v[54:57], v[176:179], v[192:195], v[54:57]
	v_mfma_f32_16x16x32_bf16 v[50:53], v[184:187], v[192:195], v[50:53]
	v_mfma_f32_16x16x32_bf16 v[38:41], v[176:179], v[200:203], v[38:41]
	v_mfma_f32_16x16x32_bf16 v[34:37], v[184:187], v[200:203], v[34:37]
	v_mfma_f32_16x16x32_bf16 v[22:25], v[176:179], v[208:211], v[22:25]
	v_mfma_f32_16x16x32_bf16 v[18:21], v[184:187], v[208:211], v[18:21]
	v_mfma_f32_16x16x32_bf16 v[6:9], v[176:179], v[216:219], v[6:9]
	v_mfma_f32_16x16x32_bf16 v[2:5], v[184:187], v[216:219], v[2:5]
	s_setprio 0
	s_barrier
	s_add_i32 s48, 0, 0x18000
	v_add_u32_e32 v150, s48, v151
	s_add_i32 s49, 0, 0x1c000
	ds_read_b128 v[146:149], v150
	ds_read_b128 v[158:161], v150 offset:1024
	ds_read_b128 v[164:167], v150 offset:2048
	ds_read_b128 v[168:171], v150 offset:3072
	v_add_u32_e32 v150, s49, v151
	ds_read_b128 v[172:175], v150
	ds_read_b128 v[176:179], v150 offset:1024
	ds_read_b128 v[180:183], v150 offset:2048
	ds_read_b128 v[184:187], v150 offset:3072
	s_add_u32 s28, s28, 0x100000
	s_addc_u32 s29, s29, 0
	s_mov_b32 m0, s33
	v_lshl_add_u64 v[228:229], s[28:29], 0, v[130:131]
	ds_read_b128 v[188:191], v156 offset:32768
	ds_read_b128 v[192:195], v156 offset:33792
	ds_read_b128 v[196:199], v156 offset:34816
	ds_read_b128 v[200:203], v156 offset:35840
	ds_read_b128 v[204:207], v156 offset:36864
	ds_read_b128 v[208:211], v156 offset:37888
	ds_read_b128 v[212:215], v156 offset:38912
	ds_read_b128 v[216:219], v156 offset:39936
	s_mov_b32 m0, s23
	s_nop 0
	global_load_lds_dwordx4 v[224:225], off
	s_mov_b32 m0, s31
	s_nop 0
	global_load_lds_dwordx4 v[226:227], off
	s_mov_b32 m0, s33
	s_nop 0
	global_load_lds_dwordx4 v[228:229], off
	v_lshl_add_u64 v[228:229], s[28:29], 0, v[134:135]
	s_mov_b32 m0, s34
	s_nop 0
	global_load_lds_dwordx4 v[228:229], off
	s_waitcnt vmcnt(8)
	s_waitcnt lgkmcnt(0)
	s_barrier
	s_setprio 1
	s_waitcnt lgkmcnt(0)
	v_mfma_f32_16x16x32_bf16 v[126:129], v[146:149], v[188:191], v[126:129]
	v_mfma_f32_16x16x32_bf16 v[122:125], v[164:167], v[188:191], v[122:125]
	v_mfma_f32_16x16x32_bf16 v[110:113], v[146:149], v[196:199], v[110:113]
	v_mfma_f32_16x16x32_bf16 v[106:109], v[164:167], v[196:199], v[106:109]
	v_mfma_f32_16x16x32_bf16 v[94:97], v[146:149], v[204:207], v[94:97]
	v_mfma_f32_16x16x32_bf16 v[90:93], v[164:167], v[204:207], v[90:93]
	v_mfma_f32_16x16x32_bf16 v[78:81], v[146:149], v[212:215], v[78:81]
	v_mfma_f32_16x16x32_bf16 v[74:77], v[164:167], v[212:215], v[74:77]
	v_mfma_f32_16x16x32_bf16 v[126:129], v[158:161], v[192:195], v[126:129]
	v_mfma_f32_16x16x32_bf16 v[122:125], v[168:171], v[192:195], v[122:125]
	v_mfma_f32_16x16x32_bf16 v[110:113], v[158:161], v[200:203], v[110:113]
	v_mfma_f32_16x16x32_bf16 v[106:109], v[168:171], v[200:203], v[106:109]
	v_mfma_f32_16x16x32_bf16 v[94:97], v[158:161], v[208:211], v[94:97]
	v_mfma_f32_16x16x32_bf16 v[90:93], v[168:171], v[208:211], v[90:93]
	v_mfma_f32_16x16x32_bf16 v[78:81], v[158:161], v[216:219], v[78:81]
	v_mfma_f32_16x16x32_bf16 v[74:77], v[168:171], v[216:219], v[74:77]
	s_setprio 0
	s_setprio 1
	v_mfma_f32_16x16x32_bf16 v[118:121], v[172:175], v[188:191], v[118:121]
	v_mfma_f32_16x16x32_bf16 v[114:117], v[180:183], v[188:191], v[114:117]
	v_mfma_f32_16x16x32_bf16 v[102:105], v[172:175], v[196:199], v[102:105]
	v_mfma_f32_16x16x32_bf16 v[98:101], v[180:183], v[196:199], v[98:101]
	v_mfma_f32_16x16x32_bf16 v[86:89], v[172:175], v[204:207], v[86:89]
	v_mfma_f32_16x16x32_bf16 v[82:85], v[180:183], v[204:207], v[82:85]
	v_mfma_f32_16x16x32_bf16 v[70:73], v[172:175], v[212:215], v[70:73]
	v_mfma_f32_16x16x32_bf16 v[66:69], v[180:183], v[212:215], v[66:69]
	v_mfma_f32_16x16x32_bf16 v[118:121], v[176:179], v[192:195], v[118:121]
	v_mfma_f32_16x16x32_bf16 v[114:117], v[184:187], v[192:195], v[114:117]
	v_mfma_f32_16x16x32_bf16 v[102:105], v[176:179], v[200:203], v[102:105]
	v_mfma_f32_16x16x32_bf16 v[98:101], v[184:187], v[200:203], v[98:101]
	v_mfma_f32_16x16x32_bf16 v[86:89], v[176:179], v[208:211], v[86:89]
	v_mfma_f32_16x16x32_bf16 v[82:85], v[184:187], v[208:211], v[82:85]
	v_mfma_f32_16x16x32_bf16 v[70:73], v[176:179], v[216:219], v[70:73]
	v_mfma_f32_16x16x32_bf16 v[66:69], v[184:187], v[216:219], v[66:69]
	s_setprio 0
	s_barrier
	s_add_i32 s28, s48, s30
	v_lshl_add_u64 v[220:221], v[220:221], 0, s[8:9]
	s_mov_b32 m0, s28
	ds_read_b128 v[188:191], v156 offset:49152
	ds_read_b128 v[192:195], v156 offset:50176
	ds_read_b128 v[196:199], v156 offset:51200
	ds_read_b128 v[200:203], v156 offset:52224
	ds_read_b128 v[204:207], v156 offset:53248
	ds_read_b128 v[208:211], v156 offset:54272
	ds_read_b128 v[212:215], v156 offset:55296
	ds_read_b128 v[216:219], v156 offset:56320
	global_load_lds_dwordx4 v[220:221], off
	s_add_i32 m0, s28, 0x2000
	s_add_u32 s26, s26, 0x100080
	v_lshl_add_u64 v[220:221], v[222:223], 0, s[8:9]
	s_addc_u32 s27, s27, 0
	s_add_i32 s28, s49, s30
	global_load_lds_dwordx4 v[220:221], off
	v_lshl_add_u64 v[220:221], s[26:27], 0, v[132:133]
	s_mov_b32 m0, s28
	s_nop 0
	global_load_lds_dwordx4 v[220:221], off
	v_lshl_add_u64 v[220:221], s[26:27], 0, v[136:137]
	s_add_i32 m0, s28, 0x2000
	s_nop 0
	global_load_lds_dwordx4 v[220:221], off
	v_lshl_add_u64 v[224:225], v[224:225], 0, s[8:9]
	v_lshl_add_u64 v[226:227], v[226:227], 0, s[8:9]
	s_waitcnt vmcnt(6)
	s_waitcnt lgkmcnt(0)
	s_barrier
	s_setprio 1
	s_waitcnt lgkmcnt(0)
	v_mfma_f32_16x16x32_bf16 v[62:65], v[146:149], v[188:191], v[62:65]
	v_mfma_f32_16x16x32_bf16 v[58:61], v[164:167], v[188:191], v[58:61]
	v_mfma_f32_16x16x32_bf16 v[46:49], v[146:149], v[196:199], v[46:49]
	v_mfma_f32_16x16x32_bf16 v[42:45], v[164:167], v[196:199], v[42:45]
	v_mfma_f32_16x16x32_bf16 v[30:33], v[146:149], v[204:207], v[30:33]
	v_mfma_f32_16x16x32_bf16 v[26:29], v[164:167], v[204:207], v[26:29]
	v_mfma_f32_16x16x32_bf16 v[14:17], v[146:149], v[212:215], v[14:17]
	v_mfma_f32_16x16x32_bf16 v[10:13], v[164:167], v[212:215], v[10:13]
	v_mfma_f32_16x16x32_bf16 v[62:65], v[158:161], v[192:195], v[62:65]
	v_mfma_f32_16x16x32_bf16 v[58:61], v[168:171], v[192:195], v[58:61]
	v_mfma_f32_16x16x32_bf16 v[46:49], v[158:161], v[200:203], v[46:49]
	v_mfma_f32_16x16x32_bf16 v[42:45], v[168:171], v[200:203], v[42:45]
	v_mfma_f32_16x16x32_bf16 v[30:33], v[158:161], v[208:211], v[30:33]
	v_mfma_f32_16x16x32_bf16 v[26:29], v[168:171], v[208:211], v[26:29]
	v_mfma_f32_16x16x32_bf16 v[14:17], v[158:161], v[216:219], v[14:17]
	v_mfma_f32_16x16x32_bf16 v[10:13], v[168:171], v[216:219], v[10:13]
	s_setprio 0
	s_setprio 1
	v_mfma_f32_16x16x32_bf16 v[54:57], v[172:175], v[188:191], v[54:57]
	v_mfma_f32_16x16x32_bf16 v[50:53], v[180:183], v[188:191], v[50:53]
	v_mfma_f32_16x16x32_bf16 v[38:41], v[172:175], v[196:199], v[38:41]
	v_mfma_f32_16x16x32_bf16 v[34:37], v[180:183], v[196:199], v[34:37]
	v_mfma_f32_16x16x32_bf16 v[22:25], v[172:175], v[204:207], v[22:25]
	v_mfma_f32_16x16x32_bf16 v[18:21], v[180:183], v[204:207], v[18:21]
	v_mfma_f32_16x16x32_bf16 v[6:9], v[172:175], v[212:215], v[6:9]
	v_mfma_f32_16x16x32_bf16 v[2:5], v[180:183], v[212:215], v[2:5]
	v_mfma_f32_16x16x32_bf16 v[54:57], v[176:179], v[192:195], v[54:57]
	v_mfma_f32_16x16x32_bf16 v[50:53], v[184:187], v[192:195], v[50:53]
	v_mfma_f32_16x16x32_bf16 v[38:41], v[176:179], v[200:203], v[38:41]
	v_mfma_f32_16x16x32_bf16 v[34:37], v[184:187], v[200:203], v[34:37]
	v_mfma_f32_16x16x32_bf16 v[22:25], v[176:179], v[208:211], v[22:25]
	v_mfma_f32_16x16x32_bf16 v[18:21], v[184:187], v[208:211], v[18:21]
	v_mfma_f32_16x16x32_bf16 v[6:9], v[176:179], v[216:219], v[6:9]
	v_mfma_f32_16x16x32_bf16 v[2:5], v[184:187], v[216:219], v[2:5]
	s_setprio 0
	s_barrier
	s_add_i32 s47, s47, 2
	s_mov_b32 s32, 1
	s_add_u32 s24, s24, 0x100
	s_addc_u32 s25, s25, 0
	s_add_u32 s45, s45, 0x100
	s_addc_u32 s46, s46, 0
	s_cmp_gt_u32 s47, 61
	s_cbranch_scc0 .LBB0_820
	s_and_b64 vcc, exec, s[10:11]
	s_cbranch_vccz .LBB0_823
	s_barrier

.LBB0_964:
	s_lshl_b32 s1, s1, 5
	s_mov_b64 s[8:9], 0x80
	s_and_b32 s1, s1, 0x60
	s_add_i32 m0, s28, 0x18000
	v_lshl_add_u64 v[8:9], v[8:9], 0, s[8:9]
	s_lshl_b32 s12, s0, 13
	s_lshl_b32 s13, s1, 7
	s_waitcnt vmcnt(2)
	s_barrier
	global_load_lds_dwordx4 v[8:9], off
	v_lshl_add_u64 v[6:7], v[6:7], 0, s[8:9]
	s_add_i32 m0, s28, 0x1a000
	s_add_i32 s34, s28, 0x8000
	s_add_i32 s35, s28, 0xa000
	global_load_lds_dwordx4 v[6:7], off
	v_lshl_add_u64 v[2:3], v[2:3], 0, s[8:9]
	s_mov_b32 m0, s34
	s_add_u32 s10, s22, 0x2b0080
	global_load_lds_dwordx4 v[2:3], off
	v_lshl_add_u64 v[2:3], v[4:5], 0, s[8:9]
	s_mov_b32 m0, s35
	s_addc_u32 s11, s23, 0
	global_load_lds_dwordx4 v[2:3], off
	s_add_i32 m0, s28, 0x1c000
	v_lshl_add_u64 v[2:3], s[10:11], 0, v[132:133]
	global_load_lds_dwordx4 v[2:3], off
	v_lshl_add_u64 v[2:3], s[10:11], 0, v[136:137]
	s_add_i32 m0, s28, 0x1e000
	v_lshlrev_b32_e32 v4, 2, v0
	global_load_lds_dwordx4 v[2:3], off
	v_and_b32_e32 v2, 15, v0
	v_lshl_or_b32 v1, s0, 6, v2
	v_lshlrev_b32_e32 v3, 1, v12
	v_lshlrev_b32_e32 v5, 6, v0
	s_movk_i32 s0, 0x3c0
	v_lshl_or_b32 v2, v2, 6, v3
	v_and_b32_e32 v4, 32, v4
	v_and_or_b32 v3, v5, s0, v3
	v_bitop3_b32 v148, s13, v3, v4 bitop3:0xf6
	s_waitcnt vmcnt(6)
	s_cmpk_lt_u32 s4, 0x100
	v_add_u16_e32 v3, v10, v11
	v_bitop3_b32 v2, v2, s12, v4 bitop3:0xde
	s_cselect_b64 s[10:11], -1, 0
	v_lshrrev_b16_e32 v3, 1, v3
	s_add_i32 s37, 0, 0x10000
	s_add_i32 s38, 0, 0x14000
	s_sext_i32_i8 s46, s5
	s_ashr_i32 s36, s96, 31
	v_or_b32_e32 v149, s1, v12
	v_add_lshl_u32 v138, v13, v3, 1
	v_mov_b32_e32 v139, v133
	v_add_lshl_u32 v140, v14, v3, 1
	v_mov_b32_e32 v141, v133
	v_mov_b64_e32 v[142:143], 0x200
	v_mov_b64_e32 v[144:145], 0x1ff
	v_add_u32_e32 v150, s37, v148
	v_add_u32_e32 v151, s38, v148
	v_add_u32_e32 v152, 0, v2
	s_mov_b32 s39, 0x100000
	s_mov_b64 s[12:13], 0x120000
	s_mov_b32 s40, 0x120000
	s_mov_b64 s[14:15], 0x140000
	s_mov_b32 s41, 0x140000
	s_mov_b64 s[16:17], 0x160000
	s_mov_b32 s42, 0x160000
	s_barrier
	s_mov_b32 s32, 0
	s_branch .LBB0_967

.LBB0_978:
	ds_read_b128 v[154:157], v150
	ds_read_b128 v[158:161], v150 offset:1024
	ds_read_b128 v[164:167], v150 offset:2048
	ds_read_b128 v[168:171], v150 offset:3072
	ds_read_b128 v[172:175], v151
	ds_read_b128 v[176:179], v151 offset:1024
	ds_read_b128 v[180:183], v151 offset:2048
	ds_read_b128 v[184:187], v151 offset:3072
	s_add_u32 s22, s20, 0xffd50080
	s_addc_u32 s23, s21, -1
	s_cmpk_eq_i32 s49, 0xa8
	s_cselect_b32 s25, s1, s23
	s_cselect_b32 s24, s0, s22
	s_cselect_b32 s23, s19, s48
	s_cselect_b32 s22, s18, s47
	v_lshl_add_u64 v[146:147], s[20:21], 0, v[138:139]
	s_add_i32 m0, s28, 0xc000
	ds_read_b128 v[188:191], v152
	ds_read_b128 v[192:195], v152 offset:1024
	ds_read_b128 v[196:199], v152 offset:2048
	ds_read_b128 v[200:203], v152 offset:3072
	ds_read_b128 v[204:207], v152 offset:4096
	ds_read_b128 v[208:211], v152 offset:5120
	ds_read_b128 v[212:215], v152 offset:6144
	ds_read_b128 v[216:219], v152 offset:7168
	s_cmp_lg_u32 s32, 0
	s_cbranch_scc0 .Lrebal_skip_978
	s_mov_b32 m0, s34
	s_nop 0
	global_load_lds_dwordx4 v[222:223], off
	s_mov_b32 m0, s35
	s_nop 0
	global_load_lds_dwordx4 v[224:225], off
.Lrebal_skip_978:
	s_add_i32 m0, s28, 0xc000
	s_nop 0
	global_load_lds_dwordx4 v[146:147], off
	v_lshl_add_u64 v[146:147], s[20:21], 0, v[140:141]
	s_add_i32 m0, s28, 0xe000
	s_nop 0
	global_load_lds_dwordx4 v[146:147], off
	s_waitcnt vmcnt(8)
	s_waitcnt lgkmcnt(0)
	s_barrier
	s_setprio 1
	s_waitcnt lgkmcnt(0)
	v_mfma_f32_16x16x32_bf16 v[126:129], v[154:157], v[188:191], v[126:129]
	v_mfma_f32_16x16x32_bf16 v[122:125], v[164:167], v[188:191], v[122:125]
	v_mfma_f32_16x16x32_bf16 v[118:121], v[154:157], v[196:199], v[118:121]
	v_mfma_f32_16x16x32_bf16 v[110:113], v[164:167], v[196:199], v[110:113]
	v_mfma_f32_16x16x32_bf16 v[102:105], v[154:157], v[204:207], v[102:105]
	v_mfma_f32_16x16x32_bf16 v[94:97], v[164:167], v[204:207], v[94:97]
	v_mfma_f32_16x16x32_bf16 v[82:85], v[154:157], v[212:215], v[82:85]
	v_mfma_f32_16x16x32_bf16 v[74:77], v[164:167], v[212:215], v[74:77]
	v_mfma_f32_16x16x32_bf16 v[126:129], v[158:161], v[192:195], v[126:129]
	v_mfma_f32_16x16x32_bf16 v[122:125], v[168:171], v[192:195], v[122:125]
	v_mfma_f32_16x16x32_bf16 v[118:121], v[158:161], v[200:203], v[118:121]
	v_mfma_f32_16x16x32_bf16 v[110:113], v[168:171], v[200:203], v[110:113]
	v_mfma_f32_16x16x32_bf16 v[102:105], v[158:161], v[208:211], v[102:105]
	v_mfma_f32_16x16x32_bf16 v[94:97], v[168:171], v[208:211], v[94:97]
	v_mfma_f32_16x16x32_bf16 v[82:85], v[158:161], v[216:219], v[82:85]
	v_mfma_f32_16x16x32_bf16 v[74:77], v[168:171], v[216:219], v[74:77]
	s_setprio 0
	s_setprio 1
	v_mfma_f32_16x16x32_bf16 v[114:117], v[172:175], v[188:191], v[114:117]
	v_mfma_f32_16x16x32_bf16 v[106:109], v[180:183], v[188:191], v[106:109]
	v_mfma_f32_16x16x32_bf16 v[98:101], v[172:175], v[196:199], v[98:101]
	v_mfma_f32_16x16x32_bf16 v[90:93], v[180:183], v[196:199], v[90:93]
	v_mfma_f32_16x16x32_bf16 v[86:89], v[172:175], v[204:207], v[86:89]
	v_mfma_f32_16x16x32_bf16 v[78:81], v[180:183], v[204:207], v[78:81]
	v_mfma_f32_16x16x32_bf16 v[70:73], v[172:175], v[212:215], v[70:73]
	v_mfma_f32_16x16x32_bf16 v[66:69], v[180:183], v[212:215], v[66:69]
	v_mfma_f32_16x16x32_bf16 v[114:117], v[176:179], v[192:195], v[114:117]
	v_mfma_f32_16x16x32_bf16 v[106:109], v[184:187], v[192:195], v[106:109]
	v_mfma_f32_16x16x32_bf16 v[98:101], v[176:179], v[200:203], v[98:101]
	v_mfma_f32_16x16x32_bf16 v[90:93], v[184:187], v[200:203], v[90:93]
	v_mfma_f32_16x16x32_bf16 v[86:89], v[176:179], v[208:211], v[86:89]
	v_mfma_f32_16x16x32_bf16 v[78:81], v[184:187], v[208:211], v[78:81]
	v_mfma_f32_16x16x32_bf16 v[70:73], v[176:179], v[216:219], v[70:73]
	v_mfma_f32_16x16x32_bf16 v[66:69], v[184:187], v[216:219], v[66:69]
	s_setprio 0
	s_barrier
	s_add_i32 s50, s37, s27
	v_lshl_add_u64 v[146:147], s[22:23], 0, v[132:133]
	s_mov_b32 m0, s50
	ds_read_b128 v[188:191], v152 offset:16384
	ds_read_b128 v[192:195], v152 offset:17408
	ds_read_b128 v[196:199], v152 offset:18432
	ds_read_b128 v[200:203], v152 offset:19456
	ds_read_b128 v[204:207], v152 offset:20480
	ds_read_b128 v[208:211], v152 offset:21504
	ds_read_b128 v[212:215], v152 offset:22528
	ds_read_b128 v[216:219], v152 offset:23552
	global_load_lds_dwordx4 v[146:147], off
	s_add_i32 m0, s50, 0x2000
	s_add_u32 s50, s22, 0x2b0000
	v_lshl_add_u64 v[220:221], s[22:23], 0, v[136:137]
	s_addc_u32 s51, s23, 0
	s_add_i32 s52, s38, s27
	global_load_lds_dwordx4 v[220:221], off
	v_lshl_add_u64 v[222:223], s[50:51], 0, v[132:133]
	s_mov_b32 m0, s52
	v_lshl_add_u64 v[224:225], s[24:25], 0, v[134:135]
	global_load_lds_dwordx4 v[222:223], off
	v_lshl_add_u64 v[222:223], s[50:51], 0, v[136:137]
	s_add_i32 m0, s52, 0x2000
	s_nop 0
	global_load_lds_dwordx4 v[222:223], off
	v_lshl_add_u64 v[222:223], s[24:25], 0, v[130:131]
	s_waitcnt vmcnt(6)
	s_waitcnt lgkmcnt(0)
	s_barrier
	s_setprio 1
	s_waitcnt lgkmcnt(0)
	v_mfma_f32_16x16x32_bf16 v[62:65], v[154:157], v[188:191], v[62:65]
	v_mfma_f32_16x16x32_bf16 v[58:61], v[164:167], v[188:191], v[58:61]
	v_mfma_f32_16x16x32_bf16 v[54:57], v[154:157], v[196:199], v[54:57]
	v_mfma_f32_16x16x32_bf16 v[46:49], v[164:167], v[196:199], v[46:49]
	v_mfma_f32_16x16x32_bf16 v[38:41], v[154:157], v[204:207], v[38:41]
	v_mfma_f32_16x16x32_bf16 v[30:33], v[164:167], v[204:207], v[30:33]
	v_mfma_f32_16x16x32_bf16 v[22:25], v[154:157], v[212:215], v[22:25]
	v_mfma_f32_16x16x32_bf16 v[14:17], v[164:167], v[212:215], v[14:17]
	v_mfma_f32_16x16x32_bf16 v[62:65], v[158:161], v[192:195], v[62:65]
	v_mfma_f32_16x16x32_bf16 v[58:61], v[168:171], v[192:195], v[58:61]
	v_mfma_f32_16x16x32_bf16 v[54:57], v[158:161], v[200:203], v[54:57]
	v_mfma_f32_16x16x32_bf16 v[46:49], v[168:171], v[200:203], v[46:49]
	v_mfma_f32_16x16x32_bf16 v[38:41], v[158:161], v[208:211], v[38:41]
	v_mfma_f32_16x16x32_bf16 v[30:33], v[168:171], v[208:211], v[30:33]
	v_mfma_f32_16x16x32_bf16 v[22:25], v[158:161], v[216:219], v[22:25]
	v_mfma_f32_16x16x32_bf16 v[14:17], v[168:171], v[216:219], v[14:17]
	s_setprio 0
	s_setprio 1
	v_mfma_f32_16x16x32_bf16 v[50:53], v[172:175], v[188:191], v[50:53]
	v_mfma_f32_16x16x32_bf16 v[42:45], v[180:183], v[188:191], v[42:45]
	v_mfma_f32_16x16x32_bf16 v[34:37], v[172:175], v[196:199], v[34:37]
	v_mfma_f32_16x16x32_bf16 v[26:29], v[180:183], v[196:199], v[26:29]
	v_mfma_f32_16x16x32_bf16 v[18:21], v[172:175], v[204:207], v[18:21]
	v_mfma_f32_16x16x32_bf16 v[10:13], v[180:183], v[204:207], v[10:13]
	v_mfma_f32_16x16x32_bf16 v[6:9], v[172:175], v[212:215], v[6:9]
	v_mfma_f32_16x16x32_bf16 v[2:5], v[180:183], v[212:215], v[2:5]
	v_mfma_f32_16x16x32_bf16 v[50:53], v[176:179], v[192:195], v[50:53]
	v_mfma_f32_16x16x32_bf16 v[42:45], v[184:187], v[192:195], v[42:45]
	v_mfma_f32_16x16x32_bf16 v[34:37], v[176:179], v[200:203], v[34:37]
	v_mfma_f32_16x16x32_bf16 v[26:29], v[184:187], v[200:203], v[26:29]
	v_mfma_f32_16x16x32_bf16 v[18:21], v[176:179], v[208:211], v[18:21]
	v_mfma_f32_16x16x32_bf16 v[10:13], v[184:187], v[208:211], v[10:13]
	v_mfma_f32_16x16x32_bf16 v[6:9], v[176:179], v[216:219], v[6:9]
	v_mfma_f32_16x16x32_bf16 v[2:5], v[184:187], v[216:219], v[2:5]
	s_setprio 0
	s_barrier
	s_add_i32 s50, 0, 0x18000
	v_add_u32_e32 v153, s50, v148
	s_add_i32 s51, 0, 0x1c000
	ds_read_b128 v[154:157], v153
	ds_read_b128 v[158:161], v153 offset:1024
	ds_read_b128 v[164:167], v153 offset:2048
	ds_read_b128 v[168:171], v153 offset:3072
	v_add_u32_e32 v153, s51, v148
	ds_read_b128 v[172:175], v153
	ds_read_b128 v[176:179], v153 offset:1024
	ds_read_b128 v[180:183], v153 offset:2048
	ds_read_b128 v[184:187], v153 offset:3072
	s_add_u32 s24, s24, 0x2b0000
	s_addc_u32 s25, s25, 0
	s_mov_b32 m0, s30
	v_lshl_add_u64 v[226:227], s[24:25], 0, v[130:131]
	ds_read_b128 v[188:191], v152 offset:32768
	ds_read_b128 v[192:195], v152 offset:33792
	ds_read_b128 v[196:199], v152 offset:34816
	ds_read_b128 v[200:203], v152 offset:35840
	ds_read_b128 v[204:207], v152 offset:36864
	ds_read_b128 v[208:211], v152 offset:37888
	ds_read_b128 v[212:215], v152 offset:38912
	ds_read_b128 v[216:219], v152 offset:39936
	s_mov_b32 m0, s28
	s_nop 0
	global_load_lds_dwordx4 v[222:223], off
	s_mov_b32 m0, s29
	s_nop 0
	global_load_lds_dwordx4 v[224:225], off
	s_mov_b32 m0, s30
	s_nop 0
	global_load_lds_dwordx4 v[226:227], off
	v_lshl_add_u64 v[226:227], s[24:25], 0, v[134:135]
	s_mov_b32 m0, s31
	s_nop 0
	global_load_lds_dwordx4 v[226:227], off
	s_waitcnt vmcnt(8)
	s_waitcnt lgkmcnt(0)
	s_barrier
	s_setprio 1
	s_waitcnt lgkmcnt(0)
	v_mfma_f32_16x16x32_bf16 v[126:129], v[154:157], v[188:191], v[126:129]
	v_mfma_f32_16x16x32_bf16 v[122:125], v[164:167], v[188:191], v[122:125]
	v_mfma_f32_16x16x32_bf16 v[118:121], v[154:157], v[196:199], v[118:121]
	v_mfma_f32_16x16x32_bf16 v[110:113], v[164:167], v[196:199], v[110:113]
	v_mfma_f32_16x16x32_bf16 v[102:105], v[154:157], v[204:207], v[102:105]
	v_mfma_f32_16x16x32_bf16 v[94:97], v[164:167], v[204:207], v[94:97]
	v_mfma_f32_16x16x32_bf16 v[82:85], v[154:157], v[212:215], v[82:85]
	v_mfma_f32_16x16x32_bf16 v[74:77], v[164:167], v[212:215], v[74:77]
	v_mfma_f32_16x16x32_bf16 v[126:129], v[158:161], v[192:195], v[126:129]
	v_mfma_f32_16x16x32_bf16 v[122:125], v[168:171], v[192:195], v[122:125]
	v_mfma_f32_16x16x32_bf16 v[118:121], v[158:161], v[200:203], v[118:121]
	v_mfma_f32_16x16x32_bf16 v[110:113], v[168:171], v[200:203], v[110:113]
	v_mfma_f32_16x16x32_bf16 v[102:105], v[158:161], v[208:211], v[102:105]
	v_mfma_f32_16x16x32_bf16 v[94:97], v[168:171], v[208:211], v[94:97]
	v_mfma_f32_16x16x32_bf16 v[82:85], v[158:161], v[216:219], v[82:85]
	v_mfma_f32_16x16x32_bf16 v[74:77], v[168:171], v[216:219], v[74:77]
	s_setprio 0
	s_setprio 1
	v_mfma_f32_16x16x32_bf16 v[114:117], v[172:175], v[188:191], v[114:117]
	v_mfma_f32_16x16x32_bf16 v[106:109], v[180:183], v[188:191], v[106:109]
	v_mfma_f32_16x16x32_bf16 v[98:101], v[172:175], v[196:199], v[98:101]
	v_mfma_f32_16x16x32_bf16 v[90:93], v[180:183], v[196:199], v[90:93]
	v_mfma_f32_16x16x32_bf16 v[86:89], v[172:175], v[204:207], v[86:89]
	v_mfma_f32_16x16x32_bf16 v[78:81], v[180:183], v[204:207], v[78:81]
	v_mfma_f32_16x16x32_bf16 v[70:73], v[172:175], v[212:215], v[70:73]
	v_mfma_f32_16x16x32_bf16 v[66:69], v[180:183], v[212:215], v[66:69]
	v_mfma_f32_16x16x32_bf16 v[114:117], v[176:179], v[192:195], v[114:117]
	v_mfma_f32_16x16x32_bf16 v[106:109], v[184:187], v[192:195], v[106:109]
	v_mfma_f32_16x16x32_bf16 v[98:101], v[176:179], v[200:203], v[98:101]
	v_mfma_f32_16x16x32_bf16 v[90:93], v[184:187], v[200:203], v[90:93]
	v_mfma_f32_16x16x32_bf16 v[86:89], v[176:179], v[208:211], v[86:89]
	v_mfma_f32_16x16x32_bf16 v[78:81], v[184:187], v[208:211], v[78:81]
	v_mfma_f32_16x16x32_bf16 v[70:73], v[176:179], v[216:219], v[70:73]
	v_mfma_f32_16x16x32_bf16 v[66:69], v[184:187], v[216:219], v[66:69]
	s_setprio 0
	s_barrier
	s_add_i32 s24, s50, s27
	v_lshl_add_u64 v[146:147], v[146:147], 0, s[8:9]
	s_mov_b32 m0, s24
	ds_read_b128 v[188:191], v152 offset:49152
	ds_read_b128 v[192:195], v152 offset:50176
	ds_read_b128 v[196:199], v152 offset:51200
	ds_read_b128 v[200:203], v152 offset:52224
	ds_read_b128 v[204:207], v152 offset:53248
	ds_read_b128 v[208:211], v152 offset:54272
	ds_read_b128 v[212:215], v152 offset:55296
	ds_read_b128 v[216:219], v152 offset:56320
	global_load_lds_dwordx4 v[146:147], off
	s_add_i32 m0, s24, 0x2000
	s_add_u32 s22, s22, 0x2b0080
	v_lshl_add_u64 v[146:147], v[220:221], 0, s[8:9]
	s_addc_u32 s23, s23, 0
	s_add_i32 s24, s51, s27
	global_load_lds_dwordx4 v[146:147], off
	v_lshl_add_u64 v[146:147], s[22:23], 0, v[132:133]
	s_mov_b32 m0, s24
	s_nop 0
	global_load_lds_dwordx4 v[146:147], off
	v_lshl_add_u64 v[146:147], s[22:23], 0, v[136:137]
	s_add_i32 m0, s24, 0x2000
	s_nop 0
	global_load_lds_dwordx4 v[146:147], off
	v_lshl_add_u64 v[222:223], v[222:223], 0, s[8:9]
	v_lshl_add_u64 v[224:225], v[224:225], 0, s[8:9]
	s_waitcnt vmcnt(6)
	s_waitcnt lgkmcnt(0)
	s_barrier
	s_setprio 1
	s_waitcnt lgkmcnt(0)
	v_mfma_f32_16x16x32_bf16 v[62:65], v[154:157], v[188:191], v[62:65]
	v_mfma_f32_16x16x32_bf16 v[58:61], v[164:167], v[188:191], v[58:61]
	v_mfma_f32_16x16x32_bf16 v[54:57], v[154:157], v[196:199], v[54:57]
	v_mfma_f32_16x16x32_bf16 v[46:49], v[164:167], v[196:199], v[46:49]
	v_mfma_f32_16x16x32_bf16 v[38:41], v[154:157], v[204:207], v[38:41]
	v_mfma_f32_16x16x32_bf16 v[30:33], v[164:167], v[204:207], v[30:33]
	v_mfma_f32_16x16x32_bf16 v[22:25], v[154:157], v[212:215], v[22:25]
	v_mfma_f32_16x16x32_bf16 v[14:17], v[164:167], v[212:215], v[14:17]
	v_mfma_f32_16x16x32_bf16 v[62:65], v[158:161], v[192:195], v[62:65]
	v_mfma_f32_16x16x32_bf16 v[58:61], v[168:171], v[192:195], v[58:61]
	v_mfma_f32_16x16x32_bf16 v[54:57], v[158:161], v[200:203], v[54:57]
	v_mfma_f32_16x16x32_bf16 v[46:49], v[168:171], v[200:203], v[46:49]
	v_mfma_f32_16x16x32_bf16 v[38:41], v[158:161], v[208:211], v[38:41]
	v_mfma_f32_16x16x32_bf16 v[30:33], v[168:171], v[208:211], v[30:33]
	v_mfma_f32_16x16x32_bf16 v[22:25], v[158:161], v[216:219], v[22:25]
	v_mfma_f32_16x16x32_bf16 v[14:17], v[168:171], v[216:219], v[14:17]
	s_setprio 0
	s_setprio 1
	v_mfma_f32_16x16x32_bf16 v[50:53], v[172:175], v[188:191], v[50:53]
	v_mfma_f32_16x16x32_bf16 v[42:45], v[180:183], v[188:191], v[42:45]
	v_mfma_f32_16x16x32_bf16 v[34:37], v[172:175], v[196:199], v[34:37]
	v_mfma_f32_16x16x32_bf16 v[26:29], v[180:183], v[196:199], v[26:29]
	v_mfma_f32_16x16x32_bf16 v[18:21], v[172:175], v[204:207], v[18:21]
	v_mfma_f32_16x16x32_bf16 v[10:13], v[180:183], v[204:207], v[10:13]
	v_mfma_f32_16x16x32_bf16 v[6:9], v[172:175], v[212:215], v[6:9]
	v_mfma_f32_16x16x32_bf16 v[2:5], v[180:183], v[212:215], v[2:5]
	v_mfma_f32_16x16x32_bf16 v[50:53], v[176:179], v[192:195], v[50:53]
	v_mfma_f32_16x16x32_bf16 v[42:45], v[184:187], v[192:195], v[42:45]
	v_mfma_f32_16x16x32_bf16 v[34:37], v[176:179], v[200:203], v[34:37]
	v_mfma_f32_16x16x32_bf16 v[26:29], v[184:187], v[200:203], v[26:29]
	v_mfma_f32_16x16x32_bf16 v[18:21], v[176:179], v[208:211], v[18:21]
	v_mfma_f32_16x16x32_bf16 v[10:13], v[184:187], v[208:211], v[10:13]
	v_mfma_f32_16x16x32_bf16 v[6:9], v[176:179], v[216:219], v[6:9]
	v_mfma_f32_16x16x32_bf16 v[2:5], v[184:187], v[216:219], v[2:5]
	s_setprio 0
	s_barrier
	s_add_i32 s49, s49, 2
	s_mov_b32 s32, 1
	s_add_u32 s20, s20, 0x100
	s_addc_u32 s21, s21, 0
	s_add_u32 s47, s47, 0x100
	s_addc_u32 s48, s48, 0
	s_cmpk_gt_u32 s49, 0xa9
	s_cbranch_scc0 .LBB0_978
	s_and_b64 vcc, exec, s[10:11]
	s_cbranch_vccz .LBB0_981
	s_barrier

.LBB0_1121:
	s_lshl_b32 s10, s10, 5
	s_and_b32 s16, s10, 0x60
	s_mov_b64 s[10:11], 0x80
	s_add_i32 m0, s29, 0x18000
	v_lshl_add_u64 v[8:9], v[8:9], 0, s[10:11]
	s_lshl_b32 s13, s7, 13
	s_lshl_b32 s17, s16, 7
	s_waitcnt vmcnt(2)
	s_barrier
	global_load_lds_dwordx4 v[8:9], off
	v_lshl_add_u64 v[4:5], v[4:5], 0, s[10:11]
	s_add_i32 m0, s29, 0x1a000
	s_add_i32 s43, s29, 0x8000
	s_add_i32 s44, s29, 0xa000
	global_load_lds_dwordx4 v[4:5], off
	v_lshl_add_u64 v[2:3], v[2:3], 0, s[10:11]
	s_mov_b32 m0, s43
	s_add_u32 s14, s34, 0x100080
	global_load_lds_dwordx4 v[2:3], off
	v_lshl_add_u64 v[2:3], v[6:7], 0, s[10:11]
	s_mov_b32 m0, s44
	s_addc_u32 s15, s35, 0
	global_load_lds_dwordx4 v[2:3], off
	s_add_i32 m0, s29, 0x1c000
	v_lshl_add_u64 v[2:3], s[14:15], 0, v[132:133]
	global_load_lds_dwordx4 v[2:3], off
	v_lshl_add_u64 v[2:3], s[14:15], 0, v[136:137]
	s_add_i32 m0, s29, 0x1e000
	s_sext_i32_i8 s48, s6
	global_load_lds_dwordx4 v[2:3], off
	v_and_b32_e32 v2, 15, v0
	v_lshlrev_b32_e32 v3, 1, v13
	v_lshlrev_b32_e32 v4, 2, v0
	v_lshlrev_b32_e32 v5, 6, v0
	s_movk_i32 s6, 0x3c0
	v_lshl_or_b32 v1, s7, 6, v2
	v_lshl_or_b32 v2, v2, 6, v3
	v_and_b32_e32 v4, 32, v4
	v_and_or_b32 v3, v5, s6, v3
	v_bitop3_b32 v154, s17, v3, v4 bitop3:0xf6
	v_lshlrev_b32_e32 v3, 10, v0
	v_bitop3_b32 v2, v2, s13, v4 bitop3:0xde
	v_and_b32_e32 v3, 0x60000, v3
	v_lshlrev_b32_e32 v4, 13, v12
	v_or3_b32 v3, v10, v3, v4
	v_add_u32_e32 v138, v3, v11
	v_lshlrev_b32_e32 v3, 6, v14
	s_waitcnt vmcnt(6)
	s_cmpk_lt_u32 s12, 0x100
	v_and_b32_e32 v3, 0xe0000, v3
	s_cselect_b64 s[12:13], -1, 0
	v_or3_b32 v3, v10, v3, v4
	s_add_i32 s46, 0, 0x10000
	s_add_i32 s47, 0, 0x14000
	s_ashr_i32 s45, s96, 31
	v_or_b32_e32 v155, s16, v13
	v_mov_b32_e32 v139, v133
	v_add_u32_e32 v140, v3, v11
	v_mov_b32_e32 v141, v133
	v_mov_b64_e32 v[142:143], 0x200
	v_mov_b64_e32 v[144:145], 0x1ff
	v_add_u32_e32 v156, s46, v154
	v_add_u32_e32 v157, s47, v154
	v_add_u32_e32 v158, 0, v2
	s_mov_b64 s[14:15], 0x120000
	s_mov_b64 s[16:17], 0x140000
	s_mov_b64 s[18:19], 0x160000
	s_barrier
	s_mov_b32 s32, 0
	s_branch .LBB0_1124

.LBB0_1131:
	ds_read_b128 v[146:149], v156
	ds_read_b128 v[150:153], v156 offset:1024
	ds_read_b128 v[164:167], v156 offset:2048
	ds_read_b128 v[168:171], v156 offset:3072
	ds_read_b128 v[172:175], v157
	ds_read_b128 v[176:179], v157 offset:1024
	ds_read_b128 v[180:183], v157 offset:2048
	ds_read_b128 v[184:187], v157 offset:3072
	s_add_u32 s34, s30, 0xfff00080
	s_addc_u32 s35, s31, -1
	s_cmp_eq_u32 s53, 60
	s_cselect_b32 s37, s23, s35
	s_cselect_b32 s36, s49, s34
	s_cselect_b32 s35, s21, s52
	s_cselect_b32 s34, s50, s51
	v_lshl_add_u64 v[160:161], s[30:31], 0, v[138:139]
	s_add_i32 m0, s29, 0xc000
	ds_read_b128 v[188:191], v158
	ds_read_b128 v[192:195], v158 offset:1024
	ds_read_b128 v[196:199], v158 offset:2048
	ds_read_b128 v[200:203], v158 offset:3072
	ds_read_b128 v[204:207], v158 offset:4096
	ds_read_b128 v[208:211], v158 offset:5120
	ds_read_b128 v[212:215], v158 offset:6144
	ds_read_b128 v[216:219], v158 offset:7168
	s_cmp_lg_u32 s32, 0
	s_cbranch_scc0 .Lrebal_skip_1131
	s_mov_b32 m0, s43
	s_nop 0
	global_load_lds_dwordx4 v[222:223], off
	s_mov_b32 m0, s44
	s_nop 0
	global_load_lds_dwordx4 v[224:225], off
.Lrebal_skip_1131:
	s_add_i32 m0, s29, 0xc000
	s_nop 0
	global_load_lds_dwordx4 v[160:161], off
	v_lshl_add_u64 v[160:161], s[30:31], 0, v[140:141]
	s_add_i32 m0, s29, 0xe000
	s_nop 0
	global_load_lds_dwordx4 v[160:161], off
	s_waitcnt vmcnt(8)
	s_waitcnt lgkmcnt(0)
	s_barrier
	s_setprio 1
	s_waitcnt lgkmcnt(0)
	v_mfma_f32_16x16x32_bf16 v[126:129], v[146:149], v[188:191], v[126:129]
	v_mfma_f32_16x16x32_bf16 v[122:125], v[164:167], v[188:191], v[122:125]
	v_mfma_f32_16x16x32_bf16 v[110:113], v[146:149], v[196:199], v[110:113]
	v_mfma_f32_16x16x32_bf16 v[106:109], v[164:167], v[196:199], v[106:109]
	v_mfma_f32_16x16x32_bf16 v[94:97], v[146:149], v[204:207], v[94:97]
	v_mfma_f32_16x16x32_bf16 v[90:93], v[164:167], v[204:207], v[90:93]
	v_mfma_f32_16x16x32_bf16 v[78:81], v[146:149], v[212:215], v[78:81]
	v_mfma_f32_16x16x32_bf16 v[74:77], v[164:167], v[212:215], v[74:77]
	v_mfma_f32_16x16x32_bf16 v[126:129], v[150:153], v[192:195], v[126:129]
	v_mfma_f32_16x16x32_bf16 v[122:125], v[168:171], v[192:195], v[122:125]
	v_mfma_f32_16x16x32_bf16 v[110:113], v[150:153], v[200:203], v[110:113]
	v_mfma_f32_16x16x32_bf16 v[106:109], v[168:171], v[200:203], v[106:109]
	v_mfma_f32_16x16x32_bf16 v[94:97], v[150:153], v[208:211], v[94:97]
	v_mfma_f32_16x16x32_bf16 v[90:93], v[168:171], v[208:211], v[90:93]
	v_mfma_f32_16x16x32_bf16 v[78:81], v[150:153], v[216:219], v[78:81]
	v_mfma_f32_16x16x32_bf16 v[74:77], v[168:171], v[216:219], v[74:77]
	s_setprio 0
	s_setprio 1
	v_mfma_f32_16x16x32_bf16 v[118:121], v[172:175], v[188:191], v[118:121]
	v_mfma_f32_16x16x32_bf16 v[114:117], v[180:183], v[188:191], v[114:117]
	v_mfma_f32_16x16x32_bf16 v[102:105], v[172:175], v[196:199], v[102:105]
	v_mfma_f32_16x16x32_bf16 v[98:101], v[180:183], v[196:199], v[98:101]
	v_mfma_f32_16x16x32_bf16 v[86:89], v[172:175], v[204:207], v[86:89]
	v_mfma_f32_16x16x32_bf16 v[82:85], v[180:183], v[204:207], v[82:85]
	v_mfma_f32_16x16x32_bf16 v[70:73], v[172:175], v[212:215], v[70:73]
	v_mfma_f32_16x16x32_bf16 v[66:69], v[180:183], v[212:215], v[66:69]
	v_mfma_f32_16x16x32_bf16 v[118:121], v[176:179], v[192:195], v[118:121]
	v_mfma_f32_16x16x32_bf16 v[114:117], v[184:187], v[192:195], v[114:117]
	v_mfma_f32_16x16x32_bf16 v[102:105], v[176:179], v[200:203], v[102:105]
	v_mfma_f32_16x16x32_bf16 v[98:101], v[184:187], v[200:203], v[98:101]
	v_mfma_f32_16x16x32_bf16 v[86:89], v[176:179], v[208:211], v[86:89]
	v_mfma_f32_16x16x32_bf16 v[82:85], v[184:187], v[208:211], v[82:85]
	v_mfma_f32_16x16x32_bf16 v[70:73], v[176:179], v[216:219], v[70:73]
	v_mfma_f32_16x16x32_bf16 v[66:69], v[184:187], v[216:219], v[66:69]
	s_setprio 0
	s_barrier
	s_add_i32 s54, s46, s38
	v_lshl_add_u64 v[160:161], s[34:35], 0, v[132:133]
	s_mov_b32 m0, s54
	ds_read_b128 v[188:191], v158 offset:16384
	ds_read_b128 v[192:195], v158 offset:17408
	ds_read_b128 v[196:199], v158 offset:18432
	ds_read_b128 v[200:203], v158 offset:19456
	ds_read_b128 v[204:207], v158 offset:20480
	ds_read_b128 v[208:211], v158 offset:21504
	ds_read_b128 v[212:215], v158 offset:22528
	ds_read_b128 v[216:219], v158 offset:23552
	global_load_lds_dwordx4 v[160:161], off
	s_add_i32 m0, s54, 0x2000
	s_add_u32 s54, s34, 0x100000
	v_lshl_add_u64 v[220:221], s[34:35], 0, v[136:137]
	s_addc_u32 s55, s35, 0
	s_add_i32 s56, s47, s38
	global_load_lds_dwordx4 v[220:221], off
	v_lshl_add_u64 v[222:223], s[54:55], 0, v[132:133]
	s_mov_b32 m0, s56
	v_lshl_add_u64 v[224:225], s[36:37], 0, v[134:135]
	global_load_lds_dwordx4 v[222:223], off
	v_lshl_add_u64 v[222:223], s[54:55], 0, v[136:137]
	s_add_i32 m0, s56, 0x2000
	s_nop 0
	global_load_lds_dwordx4 v[222:223], off
	v_lshl_add_u64 v[222:223], s[36:37], 0, v[130:131]
	s_waitcnt vmcnt(6)
	s_waitcnt lgkmcnt(0)
	s_barrier
	s_setprio 1
	s_waitcnt lgkmcnt(0)
	v_mfma_f32_16x16x32_bf16 v[62:65], v[146:149], v[188:191], v[62:65]
	v_mfma_f32_16x16x32_bf16 v[58:61], v[164:167], v[188:191], v[58:61]
	v_mfma_f32_16x16x32_bf16 v[46:49], v[146:149], v[196:199], v[46:49]
	v_mfma_f32_16x16x32_bf16 v[42:45], v[164:167], v[196:199], v[42:45]
	v_mfma_f32_16x16x32_bf16 v[30:33], v[146:149], v[204:207], v[30:33]
	v_mfma_f32_16x16x32_bf16 v[26:29], v[164:167], v[204:207], v[26:29]
	v_mfma_f32_16x16x32_bf16 v[14:17], v[146:149], v[212:215], v[14:17]
	v_mfma_f32_16x16x32_bf16 v[10:13], v[164:167], v[212:215], v[10:13]
	v_mfma_f32_16x16x32_bf16 v[62:65], v[150:153], v[192:195], v[62:65]
	v_mfma_f32_16x16x32_bf16 v[58:61], v[168:171], v[192:195], v[58:61]
	v_mfma_f32_16x16x32_bf16 v[46:49], v[150:153], v[200:203], v[46:49]
	v_mfma_f32_16x16x32_bf16 v[42:45], v[168:171], v[200:203], v[42:45]
	v_mfma_f32_16x16x32_bf16 v[30:33], v[150:153], v[208:211], v[30:33]
	v_mfma_f32_16x16x32_bf16 v[26:29], v[168:171], v[208:211], v[26:29]
	v_mfma_f32_16x16x32_bf16 v[14:17], v[150:153], v[216:219], v[14:17]
	v_mfma_f32_16x16x32_bf16 v[10:13], v[168:171], v[216:219], v[10:13]
	s_setprio 0
	s_setprio 1
	v_mfma_f32_16x16x32_bf16 v[54:57], v[172:175], v[188:191], v[54:57]
	v_mfma_f32_16x16x32_bf16 v[50:53], v[180:183], v[188:191], v[50:53]
	v_mfma_f32_16x16x32_bf16 v[38:41], v[172:175], v[196:199], v[38:41]
	v_mfma_f32_16x16x32_bf16 v[34:37], v[180:183], v[196:199], v[34:37]
	v_mfma_f32_16x16x32_bf16 v[22:25], v[172:175], v[204:207], v[22:25]
	v_mfma_f32_16x16x32_bf16 v[18:21], v[180:183], v[204:207], v[18:21]
	v_mfma_f32_16x16x32_bf16 v[6:9], v[172:175], v[212:215], v[6:9]
	v_mfma_f32_16x16x32_bf16 v[2:5], v[180:183], v[212:215], v[2:5]
	v_mfma_f32_16x16x32_bf16 v[54:57], v[176:179], v[192:195], v[54:57]
	v_mfma_f32_16x16x32_bf16 v[50:53], v[184:187], v[192:195], v[50:53]
	v_mfma_f32_16x16x32_bf16 v[38:41], v[176:179], v[200:203], v[38:41]
	v_mfma_f32_16x16x32_bf16 v[34:37], v[184:187], v[200:203], v[34:37]
	v_mfma_f32_16x16x32_bf16 v[22:25], v[176:179], v[208:211], v[22:25]
	v_mfma_f32_16x16x32_bf16 v[18:21], v[184:187], v[208:211], v[18:21]
	v_mfma_f32_16x16x32_bf16 v[6:9], v[176:179], v[216:219], v[6:9]
	v_mfma_f32_16x16x32_bf16 v[2:5], v[184:187], v[216:219], v[2:5]
	s_setprio 0
	s_barrier
	s_add_i32 s54, 0, 0x18000
	v_add_u32_e32 v159, s54, v154
	s_add_i32 s55, 0, 0x1c000
	ds_read_b128 v[146:149], v159
	ds_read_b128 v[150:153], v159 offset:1024
	ds_read_b128 v[164:167], v159 offset:2048
	ds_read_b128 v[168:171], v159 offset:3072
	v_add_u32_e32 v159, s55, v154
	ds_read_b128 v[172:175], v159
	ds_read_b128 v[176:179], v159 offset:1024
	ds_read_b128 v[180:183], v159 offset:2048
	ds_read_b128 v[184:187], v159 offset:3072
	s_add_u32 s36, s36, 0x100000
	s_addc_u32 s37, s37, 0
	s_mov_b32 m0, s40
	v_lshl_add_u64 v[226:227], s[36:37], 0, v[130:131]
	ds_read_b128 v[188:191], v158 offset:32768
	ds_read_b128 v[192:195], v158 offset:33792
	ds_read_b128 v[196:199], v158 offset:34816
	ds_read_b128 v[200:203], v158 offset:35840
	ds_read_b128 v[204:207], v158 offset:36864
	ds_read_b128 v[208:211], v158 offset:37888
	ds_read_b128 v[212:215], v158 offset:38912
	ds_read_b128 v[216:219], v158 offset:39936
	s_mov_b32 m0, s29
	s_nop 0
	global_load_lds_dwordx4 v[222:223], off
	s_mov_b32 m0, s39
	s_nop 0
	global_load_lds_dwordx4 v[224:225], off
	s_mov_b32 m0, s40
	s_nop 0
	global_load_lds_dwordx4 v[226:227], off
	v_lshl_add_u64 v[226:227], s[36:37], 0, v[134:135]
	s_mov_b32 m0, s41
	s_nop 0
	global_load_lds_dwordx4 v[226:227], off
	s_waitcnt vmcnt(8)
	s_waitcnt lgkmcnt(0)
	s_barrier
	s_setprio 1
	s_waitcnt lgkmcnt(0)
	v_mfma_f32_16x16x32_bf16 v[126:129], v[146:149], v[188:191], v[126:129]
	v_mfma_f32_16x16x32_bf16 v[122:125], v[164:167], v[188:191], v[122:125]
	v_mfma_f32_16x16x32_bf16 v[110:113], v[146:149], v[196:199], v[110:113]
	v_mfma_f32_16x16x32_bf16 v[106:109], v[164:167], v[196:199], v[106:109]
	v_mfma_f32_16x16x32_bf16 v[94:97], v[146:149], v[204:207], v[94:97]
	v_mfma_f32_16x16x32_bf16 v[90:93], v[164:167], v[204:207], v[90:93]
	v_mfma_f32_16x16x32_bf16 v[78:81], v[146:149], v[212:215], v[78:81]
	v_mfma_f32_16x16x32_bf16 v[74:77], v[164:167], v[212:215], v[74:77]
	v_mfma_f32_16x16x32_bf16 v[126:129], v[150:153], v[192:195], v[126:129]
	v_mfma_f32_16x16x32_bf16 v[122:125], v[168:171], v[192:195], v[122:125]
	v_mfma_f32_16x16x32_bf16 v[110:113], v[150:153], v[200:203], v[110:113]
	v_mfma_f32_16x16x32_bf16 v[106:109], v[168:171], v[200:203], v[106:109]
	v_mfma_f32_16x16x32_bf16 v[94:97], v[150:153], v[208:211], v[94:97]
	v_mfma_f32_16x16x32_bf16 v[90:93], v[168:171], v[208:211], v[90:93]
	v_mfma_f32_16x16x32_bf16 v[78:81], v[150:153], v[216:219], v[78:81]
	v_mfma_f32_16x16x32_bf16 v[74:77], v[168:171], v[216:219], v[74:77]
	s_setprio 0
	s_setprio 1
	v_mfma_f32_16x16x32_bf16 v[118:121], v[172:175], v[188:191], v[118:121]
	v_mfma_f32_16x16x32_bf16 v[114:117], v[180:183], v[188:191], v[114:117]
	v_mfma_f32_16x16x32_bf16 v[102:105], v[172:175], v[196:199], v[102:105]
	v_mfma_f32_16x16x32_bf16 v[98:101], v[180:183], v[196:199], v[98:101]
	v_mfma_f32_16x16x32_bf16 v[86:89], v[172:175], v[204:207], v[86:89]
	v_mfma_f32_16x16x32_bf16 v[82:85], v[180:183], v[204:207], v[82:85]
	v_mfma_f32_16x16x32_bf16 v[70:73], v[172:175], v[212:215], v[70:73]
	v_mfma_f32_16x16x32_bf16 v[66:69], v[180:183], v[212:215], v[66:69]
	v_mfma_f32_16x16x32_bf16 v[118:121], v[176:179], v[192:195], v[118:121]
	v_mfma_f32_16x16x32_bf16 v[114:117], v[184:187], v[192:195], v[114:117]
	v_mfma_f32_16x16x32_bf16 v[102:105], v[176:179], v[200:203], v[102:105]
	v_mfma_f32_16x16x32_bf16 v[98:101], v[184:187], v[200:203], v[98:101]
	v_mfma_f32_16x16x32_bf16 v[86:89], v[176:179], v[208:211], v[86:89]
	v_mfma_f32_16x16x32_bf16 v[82:85], v[184:187], v[208:211], v[82:85]
	v_mfma_f32_16x16x32_bf16 v[70:73], v[176:179], v[216:219], v[70:73]
	v_mfma_f32_16x16x32_bf16 v[66:69], v[184:187], v[216:219], v[66:69]
	s_setprio 0
	s_barrier
	s_add_i32 s36, s54, s38
	v_lshl_add_u64 v[160:161], v[160:161], 0, s[10:11]
	s_mov_b32 m0, s36
	ds_read_b128 v[188:191], v158 offset:49152
	ds_read_b128 v[192:195], v158 offset:50176
	ds_read_b128 v[196:199], v158 offset:51200
	ds_read_b128 v[200:203], v158 offset:52224
	ds_read_b128 v[204:207], v158 offset:53248
	ds_read_b128 v[208:211], v158 offset:54272
	ds_read_b128 v[212:215], v158 offset:55296
	ds_read_b128 v[216:219], v158 offset:56320
	global_load_lds_dwordx4 v[160:161], off
	s_add_i32 m0, s36, 0x2000
	s_add_u32 s34, s34, 0x100080
	v_lshl_add_u64 v[160:161], v[220:221], 0, s[10:11]
	s_addc_u32 s35, s35, 0
	s_add_i32 s36, s55, s38
	global_load_lds_dwordx4 v[160:161], off
	v_lshl_add_u64 v[160:161], s[34:35], 0, v[132:133]
	s_mov_b32 m0, s36
	s_nop 0
	global_load_lds_dwordx4 v[160:161], off
	v_lshl_add_u64 v[160:161], s[34:35], 0, v[136:137]
	s_add_i32 m0, s36, 0x2000
	s_nop 0
	global_load_lds_dwordx4 v[160:161], off
	v_lshl_add_u64 v[222:223], v[222:223], 0, s[10:11]
	v_lshl_add_u64 v[224:225], v[224:225], 0, s[10:11]
	s_waitcnt vmcnt(6)
	s_waitcnt lgkmcnt(0)
	s_barrier
	s_setprio 1
	s_waitcnt lgkmcnt(0)
	v_mfma_f32_16x16x32_bf16 v[62:65], v[146:149], v[188:191], v[62:65]
	v_mfma_f32_16x16x32_bf16 v[58:61], v[164:167], v[188:191], v[58:61]
	v_mfma_f32_16x16x32_bf16 v[46:49], v[146:149], v[196:199], v[46:49]
	v_mfma_f32_16x16x32_bf16 v[42:45], v[164:167], v[196:199], v[42:45]
	v_mfma_f32_16x16x32_bf16 v[30:33], v[146:149], v[204:207], v[30:33]
	v_mfma_f32_16x16x32_bf16 v[26:29], v[164:167], v[204:207], v[26:29]
	v_mfma_f32_16x16x32_bf16 v[14:17], v[146:149], v[212:215], v[14:17]
	v_mfma_f32_16x16x32_bf16 v[10:13], v[164:167], v[212:215], v[10:13]
	v_mfma_f32_16x16x32_bf16 v[62:65], v[150:153], v[192:195], v[62:65]
	v_mfma_f32_16x16x32_bf16 v[58:61], v[168:171], v[192:195], v[58:61]
	v_mfma_f32_16x16x32_bf16 v[46:49], v[150:153], v[200:203], v[46:49]
	v_mfma_f32_16x16x32_bf16 v[42:45], v[168:171], v[200:203], v[42:45]
	v_mfma_f32_16x16x32_bf16 v[30:33], v[150:153], v[208:211], v[30:33]
	v_mfma_f32_16x16x32_bf16 v[26:29], v[168:171], v[208:211], v[26:29]
	v_mfma_f32_16x16x32_bf16 v[14:17], v[150:153], v[216:219], v[14:17]
	v_mfma_f32_16x16x32_bf16 v[10:13], v[168:171], v[216:219], v[10:13]
	s_setprio 0
	s_setprio 1
	v_mfma_f32_16x16x32_bf16 v[54:57], v[172:175], v[188:191], v[54:57]
	v_mfma_f32_16x16x32_bf16 v[50:53], v[180:183], v[188:191], v[50:53]
	v_mfma_f32_16x16x32_bf16 v[38:41], v[172:175], v[196:199], v[38:41]
	v_mfma_f32_16x16x32_bf16 v[34:37], v[180:183], v[196:199], v[34:37]
	v_mfma_f32_16x16x32_bf16 v[22:25], v[172:175], v[204:207], v[22:25]
	v_mfma_f32_16x16x32_bf16 v[18:21], v[180:183], v[204:207], v[18:21]
	v_mfma_f32_16x16x32_bf16 v[6:9], v[172:175], v[212:215], v[6:9]
	v_mfma_f32_16x16x32_bf16 v[2:5], v[180:183], v[212:215], v[2:5]
	v_mfma_f32_16x16x32_bf16 v[54:57], v[176:179], v[192:195], v[54:57]
	v_mfma_f32_16x16x32_bf16 v[50:53], v[184:187], v[192:195], v[50:53]
	v_mfma_f32_16x16x32_bf16 v[38:41], v[176:179], v[200:203], v[38:41]
	v_mfma_f32_16x16x32_bf16 v[34:37], v[184:187], v[200:203], v[34:37]
	v_mfma_f32_16x16x32_bf16 v[22:25], v[176:179], v[208:211], v[22:25]
	v_mfma_f32_16x16x32_bf16 v[18:21], v[184:187], v[208:211], v[18:21]
	v_mfma_f32_16x16x32_bf16 v[6:9], v[176:179], v[216:219], v[6:9]
	v_mfma_f32_16x16x32_bf16 v[2:5], v[184:187], v[216:219], v[2:5]
	s_setprio 0
	s_barrier
	s_add_i32 s53, s53, 2
	s_mov_b32 s32, 1
	s_add_u32 s30, s30, 0x100
	s_addc_u32 s31, s31, 0
	s_add_u32 s51, s51, 0x100
	s_addc_u32 s52, s52, 0
	s_cmp_gt_u32 s53, 61
	s_cbranch_scc0 .LBB0_1131
	s_and_b64 vcc, exec, s[12:13]
	s_cbranch_vccz .LBB0_1134
	s_barrier

.LBB0_1254:
	s_lshl_b32 s6, s6, 5
	s_and_b32 s12, s6, 0x60
	s_mov_b64 s[6:7], 0x80
	s_add_i32 m0, s36, 0x18000
	v_lshl_add_u64 v[8:9], v[8:9], 0, s[6:7]
	s_lshl_b32 s9, s8, 13
	s_lshl_b32 s13, s12, 7
	s_waitcnt vmcnt(2)
	s_barrier
	global_load_lds_dwordx4 v[8:9], off
	v_lshl_add_u64 v[6:7], v[6:7], 0, s[6:7]
	s_add_i32 m0, s36, 0x1a000
	s_add_i32 s41, s36, 0x8000
	s_add_i32 s42, s36, 0xa000
	global_load_lds_dwordx4 v[6:7], off
	v_lshl_add_u64 v[2:3], v[2:3], 0, s[6:7]
	s_mov_b32 m0, s41
	s_add_u32 s10, s28, 0x100080
	global_load_lds_dwordx4 v[2:3], off
	v_lshl_add_u64 v[2:3], v[4:5], 0, s[6:7]
	s_mov_b32 m0, s42
	s_addc_u32 s11, s29, 0
	global_load_lds_dwordx4 v[2:3], off
	s_add_i32 m0, s36, 0x1c000
	v_lshl_add_u64 v[2:3], s[10:11], 0, v[134:135]
	global_load_lds_dwordx4 v[2:3], off
	v_lshl_add_u64 v[2:3], s[10:11], 0, v[130:131]
	s_add_i32 m0, s36, 0x1e000
	v_lshlrev_b32_e32 v4, 2, v0
	global_load_lds_dwordx4 v[2:3], off
	v_and_b32_e32 v2, 15, v0
	v_lshlrev_b32_e32 v3, 1, v14
	v_lshl_or_b32 v1, s8, 6, v2
	v_lshl_or_b32 v2, v2, 6, v3
	v_and_b32_e32 v4, 32, v4
	s_sext_i32_i16 s51, s4
	v_bitop3_b32 v5, v2, s9, v4 bitop3:0xde
	v_lshlrev_b32_e32 v2, 6, v0
	s_movk_i32 s4, 0x3c0
	v_and_or_b32 v2, v2, s4, v3
	s_cmpk_lt_u32 s5, 0x100
	v_or_b32_e32 v165, s12, v14
	v_readlane_b32 s4, v247, 31
	v_bitop3_b32 v164, s13, v2, v4 bitop3:0xf6
	v_lshlrev_b32_e32 v2, 2, v165
	v_mov_b32_e32 v3, v135
	v_readlane_b32 s5, v247, 32
	s_waitcnt vmcnt(6)
	s_cselect_b64 s[8:9], -1, 0
	s_add_i32 s44, 0, 0x10000
	v_lshl_add_u64 v[138:139], s[4:5], 0, v[2:3]
	v_lshlrev_b32_e32 v2, 10, v0
	v_and_b32_e32 v2, 0x60000, v2
	v_lshlrev_b32_e32 v3, 13, v13
	v_or3_b32 v2, v11, v2, v3
	v_add_u32_e32 v140, v2, v12
	v_lshlrev_b32_e32 v2, 6, v10
	v_and_b32_e32 v2, 0xe0000, v2
	v_or3_b32 v2, v11, v2, v3
	s_add_i32 s45, 0, 0x14000
	s_ashr_i32 s43, s96, 31
	v_mov_b32_e32 v141, v135
	v_add_u32_e32 v142, v2, v12
	v_mov_b32_e32 v143, v135
	v_mov_b64_e32 v[144:145], 0x700
	v_mov_b64_e32 v[146:147], 0x6ff
	v_add_u32_e32 v166, s44, v164
	v_add_u32_e32 v167, s45, v164
	v_add_u32_e32 v168, 0, v5
	s_mov_b32 s46, 0x20000
	s_mov_b64 s[10:11], 0x24000
	s_mov_b32 s47, 0x24000
	s_mov_b64 s[12:13], 0x28000
	s_mov_b32 s48, 0x28000
	s_mov_b64 s[14:15], 0x2c000
	s_mov_b32 s49, 0x2c000
	s_movk_i32 s50, 0x7000
	s_barrier
	s_mov_b32 s32, 0
	s_branch .LBB0_1257

.LBB0_1260:
	ds_read_b128 v[148:151], v166
	ds_read_b128 v[152:155], v166 offset:1024
	ds_read_b128 v[156:159], v166 offset:2048
	ds_read_b128 v[170:173], v166 offset:3072
	ds_read_b128 v[174:177], v167
	ds_read_b128 v[178:181], v167 offset:1024
	ds_read_b128 v[182:185], v167 offset:2048
	ds_read_b128 v[186:189], v167 offset:3072
	s_add_u32 s28, s26, 0xfff00080
	s_addc_u32 s29, s27, -1
	s_cmp_eq_u32 s55, 60
	s_cselect_b32 s31, s19, s29
	s_cselect_b32 s30, s25, s28
	s_cselect_b32 s29, s17, s54
	s_cselect_b32 s28, s52, s53
	v_lshl_add_u64 v[160:161], s[26:27], 0, v[140:141]
	s_add_i32 m0, s36, 0xc000
	ds_read_b128 v[190:193], v168
	ds_read_b128 v[194:197], v168 offset:1024
	ds_read_b128 v[198:201], v168 offset:2048
	ds_read_b128 v[202:205], v168 offset:3072
	ds_read_b128 v[206:209], v168 offset:4096
	ds_read_b128 v[210:213], v168 offset:5120
	ds_read_b128 v[214:217], v168 offset:6144
	ds_read_b128 v[218:221], v168 offset:7168
	s_cmp_lg_u32 s32, 0
	s_cbranch_scc0 .Lrebal_skip_1260
	s_mov_b32 m0, s41
	s_nop 0
	global_load_lds_dwordx4 v[224:225], off
	s_mov_b32 m0, s42
	s_nop 0
	global_load_lds_dwordx4 v[226:227], off
.Lrebal_skip_1260:
	s_add_i32 m0, s36, 0xc000
	s_nop 0
	global_load_lds_dwordx4 v[160:161], off
	v_lshl_add_u64 v[160:161], s[26:27], 0, v[142:143]
	s_add_i32 m0, s36, 0xe000
	s_nop 0
	global_load_lds_dwordx4 v[160:161], off
	s_waitcnt vmcnt(8)
	s_waitcnt lgkmcnt(0)
	s_barrier
	s_setprio 1
	s_waitcnt lgkmcnt(0)
	v_mfma_f32_16x16x32_bf16 v[126:129], v[148:151], v[190:193], v[126:129]
	v_mfma_f32_16x16x32_bf16 v[122:125], v[156:159], v[190:193], v[122:125]
	v_mfma_f32_16x16x32_bf16 v[110:113], v[148:151], v[198:201], v[110:113]
	v_mfma_f32_16x16x32_bf16 v[106:109], v[156:159], v[198:201], v[106:109]
	v_mfma_f32_16x16x32_bf16 v[94:97], v[148:151], v[206:209], v[94:97]
	v_mfma_f32_16x16x32_bf16 v[90:93], v[156:159], v[206:209], v[90:93]
	v_mfma_f32_16x16x32_bf16 v[86:89], v[148:151], v[214:217], v[86:89]
	v_mfma_f32_16x16x32_bf16 v[78:81], v[156:159], v[214:217], v[78:81]
	v_mfma_f32_16x16x32_bf16 v[126:129], v[152:155], v[194:197], v[126:129]
	v_mfma_f32_16x16x32_bf16 v[122:125], v[170:173], v[194:197], v[122:125]
	v_mfma_f32_16x16x32_bf16 v[110:113], v[152:155], v[202:205], v[110:113]
	v_mfma_f32_16x16x32_bf16 v[106:109], v[170:173], v[202:205], v[106:109]
	v_mfma_f32_16x16x32_bf16 v[94:97], v[152:155], v[210:213], v[94:97]
	v_mfma_f32_16x16x32_bf16 v[90:93], v[170:173], v[210:213], v[90:93]
	v_mfma_f32_16x16x32_bf16 v[86:89], v[152:155], v[218:221], v[86:89]
	v_mfma_f32_16x16x32_bf16 v[78:81], v[170:173], v[218:221], v[78:81]
	s_setprio 0
	s_setprio 1
	v_mfma_f32_16x16x32_bf16 v[118:121], v[174:177], v[190:193], v[118:121]
	v_mfma_f32_16x16x32_bf16 v[114:117], v[182:185], v[190:193], v[114:117]
	v_mfma_f32_16x16x32_bf16 v[102:105], v[174:177], v[198:201], v[102:105]
	v_mfma_f32_16x16x32_bf16 v[98:101], v[182:185], v[198:201], v[98:101]
	v_mfma_f32_16x16x32_bf16 v[82:85], v[174:177], v[206:209], v[82:85]
	v_mfma_f32_16x16x32_bf16 v[74:77], v[182:185], v[206:209], v[74:77]
	v_mfma_f32_16x16x32_bf16 v[70:73], v[174:177], v[214:217], v[70:73]
	v_mfma_f32_16x16x32_bf16 v[66:69], v[182:185], v[214:217], v[66:69]
	v_mfma_f32_16x16x32_bf16 v[118:121], v[178:181], v[194:197], v[118:121]
	v_mfma_f32_16x16x32_bf16 v[114:117], v[186:189], v[194:197], v[114:117]
	v_mfma_f32_16x16x32_bf16 v[102:105], v[178:181], v[202:205], v[102:105]
	v_mfma_f32_16x16x32_bf16 v[98:101], v[186:189], v[202:205], v[98:101]
	v_mfma_f32_16x16x32_bf16 v[82:85], v[178:181], v[210:213], v[82:85]
	v_mfma_f32_16x16x32_bf16 v[74:77], v[186:189], v[210:213], v[74:77]
	v_mfma_f32_16x16x32_bf16 v[70:73], v[178:181], v[218:221], v[70:73]
	v_mfma_f32_16x16x32_bf16 v[66:69], v[186:189], v[218:221], v[66:69]
	s_setprio 0
	s_barrier
	s_add_i32 s56, s44, s33
	v_lshl_add_u64 v[160:161], s[28:29], 0, v[134:135]
	s_mov_b32 m0, s56
	ds_read_b128 v[190:193], v168 offset:16384
	ds_read_b128 v[194:197], v168 offset:17408
	ds_read_b128 v[198:201], v168 offset:18432
	ds_read_b128 v[202:205], v168 offset:19456
	ds_read_b128 v[206:209], v168 offset:20480
	ds_read_b128 v[210:213], v168 offset:21504
	ds_read_b128 v[214:217], v168 offset:22528
	ds_read_b128 v[218:221], v168 offset:23552
	global_load_lds_dwordx4 v[160:161], off
	s_add_i32 m0, s56, 0x2000
	s_add_u32 s56, s28, 0x100000
	v_lshl_add_u64 v[222:223], s[28:29], 0, v[130:131]
	s_addc_u32 s57, s29, 0
	s_add_i32 s58, s45, s33
	global_load_lds_dwordx4 v[222:223], off
	v_lshl_add_u64 v[224:225], s[56:57], 0, v[134:135]
	s_mov_b32 m0, s58
	v_lshl_add_u64 v[226:227], s[30:31], 0, v[132:133]
	global_load_lds_dwordx4 v[224:225], off
	v_lshl_add_u64 v[224:225], s[56:57], 0, v[130:131]
	s_add_i32 m0, s58, 0x2000
	s_nop 0
	global_load_lds_dwordx4 v[224:225], off
	v_lshl_add_u64 v[224:225], s[30:31], 0, v[136:137]
	s_waitcnt vmcnt(6)
	s_waitcnt lgkmcnt(0)
	s_barrier
	s_setprio 1
	s_waitcnt lgkmcnt(0)
	v_mfma_f32_16x16x32_bf16 v[62:65], v[148:151], v[190:193], v[62:65]
	v_mfma_f32_16x16x32_bf16 v[58:61], v[156:159], v[190:193], v[58:61]
	v_mfma_f32_16x16x32_bf16 v[46:49], v[148:151], v[198:201], v[46:49]
	v_mfma_f32_16x16x32_bf16 v[42:45], v[156:159], v[198:201], v[42:45]
	v_mfma_f32_16x16x32_bf16 v[30:33], v[148:151], v[206:209], v[30:33]
	v_mfma_f32_16x16x32_bf16 v[26:29], v[156:159], v[206:209], v[26:29]
	v_mfma_f32_16x16x32_bf16 v[14:17], v[148:151], v[214:217], v[14:17]
	v_mfma_f32_16x16x32_bf16 v[10:13], v[156:159], v[214:217], v[10:13]
	v_mfma_f32_16x16x32_bf16 v[62:65], v[152:155], v[194:197], v[62:65]
	v_mfma_f32_16x16x32_bf16 v[58:61], v[170:173], v[194:197], v[58:61]
	v_mfma_f32_16x16x32_bf16 v[46:49], v[152:155], v[202:205], v[46:49]
	v_mfma_f32_16x16x32_bf16 v[42:45], v[170:173], v[202:205], v[42:45]
	v_mfma_f32_16x16x32_bf16 v[30:33], v[152:155], v[210:213], v[30:33]
	v_mfma_f32_16x16x32_bf16 v[26:29], v[170:173], v[210:213], v[26:29]
	v_mfma_f32_16x16x32_bf16 v[14:17], v[152:155], v[218:221], v[14:17]
	v_mfma_f32_16x16x32_bf16 v[10:13], v[170:173], v[218:221], v[10:13]
	s_setprio 0
	s_setprio 1
	v_mfma_f32_16x16x32_bf16 v[54:57], v[174:177], v[190:193], v[54:57]
	v_mfma_f32_16x16x32_bf16 v[50:53], v[182:185], v[190:193], v[50:53]
	v_mfma_f32_16x16x32_bf16 v[38:41], v[174:177], v[198:201], v[38:41]
	v_mfma_f32_16x16x32_bf16 v[34:37], v[182:185], v[198:201], v[34:37]
	v_mfma_f32_16x16x32_bf16 v[22:25], v[174:177], v[206:209], v[22:25]
	v_mfma_f32_16x16x32_bf16 v[18:21], v[182:185], v[206:209], v[18:21]
	v_mfma_f32_16x16x32_bf16 v[6:9], v[174:177], v[214:217], v[6:9]
	v_mfma_f32_16x16x32_bf16 v[2:5], v[182:185], v[214:217], v[2:5]
	v_mfma_f32_16x16x32_bf16 v[54:57], v[178:181], v[194:197], v[54:57]
	v_mfma_f32_16x16x32_bf16 v[50:53], v[186:189], v[194:197], v[50:53]
	v_mfma_f32_16x16x32_bf16 v[38:41], v[178:181], v[202:205], v[38:41]
	v_mfma_f32_16x16x32_bf16 v[34:37], v[186:189], v[202:205], v[34:37]
	v_mfma_f32_16x16x32_bf16 v[22:25], v[178:181], v[210:213], v[22:25]
	v_mfma_f32_16x16x32_bf16 v[18:21], v[186:189], v[210:213], v[18:21]
	v_mfma_f32_16x16x32_bf16 v[6:9], v[178:181], v[218:221], v[6:9]
	v_mfma_f32_16x16x32_bf16 v[2:5], v[186:189], v[218:221], v[2:5]
	s_setprio 0
	s_barrier
	s_add_i32 s56, 0, 0x18000
	v_add_u32_e32 v169, s56, v164
	s_add_i32 s57, 0, 0x1c000
	ds_read_b128 v[148:151], v169
	ds_read_b128 v[152:155], v169 offset:1024
	ds_read_b128 v[156:159], v169 offset:2048
	ds_read_b128 v[170:173], v169 offset:3072
	v_add_u32_e32 v169, s57, v164
	ds_read_b128 v[174:177], v169
	ds_read_b128 v[178:181], v169 offset:1024
	ds_read_b128 v[182:185], v169 offset:2048
	ds_read_b128 v[186:189], v169 offset:3072
	s_add_u32 s30, s30, 0x100000
	s_addc_u32 s31, s31, 0
	s_mov_b32 m0, s38
	v_lshl_add_u64 v[228:229], s[30:31], 0, v[136:137]
	ds_read_b128 v[190:193], v168 offset:32768
	ds_read_b128 v[194:197], v168 offset:33792
	ds_read_b128 v[198:201], v168 offset:34816
	ds_read_b128 v[202:205], v168 offset:35840
	ds_read_b128 v[206:209], v168 offset:36864
	ds_read_b128 v[210:213], v168 offset:37888
	ds_read_b128 v[214:217], v168 offset:38912
	ds_read_b128 v[218:221], v168 offset:39936
	s_mov_b32 m0, s36
	s_nop 0
	global_load_lds_dwordx4 v[224:225], off
	s_mov_b32 m0, s37
	s_nop 0
	global_load_lds_dwordx4 v[226:227], off
	s_mov_b32 m0, s38
	s_nop 0
	global_load_lds_dwordx4 v[228:229], off
	v_lshl_add_u64 v[228:229], s[30:31], 0, v[132:133]
	s_mov_b32 m0, s39
	s_nop 0
	global_load_lds_dwordx4 v[228:229], off
	s_waitcnt vmcnt(8)
	s_waitcnt lgkmcnt(0)
	s_barrier
	s_setprio 1
	s_waitcnt lgkmcnt(0)
	v_mfma_f32_16x16x32_bf16 v[126:129], v[148:151], v[190:193], v[126:129]
	v_mfma_f32_16x16x32_bf16 v[122:125], v[156:159], v[190:193], v[122:125]
	v_mfma_f32_16x16x32_bf16 v[110:113], v[148:151], v[198:201], v[110:113]
	v_mfma_f32_16x16x32_bf16 v[106:109], v[156:159], v[198:201], v[106:109]
	v_mfma_f32_16x16x32_bf16 v[94:97], v[148:151], v[206:209], v[94:97]
	v_mfma_f32_16x16x32_bf16 v[90:93], v[156:159], v[206:209], v[90:93]
	v_mfma_f32_16x16x32_bf16 v[86:89], v[148:151], v[214:217], v[86:89]
	v_mfma_f32_16x16x32_bf16 v[78:81], v[156:159], v[214:217], v[78:81]
	v_mfma_f32_16x16x32_bf16 v[126:129], v[152:155], v[194:197], v[126:129]
	v_mfma_f32_16x16x32_bf16 v[122:125], v[170:173], v[194:197], v[122:125]
	v_mfma_f32_16x16x32_bf16 v[110:113], v[152:155], v[202:205], v[110:113]
	v_mfma_f32_16x16x32_bf16 v[106:109], v[170:173], v[202:205], v[106:109]
	v_mfma_f32_16x16x32_bf16 v[94:97], v[152:155], v[210:213], v[94:97]
	v_mfma_f32_16x16x32_bf16 v[90:93], v[170:173], v[210:213], v[90:93]
	v_mfma_f32_16x16x32_bf16 v[86:89], v[152:155], v[218:221], v[86:89]
	v_mfma_f32_16x16x32_bf16 v[78:81], v[170:173], v[218:221], v[78:81]
	s_setprio 0
	s_setprio 1
	v_mfma_f32_16x16x32_bf16 v[118:121], v[174:177], v[190:193], v[118:121]
	v_mfma_f32_16x16x32_bf16 v[114:117], v[182:185], v[190:193], v[114:117]
	v_mfma_f32_16x16x32_bf16 v[102:105], v[174:177], v[198:201], v[102:105]
	v_mfma_f32_16x16x32_bf16 v[98:101], v[182:185], v[198:201], v[98:101]
	v_mfma_f32_16x16x32_bf16 v[82:85], v[174:177], v[206:209], v[82:85]
	v_mfma_f32_16x16x32_bf16 v[74:77], v[182:185], v[206:209], v[74:77]
	v_mfma_f32_16x16x32_bf16 v[70:73], v[174:177], v[214:217], v[70:73]
	v_mfma_f32_16x16x32_bf16 v[66:69], v[182:185], v[214:217], v[66:69]
	v_mfma_f32_16x16x32_bf16 v[118:121], v[178:181], v[194:197], v[118:121]
	v_mfma_f32_16x16x32_bf16 v[114:117], v[186:189], v[194:197], v[114:117]
	v_mfma_f32_16x16x32_bf16 v[102:105], v[178:181], v[202:205], v[102:105]
	v_mfma_f32_16x16x32_bf16 v[98:101], v[186:189], v[202:205], v[98:101]
	v_mfma_f32_16x16x32_bf16 v[82:85], v[178:181], v[210:213], v[82:85]
	v_mfma_f32_16x16x32_bf16 v[74:77], v[186:189], v[210:213], v[74:77]
	v_mfma_f32_16x16x32_bf16 v[70:73], v[178:181], v[218:221], v[70:73]
	v_mfma_f32_16x16x32_bf16 v[66:69], v[186:189], v[218:221], v[66:69]
	s_setprio 0
	s_barrier
	s_add_i32 s30, s56, s33
	v_lshl_add_u64 v[160:161], v[160:161], 0, s[6:7]
	s_mov_b32 m0, s30
	ds_read_b128 v[190:193], v168 offset:49152
	ds_read_b128 v[194:197], v168 offset:50176
	ds_read_b128 v[198:201], v168 offset:51200
	ds_read_b128 v[202:205], v168 offset:52224
	ds_read_b128 v[206:209], v168 offset:53248
	ds_read_b128 v[210:213], v168 offset:54272
	ds_read_b128 v[214:217], v168 offset:55296
	ds_read_b128 v[218:221], v168 offset:56320
	global_load_lds_dwordx4 v[160:161], off
	s_add_i32 m0, s30, 0x2000
	s_add_u32 s28, s28, 0x100080
	v_lshl_add_u64 v[160:161], v[222:223], 0, s[6:7]
	s_addc_u32 s29, s29, 0
	s_add_i32 s30, s57, s33
	global_load_lds_dwordx4 v[160:161], off
	v_lshl_add_u64 v[160:161], s[28:29], 0, v[134:135]
	s_mov_b32 m0, s30
	s_nop 0
	global_load_lds_dwordx4 v[160:161], off
	v_lshl_add_u64 v[160:161], s[28:29], 0, v[130:131]
	s_add_i32 m0, s30, 0x2000
	s_nop 0
	global_load_lds_dwordx4 v[160:161], off
	v_lshl_add_u64 v[224:225], v[224:225], 0, s[6:7]
	v_lshl_add_u64 v[226:227], v[226:227], 0, s[6:7]
	s_waitcnt vmcnt(6)
	s_waitcnt lgkmcnt(0)
	s_barrier
	s_setprio 1
	s_waitcnt lgkmcnt(0)
	v_mfma_f32_16x16x32_bf16 v[62:65], v[148:151], v[190:193], v[62:65]
	v_mfma_f32_16x16x32_bf16 v[58:61], v[156:159], v[190:193], v[58:61]
	v_mfma_f32_16x16x32_bf16 v[46:49], v[148:151], v[198:201], v[46:49]
	v_mfma_f32_16x16x32_bf16 v[42:45], v[156:159], v[198:201], v[42:45]
	v_mfma_f32_16x16x32_bf16 v[30:33], v[148:151], v[206:209], v[30:33]
	v_mfma_f32_16x16x32_bf16 v[26:29], v[156:159], v[206:209], v[26:29]
	v_mfma_f32_16x16x32_bf16 v[14:17], v[148:151], v[214:217], v[14:17]
	v_mfma_f32_16x16x32_bf16 v[10:13], v[156:159], v[214:217], v[10:13]
	v_mfma_f32_16x16x32_bf16 v[62:65], v[152:155], v[194:197], v[62:65]
	v_mfma_f32_16x16x32_bf16 v[58:61], v[170:173], v[194:197], v[58:61]
	v_mfma_f32_16x16x32_bf16 v[46:49], v[152:155], v[202:205], v[46:49]
	v_mfma_f32_16x16x32_bf16 v[42:45], v[170:173], v[202:205], v[42:45]
	v_mfma_f32_16x16x32_bf16 v[30:33], v[152:155], v[210:213], v[30:33]
	v_mfma_f32_16x16x32_bf16 v[26:29], v[170:173], v[210:213], v[26:29]
	v_mfma_f32_16x16x32_bf16 v[14:17], v[152:155], v[218:221], v[14:17]
	v_mfma_f32_16x16x32_bf16 v[10:13], v[170:173], v[218:221], v[10:13]
	s_setprio 0
	s_setprio 1
	v_mfma_f32_16x16x32_bf16 v[54:57], v[174:177], v[190:193], v[54:57]
	v_mfma_f32_16x16x32_bf16 v[50:53], v[182:185], v[190:193], v[50:53]
	v_mfma_f32_16x16x32_bf16 v[38:41], v[174:177], v[198:201], v[38:41]
	v_mfma_f32_16x16x32_bf16 v[34:37], v[182:185], v[198:201], v[34:37]
	v_mfma_f32_16x16x32_bf16 v[22:25], v[174:177], v[206:209], v[22:25]
	v_mfma_f32_16x16x32_bf16 v[18:21], v[182:185], v[206:209], v[18:21]
	v_mfma_f32_16x16x32_bf16 v[6:9], v[174:177], v[214:217], v[6:9]
	v_mfma_f32_16x16x32_bf16 v[2:5], v[182:185], v[214:217], v[2:5]
	v_mfma_f32_16x16x32_bf16 v[54:57], v[178:181], v[194:197], v[54:57]
	v_mfma_f32_16x16x32_bf16 v[50:53], v[186:189], v[194:197], v[50:53]
	v_mfma_f32_16x16x32_bf16 v[38:41], v[178:181], v[202:205], v[38:41]
	v_mfma_f32_16x16x32_bf16 v[34:37], v[186:189], v[202:205], v[34:37]
	v_mfma_f32_16x16x32_bf16 v[22:25], v[178:181], v[210:213], v[22:25]
	v_mfma_f32_16x16x32_bf16 v[18:21], v[186:189], v[210:213], v[18:21]
	v_mfma_f32_16x16x32_bf16 v[6:9], v[178:181], v[218:221], v[6:9]
	v_mfma_f32_16x16x32_bf16 v[2:5], v[186:189], v[218:221], v[2:5]
	s_setprio 0
	s_barrier
	s_add_i32 s55, s55, 2
	s_mov_b32 s32, 1
	s_add_u32 s26, s26, 0x100
	s_addc_u32 s27, s27, 0
	s_add_u32 s53, s53, 0x100
	s_addc_u32 s54, s54, 0
	s_cmp_gt_u32 s55, 61
	s_cbranch_scc0 .LBB0_1260
	s_and_b64 vcc, exec, s[8:9]
	s_cbranch_vccz .LBB0_1263
	s_barrier

.LBB0_1561:
	s_lshl_b32 s10, s10, 5
	s_and_b32 s16, s10, 0x60
	s_mov_b64 s[10:11], 0x80
	s_add_i32 m0, s29, 0x18000
	v_lshl_add_u64 v[8:9], v[8:9], 0, s[10:11]
	s_lshl_b32 s13, s5, 13
	s_lshl_b32 s17, s16, 7
	s_waitcnt vmcnt(2)
	s_barrier
	global_load_lds_dwordx4 v[8:9], off
	v_lshl_add_u64 v[4:5], v[4:5], 0, s[10:11]
	s_add_i32 m0, s29, 0x1a000
	s_add_i32 s43, s29, 0x8000
	s_add_i32 s44, s29, 0xa000
	global_load_lds_dwordx4 v[4:5], off
	v_lshl_add_u64 v[2:3], v[2:3], 0, s[10:11]
	s_mov_b32 m0, s43
	s_add_u32 s14, s34, 0x100080
	global_load_lds_dwordx4 v[2:3], off
	v_lshl_add_u64 v[2:3], v[6:7], 0, s[10:11]
	s_mov_b32 m0, s44
	s_addc_u32 s15, s35, 0
	global_load_lds_dwordx4 v[2:3], off
	s_add_i32 m0, s29, 0x1c000
	v_lshl_add_u64 v[2:3], s[14:15], 0, v[132:133]
	global_load_lds_dwordx4 v[2:3], off
	v_lshl_add_u64 v[2:3], s[14:15], 0, v[136:137]
	s_add_i32 m0, s29, 0x1e000
	s_sext_i32_i8 s52, s4
	global_load_lds_dwordx4 v[2:3], off
	v_and_b32_e32 v2, 15, v0
	v_lshlrev_b32_e32 v3, 1, v13
	v_lshlrev_b32_e32 v4, 2, v0
	v_lshlrev_b32_e32 v5, 6, v0
	s_movk_i32 s4, 0x3c0
	v_lshl_or_b32 v1, s5, 6, v2
	v_lshl_or_b32 v2, v2, 6, v3
	v_and_b32_e32 v4, 32, v4
	v_and_or_b32 v3, v5, s4, v3
	v_bitop3_b32 v148, s17, v3, v4 bitop3:0xf6
	v_lshlrev_b32_e32 v3, 10, v0
	v_bitop3_b32 v2, v2, s13, v4 bitop3:0xde
	v_and_b32_e32 v3, 0x60000, v3
	v_lshlrev_b32_e32 v4, 13, v12
	v_or3_b32 v3, v10, v3, v4
	v_add_u32_e32 v138, v3, v11
	v_lshlrev_b32_e32 v3, 6, v14
	s_waitcnt vmcnt(6)
	s_cmpk_lt_u32 s12, 0x100
	v_and_b32_e32 v3, 0xe0000, v3
	s_cselect_b64 s[12:13], -1, 0
	v_or3_b32 v3, v10, v3, v4
	s_add_i32 s46, 0, 0x10000
	s_add_i32 s47, 0, 0x14000
	s_ashr_i32 s45, s96, 31
	v_or_b32_e32 v149, s16, v13
	v_mov_b32_e32 v139, v133
	v_add_u32_e32 v140, v3, v11
	v_mov_b32_e32 v141, v133
	v_mov_b64_e32 v[142:143], 0x200
	v_mov_b64_e32 v[144:145], 0x1ff
	v_add_u32_e32 v150, s46, v148
	v_add_u32_e32 v151, s47, v148
	v_add_u32_e32 v152, 0, v2
	s_mov_b32 s48, 0x100000
	s_mov_b64 s[14:15], 0x120000
	s_mov_b32 s49, 0x120000
	s_mov_b64 s[16:17], 0x140000
	s_mov_b32 s50, 0x140000
	s_mov_b64 s[18:19], 0x160000
	s_mov_b32 s51, 0x160000
	s_barrier
	s_mov_b32 s32, 0
	s_branch .LBB0_1564

.LBB0_1571:
	ds_read_b128 v[154:157], v150
	ds_read_b128 v[158:161], v150 offset:1024
	ds_read_b128 v[164:167], v150 offset:2048
	ds_read_b128 v[168:171], v150 offset:3072
	ds_read_b128 v[172:175], v151
	ds_read_b128 v[176:179], v151 offset:1024
	ds_read_b128 v[180:183], v151 offset:2048
	ds_read_b128 v[184:187], v151 offset:3072
	s_add_u32 s34, s30, 0xfff00080
	s_addc_u32 s35, s31, -1
	s_cmp_eq_u32 s57, 60
	s_cselect_b32 s37, s23, s35
	s_cselect_b32 s36, s53, s34
	s_cselect_b32 s35, s21, s56
	s_cselect_b32 s34, s54, s55
	v_lshl_add_u64 v[146:147], s[30:31], 0, v[138:139]
	s_add_i32 m0, s29, 0xc000
	ds_read_b128 v[188:191], v152
	ds_read_b128 v[192:195], v152 offset:1024
	ds_read_b128 v[196:199], v152 offset:2048
	ds_read_b128 v[200:203], v152 offset:3072
	ds_read_b128 v[204:207], v152 offset:4096
	ds_read_b128 v[208:211], v152 offset:5120
	ds_read_b128 v[212:215], v152 offset:6144
	ds_read_b128 v[216:219], v152 offset:7168
	s_cmp_lg_u32 s32, 0
	s_cbranch_scc0 .Lrebal_skip_1571
	s_mov_b32 m0, s43
	s_nop 0
	global_load_lds_dwordx4 v[222:223], off
	s_mov_b32 m0, s44
	s_nop 0
	global_load_lds_dwordx4 v[224:225], off
.Lrebal_skip_1571:
	s_add_i32 m0, s29, 0xc000
	s_nop 0
	global_load_lds_dwordx4 v[146:147], off
	v_lshl_add_u64 v[146:147], s[30:31], 0, v[140:141]
	s_add_i32 m0, s29, 0xe000
	s_nop 0
	global_load_lds_dwordx4 v[146:147], off
	s_waitcnt vmcnt(8)
	s_waitcnt lgkmcnt(0)
	s_barrier
	s_setprio 1
	s_waitcnt lgkmcnt(0)
	v_mfma_f32_16x16x32_bf16 v[126:129], v[154:157], v[188:191], v[126:129]
	v_mfma_f32_16x16x32_bf16 v[122:125], v[164:167], v[188:191], v[122:125]
	v_mfma_f32_16x16x32_bf16 v[118:121], v[154:157], v[196:199], v[118:121]
	v_mfma_f32_16x16x32_bf16 v[110:113], v[164:167], v[196:199], v[110:113]
	v_mfma_f32_16x16x32_bf16 v[102:105], v[154:157], v[204:207], v[102:105]
	v_mfma_f32_16x16x32_bf16 v[94:97], v[164:167], v[204:207], v[94:97]
	v_mfma_f32_16x16x32_bf16 v[82:85], v[154:157], v[212:215], v[82:85]
	v_mfma_f32_16x16x32_bf16 v[74:77], v[164:167], v[212:215], v[74:77]
	v_mfma_f32_16x16x32_bf16 v[126:129], v[158:161], v[192:195], v[126:129]
	v_mfma_f32_16x16x32_bf16 v[122:125], v[168:171], v[192:195], v[122:125]
	v_mfma_f32_16x16x32_bf16 v[118:121], v[158:161], v[200:203], v[118:121]
	v_mfma_f32_16x16x32_bf16 v[110:113], v[168:171], v[200:203], v[110:113]
	v_mfma_f32_16x16x32_bf16 v[102:105], v[158:161], v[208:211], v[102:105]
	v_mfma_f32_16x16x32_bf16 v[94:97], v[168:171], v[208:211], v[94:97]
	v_mfma_f32_16x16x32_bf16 v[82:85], v[158:161], v[216:219], v[82:85]
	v_mfma_f32_16x16x32_bf16 v[74:77], v[168:171], v[216:219], v[74:77]
	s_setprio 0
	s_setprio 1
	v_mfma_f32_16x16x32_bf16 v[114:117], v[172:175], v[188:191], v[114:117]
	v_mfma_f32_16x16x32_bf16 v[106:109], v[180:183], v[188:191], v[106:109]
	v_mfma_f32_16x16x32_bf16 v[98:101], v[172:175], v[196:199], v[98:101]
	v_mfma_f32_16x16x32_bf16 v[90:93], v[180:183], v[196:199], v[90:93]
	v_mfma_f32_16x16x32_bf16 v[86:89], v[172:175], v[204:207], v[86:89]
	v_mfma_f32_16x16x32_bf16 v[78:81], v[180:183], v[204:207], v[78:81]
	v_mfma_f32_16x16x32_bf16 v[70:73], v[172:175], v[212:215], v[70:73]
	v_mfma_f32_16x16x32_bf16 v[66:69], v[180:183], v[212:215], v[66:69]
	v_mfma_f32_16x16x32_bf16 v[114:117], v[176:179], v[192:195], v[114:117]
	v_mfma_f32_16x16x32_bf16 v[106:109], v[184:187], v[192:195], v[106:109]
	v_mfma_f32_16x16x32_bf16 v[98:101], v[176:179], v[200:203], v[98:101]
	v_mfma_f32_16x16x32_bf16 v[90:93], v[184:187], v[200:203], v[90:93]
	v_mfma_f32_16x16x32_bf16 v[86:89], v[176:179], v[208:211], v[86:89]
	v_mfma_f32_16x16x32_bf16 v[78:81], v[184:187], v[208:211], v[78:81]
	v_mfma_f32_16x16x32_bf16 v[70:73], v[176:179], v[216:219], v[70:73]
	v_mfma_f32_16x16x32_bf16 v[66:69], v[184:187], v[216:219], v[66:69]
	s_setprio 0
	s_barrier
	s_add_i32 s58, s46, s38
	v_lshl_add_u64 v[146:147], s[34:35], 0, v[132:133]
	s_mov_b32 m0, s58
	ds_read_b128 v[188:191], v152 offset:16384
	ds_read_b128 v[192:195], v152 offset:17408
	ds_read_b128 v[196:199], v152 offset:18432
	ds_read_b128 v[200:203], v152 offset:19456
	ds_read_b128 v[204:207], v152 offset:20480
	ds_read_b128 v[208:211], v152 offset:21504
	ds_read_b128 v[212:215], v152 offset:22528
	ds_read_b128 v[216:219], v152 offset:23552
	global_load_lds_dwordx4 v[146:147], off
	s_add_i32 m0, s58, 0x2000
	s_add_u32 s58, s34, 0x100000
	v_lshl_add_u64 v[220:221], s[34:35], 0, v[136:137]
	s_addc_u32 s59, s35, 0
	s_add_i32 s60, s47, s38
	global_load_lds_dwordx4 v[220:221], off
	v_lshl_add_u64 v[222:223], s[58:59], 0, v[132:133]
	s_mov_b32 m0, s60
	v_lshl_add_u64 v[224:225], s[36:37], 0, v[134:135]
	global_load_lds_dwordx4 v[222:223], off
	v_lshl_add_u64 v[222:223], s[58:59], 0, v[136:137]
	s_add_i32 m0, s60, 0x2000
	s_nop 0
	global_load_lds_dwordx4 v[222:223], off
	v_lshl_add_u64 v[222:223], s[36:37], 0, v[130:131]
	s_waitcnt vmcnt(6)
	s_waitcnt lgkmcnt(0)
	s_barrier
	s_setprio 1
	s_waitcnt lgkmcnt(0)
	v_mfma_f32_16x16x32_bf16 v[62:65], v[154:157], v[188:191], v[62:65]
	v_mfma_f32_16x16x32_bf16 v[58:61], v[164:167], v[188:191], v[58:61]
	v_mfma_f32_16x16x32_bf16 v[54:57], v[154:157], v[196:199], v[54:57]
	v_mfma_f32_16x16x32_bf16 v[46:49], v[164:167], v[196:199], v[46:49]
	v_mfma_f32_16x16x32_bf16 v[38:41], v[154:157], v[204:207], v[38:41]
	v_mfma_f32_16x16x32_bf16 v[30:33], v[164:167], v[204:207], v[30:33]
	v_mfma_f32_16x16x32_bf16 v[22:25], v[154:157], v[212:215], v[22:25]
	v_mfma_f32_16x16x32_bf16 v[14:17], v[164:167], v[212:215], v[14:17]
	v_mfma_f32_16x16x32_bf16 v[62:65], v[158:161], v[192:195], v[62:65]
	v_mfma_f32_16x16x32_bf16 v[58:61], v[168:171], v[192:195], v[58:61]
	v_mfma_f32_16x16x32_bf16 v[54:57], v[158:161], v[200:203], v[54:57]
	v_mfma_f32_16x16x32_bf16 v[46:49], v[168:171], v[200:203], v[46:49]
	v_mfma_f32_16x16x32_bf16 v[38:41], v[158:161], v[208:211], v[38:41]
	v_mfma_f32_16x16x32_bf16 v[30:33], v[168:171], v[208:211], v[30:33]
	v_mfma_f32_16x16x32_bf16 v[22:25], v[158:161], v[216:219], v[22:25]
	v_mfma_f32_16x16x32_bf16 v[14:17], v[168:171], v[216:219], v[14:17]
	s_setprio 0
	s_setprio 1
	v_mfma_f32_16x16x32_bf16 v[50:53], v[172:175], v[188:191], v[50:53]
	v_mfma_f32_16x16x32_bf16 v[42:45], v[180:183], v[188:191], v[42:45]
	v_mfma_f32_16x16x32_bf16 v[34:37], v[172:175], v[196:199], v[34:37]
	v_mfma_f32_16x16x32_bf16 v[26:29], v[180:183], v[196:199], v[26:29]
	v_mfma_f32_16x16x32_bf16 v[18:21], v[172:175], v[204:207], v[18:21]
	v_mfma_f32_16x16x32_bf16 v[10:13], v[180:183], v[204:207], v[10:13]
	v_mfma_f32_16x16x32_bf16 v[6:9], v[172:175], v[212:215], v[6:9]
	v_mfma_f32_16x16x32_bf16 v[2:5], v[180:183], v[212:215], v[2:5]
	v_mfma_f32_16x16x32_bf16 v[50:53], v[176:179], v[192:195], v[50:53]
	v_mfma_f32_16x16x32_bf16 v[42:45], v[184:187], v[192:195], v[42:45]
	v_mfma_f32_16x16x32_bf16 v[34:37], v[176:179], v[200:203], v[34:37]
	v_mfma_f32_16x16x32_bf16 v[26:29], v[184:187], v[200:203], v[26:29]
	v_mfma_f32_16x16x32_bf16 v[18:21], v[176:179], v[208:211], v[18:21]
	v_mfma_f32_16x16x32_bf16 v[10:13], v[184:187], v[208:211], v[10:13]
	v_mfma_f32_16x16x32_bf16 v[6:9], v[176:179], v[216:219], v[6:9]
	v_mfma_f32_16x16x32_bf16 v[2:5], v[184:187], v[216:219], v[2:5]
	s_setprio 0
	s_barrier
	s_add_i32 s58, 0, 0x18000
	v_add_u32_e32 v153, s58, v148
	s_add_i32 s59, 0, 0x1c000
	ds_read_b128 v[154:157], v153
	ds_read_b128 v[158:161], v153 offset:1024
	ds_read_b128 v[164:167], v153 offset:2048
	ds_read_b128 v[168:171], v153 offset:3072
	v_add_u32_e32 v153, s59, v148
	ds_read_b128 v[172:175], v153
	ds_read_b128 v[176:179], v153 offset:1024
	ds_read_b128 v[180:183], v153 offset:2048
	ds_read_b128 v[184:187], v153 offset:3072
	s_add_u32 s36, s36, 0x100000
	s_addc_u32 s37, s37, 0
	s_mov_b32 m0, s40
	v_lshl_add_u64 v[226:227], s[36:37], 0, v[130:131]
	ds_read_b128 v[188:191], v152 offset:32768
	ds_read_b128 v[192:195], v152 offset:33792
	ds_read_b128 v[196:199], v152 offset:34816
	ds_read_b128 v[200:203], v152 offset:35840
	ds_read_b128 v[204:207], v152 offset:36864
	ds_read_b128 v[208:211], v152 offset:37888
	ds_read_b128 v[212:215], v152 offset:38912
	ds_read_b128 v[216:219], v152 offset:39936
	s_mov_b32 m0, s29
	s_nop 0
	global_load_lds_dwordx4 v[222:223], off
	s_mov_b32 m0, s39
	s_nop 0
	global_load_lds_dwordx4 v[224:225], off
	s_mov_b32 m0, s40
	s_nop 0
	global_load_lds_dwordx4 v[226:227], off
	v_lshl_add_u64 v[226:227], s[36:37], 0, v[134:135]
	s_mov_b32 m0, s41
	s_nop 0
	global_load_lds_dwordx4 v[226:227], off
	s_waitcnt vmcnt(8)
	s_waitcnt lgkmcnt(0)
	s_barrier
	s_setprio 1
	s_waitcnt lgkmcnt(0)
	v_mfma_f32_16x16x32_bf16 v[126:129], v[154:157], v[188:191], v[126:129]
	v_mfma_f32_16x16x32_bf16 v[122:125], v[164:167], v[188:191], v[122:125]
	v_mfma_f32_16x16x32_bf16 v[118:121], v[154:157], v[196:199], v[118:121]
	v_mfma_f32_16x16x32_bf16 v[110:113], v[164:167], v[196:199], v[110:113]
	v_mfma_f32_16x16x32_bf16 v[102:105], v[154:157], v[204:207], v[102:105]
	v_mfma_f32_16x16x32_bf16 v[94:97], v[164:167], v[204:207], v[94:97]
	v_mfma_f32_16x16x32_bf16 v[82:85], v[154:157], v[212:215], v[82:85]
	v_mfma_f32_16x16x32_bf16 v[74:77], v[164:167], v[212:215], v[74:77]
	v_mfma_f32_16x16x32_bf16 v[126:129], v[158:161], v[192:195], v[126:129]
	v_mfma_f32_16x16x32_bf16 v[122:125], v[168:171], v[192:195], v[122:125]
	v_mfma_f32_16x16x32_bf16 v[118:121], v[158:161], v[200:203], v[118:121]
	v_mfma_f32_16x16x32_bf16 v[110:113], v[168:171], v[200:203], v[110:113]
	v_mfma_f32_16x16x32_bf16 v[102:105], v[158:161], v[208:211], v[102:105]
	v_mfma_f32_16x16x32_bf16 v[94:97], v[168:171], v[208:211], v[94:97]
	v_mfma_f32_16x16x32_bf16 v[82:85], v[158:161], v[216:219], v[82:85]
	v_mfma_f32_16x16x32_bf16 v[74:77], v[168:171], v[216:219], v[74:77]
	s_setprio 0
	s_setprio 1
	v_mfma_f32_16x16x32_bf16 v[114:117], v[172:175], v[188:191], v[114:117]
	v_mfma_f32_16x16x32_bf16 v[106:109], v[180:183], v[188:191], v[106:109]
	v_mfma_f32_16x16x32_bf16 v[98:101], v[172:175], v[196:199], v[98:101]
	v_mfma_f32_16x16x32_bf16 v[90:93], v[180:183], v[196:199], v[90:93]
	v_mfma_f32_16x16x32_bf16 v[86:89], v[172:175], v[204:207], v[86:89]
	v_mfma_f32_16x16x32_bf16 v[78:81], v[180:183], v[204:207], v[78:81]
	v_mfma_f32_16x16x32_bf16 v[70:73], v[172:175], v[212:215], v[70:73]
	v_mfma_f32_16x16x32_bf16 v[66:69], v[180:183], v[212:215], v[66:69]
	v_mfma_f32_16x16x32_bf16 v[114:117], v[176:179], v[192:195], v[114:117]
	v_mfma_f32_16x16x32_bf16 v[106:109], v[184:187], v[192:195], v[106:109]
	v_mfma_f32_16x16x32_bf16 v[98:101], v[176:179], v[200:203], v[98:101]
	v_mfma_f32_16x16x32_bf16 v[90:93], v[184:187], v[200:203], v[90:93]
	v_mfma_f32_16x16x32_bf16 v[86:89], v[176:179], v[208:211], v[86:89]
	v_mfma_f32_16x16x32_bf16 v[78:81], v[184:187], v[208:211], v[78:81]
	v_mfma_f32_16x16x32_bf16 v[70:73], v[176:179], v[216:219], v[70:73]
	v_mfma_f32_16x16x32_bf16 v[66:69], v[184:187], v[216:219], v[66:69]
	s_setprio 0
	s_barrier
	s_add_i32 s36, s58, s38
	v_lshl_add_u64 v[146:147], v[146:147], 0, s[10:11]
	s_mov_b32 m0, s36
	ds_read_b128 v[188:191], v152 offset:49152
	ds_read_b128 v[192:195], v152 offset:50176
	ds_read_b128 v[196:199], v152 offset:51200
	ds_read_b128 v[200:203], v152 offset:52224
	ds_read_b128 v[204:207], v152 offset:53248
	ds_read_b128 v[208:211], v152 offset:54272
	ds_read_b128 v[212:215], v152 offset:55296
	ds_read_b128 v[216:219], v152 offset:56320
	global_load_lds_dwordx4 v[146:147], off
	s_add_i32 m0, s36, 0x2000
	s_add_u32 s34, s34, 0x100080
	v_lshl_add_u64 v[146:147], v[220:221], 0, s[10:11]
	s_addc_u32 s35, s35, 0
	s_add_i32 s36, s59, s38
	global_load_lds_dwordx4 v[146:147], off
	v_lshl_add_u64 v[146:147], s[34:35], 0, v[132:133]
	s_mov_b32 m0, s36
	s_nop 0
	global_load_lds_dwordx4 v[146:147], off
	v_lshl_add_u64 v[146:147], s[34:35], 0, v[136:137]
	s_add_i32 m0, s36, 0x2000
	s_nop 0
	global_load_lds_dwordx4 v[146:147], off
	v_lshl_add_u64 v[222:223], v[222:223], 0, s[10:11]
	v_lshl_add_u64 v[224:225], v[224:225], 0, s[10:11]
	s_waitcnt vmcnt(6)
	s_waitcnt lgkmcnt(0)
	s_barrier
	s_setprio 1
	s_waitcnt lgkmcnt(0)
	v_mfma_f32_16x16x32_bf16 v[62:65], v[154:157], v[188:191], v[62:65]
	v_mfma_f32_16x16x32_bf16 v[58:61], v[164:167], v[188:191], v[58:61]
	v_mfma_f32_16x16x32_bf16 v[54:57], v[154:157], v[196:199], v[54:57]
	v_mfma_f32_16x16x32_bf16 v[46:49], v[164:167], v[196:199], v[46:49]
	v_mfma_f32_16x16x32_bf16 v[38:41], v[154:157], v[204:207], v[38:41]
	v_mfma_f32_16x16x32_bf16 v[30:33], v[164:167], v[204:207], v[30:33]
	v_mfma_f32_16x16x32_bf16 v[22:25], v[154:157], v[212:215], v[22:25]
	v_mfma_f32_16x16x32_bf16 v[14:17], v[164:167], v[212:215], v[14:17]
	v_mfma_f32_16x16x32_bf16 v[62:65], v[158:161], v[192:195], v[62:65]
	v_mfma_f32_16x16x32_bf16 v[58:61], v[168:171], v[192:195], v[58:61]
	v_mfma_f32_16x16x32_bf16 v[54:57], v[158:161], v[200:203], v[54:57]
	v_mfma_f32_16x16x32_bf16 v[46:49], v[168:171], v[200:203], v[46:49]
	v_mfma_f32_16x16x32_bf16 v[38:41], v[158:161], v[208:211], v[38:41]
	v_mfma_f32_16x16x32_bf16 v[30:33], v[168:171], v[208:211], v[30:33]
	v_mfma_f32_16x16x32_bf16 v[22:25], v[158:161], v[216:219], v[22:25]
	v_mfma_f32_16x16x32_bf16 v[14:17], v[168:171], v[216:219], v[14:17]
	s_setprio 0
	s_setprio 1
	v_mfma_f32_16x16x32_bf16 v[50:53], v[172:175], v[188:191], v[50:53]
	v_mfma_f32_16x16x32_bf16 v[42:45], v[180:183], v[188:191], v[42:45]
	v_mfma_f32_16x16x32_bf16 v[34:37], v[172:175], v[196:199], v[34:37]
	v_mfma_f32_16x16x32_bf16 v[26:29], v[180:183], v[196:199], v[26:29]
	v_mfma_f32_16x16x32_bf16 v[18:21], v[172:175], v[204:207], v[18:21]
	v_mfma_f32_16x16x32_bf16 v[10:13], v[180:183], v[204:207], v[10:13]
	v_mfma_f32_16x16x32_bf16 v[6:9], v[172:175], v[212:215], v[6:9]
	v_mfma_f32_16x16x32_bf16 v[2:5], v[180:183], v[212:215], v[2:5]
	v_mfma_f32_16x16x32_bf16 v[50:53], v[176:179], v[192:195], v[50:53]
	v_mfma_f32_16x16x32_bf16 v[42:45], v[184:187], v[192:195], v[42:45]
	v_mfma_f32_16x16x32_bf16 v[34:37], v[176:179], v[200:203], v[34:37]
	v_mfma_f32_16x16x32_bf16 v[26:29], v[184:187], v[200:203], v[26:29]
	v_mfma_f32_16x16x32_bf16 v[18:21], v[176:179], v[208:211], v[18:21]
	v_mfma_f32_16x16x32_bf16 v[10:13], v[184:187], v[208:211], v[10:13]
	v_mfma_f32_16x16x32_bf16 v[6:9], v[176:179], v[216:219], v[6:9]
	v_mfma_f32_16x16x32_bf16 v[2:5], v[184:187], v[216:219], v[2:5]
	s_setprio 0
	s_barrier
	s_add_i32 s57, s57, 2
	s_mov_b32 s32, 1
	s_add_u32 s30, s30, 0x100
	s_addc_u32 s31, s31, 0
	s_add_u32 s55, s55, 0x100
	s_addc_u32 s56, s56, 0
	s_cmp_gt_u32 s57, 61
	s_cbranch_scc0 .LBB0_1571
	s_and_b64 vcc, exec, s[12:13]
	s_cbranch_vccz .LBB0_1574
	s_barrier

.LBB0_1689:
	s_lshl_b32 s8, s8, 5
	s_and_b32 s14, s8, 0x60
	s_mov_b64 s[8:9], 0x80
	s_add_i32 m0, s23, 0x18000
	v_lshl_add_u64 v[8:9], v[8:9], 0, s[8:9]
	s_lshl_b32 s7, s5, 13
	s_lshl_b32 s12, s14, 7
	s_waitcnt vmcnt(2)
	s_barrier
	global_load_lds_dwordx4 v[8:9], off
	v_lshl_add_u64 v[6:7], v[6:7], 0, s[8:9]
	s_add_i32 m0, s23, 0x1a000
	s_add_i32 s38, s23, 0x8000
	s_add_i32 s39, s23, 0xa000
	global_load_lds_dwordx4 v[6:7], off
	v_lshl_add_u64 v[2:3], v[2:3], 0, s[8:9]
	s_mov_b32 m0, s38
	s_add_u32 s10, s26, 0x100080
	global_load_lds_dwordx4 v[2:3], off
	v_lshl_add_u64 v[2:3], v[4:5], 0, s[8:9]
	s_mov_b32 m0, s39
	s_addc_u32 s11, s27, 0
	global_load_lds_dwordx4 v[2:3], off
	s_add_i32 m0, s23, 0x1c000
	v_lshl_add_u64 v[2:3], s[10:11], 0, v[132:133]
	global_load_lds_dwordx4 v[2:3], off
	v_lshl_add_u64 v[2:3], s[10:11], 0, v[136:137]
	s_add_i32 m0, s23, 0x1e000
	v_lshlrev_b32_e32 v4, 2, v0
	global_load_lds_dwordx4 v[2:3], off
	v_and_b32_e32 v2, 15, v0
	v_lshl_or_b32 v1, s5, 6, v2
	v_lshlrev_b32_e32 v3, 1, v13
	v_lshlrev_b32_e32 v5, 6, v0
	s_movk_i32 s5, 0x3c0
	v_lshl_or_b32 v2, v2, 6, v3
	v_and_b32_e32 v4, 32, v4
	v_and_or_b32 v3, v5, s5, v3
	v_bitop3_b32 v151, s12, v3, v4 bitop3:0xf6
	v_lshlrev_b32_e32 v3, 10, v0
	v_bitop3_b32 v2, v2, s7, v4 bitop3:0xde
	v_and_b32_e32 v3, 0x60000, v3
	v_lshlrev_b32_e32 v4, 13, v12
	s_cmpk_lt_u32 s4, 0x100
	v_or3_b32 v3, v10, v3, v4
	s_cselect_b64 s[10:11], -1, 0
	s_ashr_i32 s40, s96, 31
	s_ashr_i32 s41, s88, 31
	v_add_u32_e32 v138, v3, v11
	v_lshlrev_b32_e32 v3, 6, v14
	s_waitcnt vmcnt(6)
	s_cmp_lg_u64 s[94:95], 0
	v_and_b32_e32 v3, 0xe0000, v3
	s_cselect_b64 s[12:13], -1, 0
	v_or3_b32 v3, v10, v3, v4
	s_add_i32 s43, 0, 0x10000
	s_add_i32 s44, 0, 0x14000
	v_or_b32_e32 v153, s14, v13
	v_mov_b32_e32 v139, v133
	v_add_u32_e32 v140, v3, v11
	v_mov_b32_e32 v141, v133
	v_mov_b64_e32 v[142:143], 0xac0
	v_mov_b64_e32 v[144:145], 0xabf
	s_movk_i32 s42, 0x159
	v_add_u32_e32 v154, s43, v151
	v_add_u32_e32 v155, s44, v151
	v_add_u32_e32 v156, 0, v2
	s_mov_b32 s45, 0xac00
	s_barrier
	s_mov_b32 s32, 0
	s_branch .LBB0_1692

.LBB0_1695:
	ds_read_b128 v[146:149], v154
	ds_read_b128 v[158:161], v154 offset:1024
	ds_read_b128 v[164:167], v154 offset:2048
	ds_read_b128 v[168:171], v154 offset:3072
	ds_read_b128 v[172:175], v155
	ds_read_b128 v[176:179], v155 offset:1024
	ds_read_b128 v[180:183], v155 offset:2048
	ds_read_b128 v[184:187], v155 offset:3072
	s_add_u32 s26, s24, 0xfff00080
	s_addc_u32 s27, s25, -1
	s_cmp_eq_u32 s49, 60
	s_cselect_b32 s29, s7, s27
	s_cselect_b32 s28, s17, s26
	s_cselect_b32 s27, s15, s48
	s_cselect_b32 s26, s46, s47
	v_lshl_add_u64 v[220:221], s[24:25], 0, v[138:139]
	s_add_i32 m0, s23, 0xc000
	ds_read_b128 v[188:191], v156
	ds_read_b128 v[192:195], v156 offset:1024
	ds_read_b128 v[196:199], v156 offset:2048
	ds_read_b128 v[200:203], v156 offset:3072
	ds_read_b128 v[204:207], v156 offset:4096
	ds_read_b128 v[208:211], v156 offset:5120
	ds_read_b128 v[212:215], v156 offset:6144
	ds_read_b128 v[216:219], v156 offset:7168
	s_cmp_lg_u32 s32, 0
	s_cbranch_scc0 .Lrebal_skip_1695
	s_mov_b32 m0, s38
	s_nop 0
	global_load_lds_dwordx4 v[224:225], off
	s_mov_b32 m0, s39
	s_nop 0
	global_load_lds_dwordx4 v[226:227], off
.Lrebal_skip_1695:
	s_add_i32 m0, s23, 0xc000
	s_nop 0
	global_load_lds_dwordx4 v[220:221], off
	v_lshl_add_u64 v[220:221], s[24:25], 0, v[140:141]
	s_add_i32 m0, s23, 0xe000
	s_nop 0
	global_load_lds_dwordx4 v[220:221], off
	s_waitcnt vmcnt(8)
	s_waitcnt lgkmcnt(0)
	s_barrier
	s_setprio 1
	s_waitcnt lgkmcnt(0)
	v_mfma_f32_16x16x32_bf16 v[126:129], v[146:149], v[188:191], v[126:129]
	v_mfma_f32_16x16x32_bf16 v[122:125], v[164:167], v[188:191], v[122:125]
	v_mfma_f32_16x16x32_bf16 v[110:113], v[146:149], v[196:199], v[110:113]
	v_mfma_f32_16x16x32_bf16 v[106:109], v[164:167], v[196:199], v[106:109]
	v_mfma_f32_16x16x32_bf16 v[94:97], v[146:149], v[204:207], v[94:97]
	v_mfma_f32_16x16x32_bf16 v[90:93], v[164:167], v[204:207], v[90:93]
	v_mfma_f32_16x16x32_bf16 v[78:81], v[146:149], v[212:215], v[78:81]
	v_mfma_f32_16x16x32_bf16 v[74:77], v[164:167], v[212:215], v[74:77]
	v_mfma_f32_16x16x32_bf16 v[126:129], v[158:161], v[192:195], v[126:129]
	v_mfma_f32_16x16x32_bf16 v[122:125], v[168:171], v[192:195], v[122:125]
	v_mfma_f32_16x16x32_bf16 v[110:113], v[158:161], v[200:203], v[110:113]
	v_mfma_f32_16x16x32_bf16 v[106:109], v[168:171], v[200:203], v[106:109]
	v_mfma_f32_16x16x32_bf16 v[94:97], v[158:161], v[208:211], v[94:97]
	v_mfma_f32_16x16x32_bf16 v[90:93], v[168:171], v[208:211], v[90:93]
	v_mfma_f32_16x16x32_bf16 v[78:81], v[158:161], v[216:219], v[78:81]
	v_mfma_f32_16x16x32_bf16 v[74:77], v[168:171], v[216:219], v[74:77]
	s_setprio 0
	s_setprio 1
	v_mfma_f32_16x16x32_bf16 v[118:121], v[172:175], v[188:191], v[118:121]
	v_mfma_f32_16x16x32_bf16 v[114:117], v[180:183], v[188:191], v[114:117]
	v_mfma_f32_16x16x32_bf16 v[102:105], v[172:175], v[196:199], v[102:105]
	v_mfma_f32_16x16x32_bf16 v[98:101], v[180:183], v[196:199], v[98:101]
	v_mfma_f32_16x16x32_bf16 v[86:89], v[172:175], v[204:207], v[86:89]
	v_mfma_f32_16x16x32_bf16 v[82:85], v[180:183], v[204:207], v[82:85]
	v_mfma_f32_16x16x32_bf16 v[70:73], v[172:175], v[212:215], v[70:73]
	v_mfma_f32_16x16x32_bf16 v[66:69], v[180:183], v[212:215], v[66:69]
	v_mfma_f32_16x16x32_bf16 v[118:121], v[176:179], v[192:195], v[118:121]
	v_mfma_f32_16x16x32_bf16 v[114:117], v[184:187], v[192:195], v[114:117]
	v_mfma_f32_16x16x32_bf16 v[102:105], v[176:179], v[200:203], v[102:105]
	v_mfma_f32_16x16x32_bf16 v[98:101], v[184:187], v[200:203], v[98:101]
	v_mfma_f32_16x16x32_bf16 v[86:89], v[176:179], v[208:211], v[86:89]
	v_mfma_f32_16x16x32_bf16 v[82:85], v[184:187], v[208:211], v[82:85]
	v_mfma_f32_16x16x32_bf16 v[70:73], v[176:179], v[216:219], v[70:73]
	v_mfma_f32_16x16x32_bf16 v[66:69], v[184:187], v[216:219], v[66:69]
	s_setprio 0
	s_barrier
	s_add_i32 s50, s43, s33
	v_lshl_add_u64 v[220:221], s[26:27], 0, v[132:133]
	s_mov_b32 m0, s50
	ds_read_b128 v[188:191], v156 offset:16384
	ds_read_b128 v[192:195], v156 offset:17408
	ds_read_b128 v[196:199], v156 offset:18432
	ds_read_b128 v[200:203], v156 offset:19456
	ds_read_b128 v[204:207], v156 offset:20480
	ds_read_b128 v[208:211], v156 offset:21504
	ds_read_b128 v[212:215], v156 offset:22528
	ds_read_b128 v[216:219], v156 offset:23552
	global_load_lds_dwordx4 v[220:221], off
	s_add_i32 m0, s50, 0x2000
	s_add_u32 s50, s26, 0x100000
	v_lshl_add_u64 v[222:223], s[26:27], 0, v[136:137]
	s_addc_u32 s51, s27, 0
	s_add_i32 s52, s44, s33
	global_load_lds_dwordx4 v[222:223], off
	v_lshl_add_u64 v[224:225], s[50:51], 0, v[132:133]
	s_mov_b32 m0, s52
	v_lshl_add_u64 v[226:227], s[28:29], 0, v[134:135]
	global_load_lds_dwordx4 v[224:225], off
	v_lshl_add_u64 v[224:225], s[50:51], 0, v[136:137]
	s_add_i32 m0, s52, 0x2000
	s_nop 0
	global_load_lds_dwordx4 v[224:225], off
	v_lshl_add_u64 v[224:225], s[28:29], 0, v[130:131]
	s_waitcnt vmcnt(6)
	s_waitcnt lgkmcnt(0)
	s_barrier
	s_setprio 1
	s_waitcnt lgkmcnt(0)
	v_mfma_f32_16x16x32_bf16 v[62:65], v[146:149], v[188:191], v[62:65]
	v_mfma_f32_16x16x32_bf16 v[58:61], v[164:167], v[188:191], v[58:61]
	v_mfma_f32_16x16x32_bf16 v[46:49], v[146:149], v[196:199], v[46:49]
	v_mfma_f32_16x16x32_bf16 v[42:45], v[164:167], v[196:199], v[42:45]
	v_mfma_f32_16x16x32_bf16 v[30:33], v[146:149], v[204:207], v[30:33]
	v_mfma_f32_16x16x32_bf16 v[26:29], v[164:167], v[204:207], v[26:29]
	v_mfma_f32_16x16x32_bf16 v[14:17], v[146:149], v[212:215], v[14:17]
	v_mfma_f32_16x16x32_bf16 v[10:13], v[164:167], v[212:215], v[10:13]
	v_mfma_f32_16x16x32_bf16 v[62:65], v[158:161], v[192:195], v[62:65]
	v_mfma_f32_16x16x32_bf16 v[58:61], v[168:171], v[192:195], v[58:61]
	v_mfma_f32_16x16x32_bf16 v[46:49], v[158:161], v[200:203], v[46:49]
	v_mfma_f32_16x16x32_bf16 v[42:45], v[168:171], v[200:203], v[42:45]
	v_mfma_f32_16x16x32_bf16 v[30:33], v[158:161], v[208:211], v[30:33]
	v_mfma_f32_16x16x32_bf16 v[26:29], v[168:171], v[208:211], v[26:29]
	v_mfma_f32_16x16x32_bf16 v[14:17], v[158:161], v[216:219], v[14:17]
	v_mfma_f32_16x16x32_bf16 v[10:13], v[168:171], v[216:219], v[10:13]
	s_setprio 0
	s_setprio 1
	v_mfma_f32_16x16x32_bf16 v[54:57], v[172:175], v[188:191], v[54:57]
	v_mfma_f32_16x16x32_bf16 v[50:53], v[180:183], v[188:191], v[50:53]
	v_mfma_f32_16x16x32_bf16 v[38:41], v[172:175], v[196:199], v[38:41]
	v_mfma_f32_16x16x32_bf16 v[34:37], v[180:183], v[196:199], v[34:37]
	v_mfma_f32_16x16x32_bf16 v[22:25], v[172:175], v[204:207], v[22:25]
	v_mfma_f32_16x16x32_bf16 v[18:21], v[180:183], v[204:207], v[18:21]
	v_mfma_f32_16x16x32_bf16 v[6:9], v[172:175], v[212:215], v[6:9]
	v_mfma_f32_16x16x32_bf16 v[2:5], v[180:183], v[212:215], v[2:5]
	v_mfma_f32_16x16x32_bf16 v[54:57], v[176:179], v[192:195], v[54:57]
	v_mfma_f32_16x16x32_bf16 v[50:53], v[184:187], v[192:195], v[50:53]
	v_mfma_f32_16x16x32_bf16 v[38:41], v[176:179], v[200:203], v[38:41]
	v_mfma_f32_16x16x32_bf16 v[34:37], v[184:187], v[200:203], v[34:37]
	v_mfma_f32_16x16x32_bf16 v[22:25], v[176:179], v[208:211], v[22:25]
	v_mfma_f32_16x16x32_bf16 v[18:21], v[184:187], v[208:211], v[18:21]
	v_mfma_f32_16x16x32_bf16 v[6:9], v[176:179], v[216:219], v[6:9]
	v_mfma_f32_16x16x32_bf16 v[2:5], v[184:187], v[216:219], v[2:5]
	s_setprio 0
	s_barrier
	s_add_i32 s50, 0, 0x18000
	v_add_u32_e32 v150, s50, v151
	s_add_i32 s51, 0, 0x1c000
	ds_read_b128 v[146:149], v150
	ds_read_b128 v[158:161], v150 offset:1024
	ds_read_b128 v[164:167], v150 offset:2048
	ds_read_b128 v[168:171], v150 offset:3072
	v_add_u32_e32 v150, s51, v151
	ds_read_b128 v[172:175], v150
	ds_read_b128 v[176:179], v150 offset:1024
	ds_read_b128 v[180:183], v150 offset:2048
	ds_read_b128 v[184:187], v150 offset:3072
	s_add_u32 s28, s28, 0x100000
	s_addc_u32 s29, s29, 0
	s_mov_b32 m0, s35
	v_lshl_add_u64 v[228:229], s[28:29], 0, v[130:131]
	ds_read_b128 v[188:191], v156 offset:32768
	ds_read_b128 v[192:195], v156 offset:33792
	ds_read_b128 v[196:199], v156 offset:34816
	ds_read_b128 v[200:203], v156 offset:35840
	ds_read_b128 v[204:207], v156 offset:36864
	ds_read_b128 v[208:211], v156 offset:37888
	ds_read_b128 v[212:215], v156 offset:38912
	ds_read_b128 v[216:219], v156 offset:39936
	s_mov_b32 m0, s23
	s_nop 0
	global_load_lds_dwordx4 v[224:225], off
	s_mov_b32 m0, s34
	s_nop 0
	global_load_lds_dwordx4 v[226:227], off
	s_mov_b32 m0, s35
	s_nop 0
	global_load_lds_dwordx4 v[228:229], off
	v_lshl_add_u64 v[228:229], s[28:29], 0, v[134:135]
	s_mov_b32 m0, s36
	s_nop 0
	global_load_lds_dwordx4 v[228:229], off
	s_waitcnt vmcnt(8)
	s_waitcnt lgkmcnt(0)
	s_barrier
	s_setprio 1
	s_waitcnt lgkmcnt(0)
	v_mfma_f32_16x16x32_bf16 v[126:129], v[146:149], v[188:191], v[126:129]
	v_mfma_f32_16x16x32_bf16 v[122:125], v[164:167], v[188:191], v[122:125]
	v_mfma_f32_16x16x32_bf16 v[110:113], v[146:149], v[196:199], v[110:113]
	v_mfma_f32_16x16x32_bf16 v[106:109], v[164:167], v[196:199], v[106:109]
	v_mfma_f32_16x16x32_bf16 v[94:97], v[146:149], v[204:207], v[94:97]
	v_mfma_f32_16x16x32_bf16 v[90:93], v[164:167], v[204:207], v[90:93]
	v_mfma_f32_16x16x32_bf16 v[78:81], v[146:149], v[212:215], v[78:81]
	v_mfma_f32_16x16x32_bf16 v[74:77], v[164:167], v[212:215], v[74:77]
	v_mfma_f32_16x16x32_bf16 v[126:129], v[158:161], v[192:195], v[126:129]
	v_mfma_f32_16x16x32_bf16 v[122:125], v[168:171], v[192:195], v[122:125]
	v_mfma_f32_16x16x32_bf16 v[110:113], v[158:161], v[200:203], v[110:113]
	v_mfma_f32_16x16x32_bf16 v[106:109], v[168:171], v[200:203], v[106:109]
	v_mfma_f32_16x16x32_bf16 v[94:97], v[158:161], v[208:211], v[94:97]
	v_mfma_f32_16x16x32_bf16 v[90:93], v[168:171], v[208:211], v[90:93]
	v_mfma_f32_16x16x32_bf16 v[78:81], v[158:161], v[216:219], v[78:81]
	v_mfma_f32_16x16x32_bf16 v[74:77], v[168:171], v[216:219], v[74:77]
	s_setprio 0
	s_setprio 1
	v_mfma_f32_16x16x32_bf16 v[118:121], v[172:175], v[188:191], v[118:121]
	v_mfma_f32_16x16x32_bf16 v[114:117], v[180:183], v[188:191], v[114:117]
	v_mfma_f32_16x16x32_bf16 v[102:105], v[172:175], v[196:199], v[102:105]
	v_mfma_f32_16x16x32_bf16 v[98:101], v[180:183], v[196:199], v[98:101]
	v_mfma_f32_16x16x32_bf16 v[86:89], v[172:175], v[204:207], v[86:89]
	v_mfma_f32_16x16x32_bf16 v[82:85], v[180:183], v[204:207], v[82:85]
	v_mfma_f32_16x16x32_bf16 v[70:73], v[172:175], v[212:215], v[70:73]
	v_mfma_f32_16x16x32_bf16 v[66:69], v[180:183], v[212:215], v[66:69]
	v_mfma_f32_16x16x32_bf16 v[118:121], v[176:179], v[192:195], v[118:121]
	v_mfma_f32_16x16x32_bf16 v[114:117], v[184:187], v[192:195], v[114:117]
	v_mfma_f32_16x16x32_bf16 v[102:105], v[176:179], v[200:203], v[102:105]
	v_mfma_f32_16x16x32_bf16 v[98:101], v[184:187], v[200:203], v[98:101]
	v_mfma_f32_16x16x32_bf16 v[86:89], v[176:179], v[208:211], v[86:89]
	v_mfma_f32_16x16x32_bf16 v[82:85], v[184:187], v[208:211], v[82:85]
	v_mfma_f32_16x16x32_bf16 v[70:73], v[176:179], v[216:219], v[70:73]
	v_mfma_f32_16x16x32_bf16 v[66:69], v[184:187], v[216:219], v[66:69]
	s_setprio 0
	s_barrier
	s_add_i32 s28, s50, s33
	v_lshl_add_u64 v[220:221], v[220:221], 0, s[8:9]
	s_mov_b32 m0, s28
	ds_read_b128 v[188:191], v156 offset:49152
	ds_read_b128 v[192:195], v156 offset:50176
	ds_read_b128 v[196:199], v156 offset:51200
	ds_read_b128 v[200:203], v156 offset:52224
	ds_read_b128 v[204:207], v156 offset:53248
	ds_read_b128 v[208:211], v156 offset:54272
	ds_read_b128 v[212:215], v156 offset:55296
	ds_read_b128 v[216:219], v156 offset:56320
	global_load_lds_dwordx4 v[220:221], off
	s_add_i32 m0, s28, 0x2000
	s_add_u32 s26, s26, 0x100080
	v_lshl_add_u64 v[220:221], v[222:223], 0, s[8:9]
	s_addc_u32 s27, s27, 0
	s_add_i32 s28, s51, s33
	global_load_lds_dwordx4 v[220:221], off
	v_lshl_add_u64 v[220:221], s[26:27], 0, v[132:133]
	s_mov_b32 m0, s28
	s_nop 0
	global_load_lds_dwordx4 v[220:221], off
	v_lshl_add_u64 v[220:221], s[26:27], 0, v[136:137]
	s_add_i32 m0, s28, 0x2000
	s_nop 0
	global_load_lds_dwordx4 v[220:221], off
	v_lshl_add_u64 v[224:225], v[224:225], 0, s[8:9]
	v_lshl_add_u64 v[226:227], v[226:227], 0, s[8:9]
	s_waitcnt vmcnt(6)
	s_waitcnt lgkmcnt(0)
	s_barrier
	s_setprio 1
	s_waitcnt lgkmcnt(0)
	v_mfma_f32_16x16x32_bf16 v[62:65], v[146:149], v[188:191], v[62:65]
	v_mfma_f32_16x16x32_bf16 v[58:61], v[164:167], v[188:191], v[58:61]
	v_mfma_f32_16x16x32_bf16 v[46:49], v[146:149], v[196:199], v[46:49]
	v_mfma_f32_16x16x32_bf16 v[42:45], v[164:167], v[196:199], v[42:45]
	v_mfma_f32_16x16x32_bf16 v[30:33], v[146:149], v[204:207], v[30:33]
	v_mfma_f32_16x16x32_bf16 v[26:29], v[164:167], v[204:207], v[26:29]
	v_mfma_f32_16x16x32_bf16 v[14:17], v[146:149], v[212:215], v[14:17]
	v_mfma_f32_16x16x32_bf16 v[10:13], v[164:167], v[212:215], v[10:13]
	v_mfma_f32_16x16x32_bf16 v[62:65], v[158:161], v[192:195], v[62:65]
	v_mfma_f32_16x16x32_bf16 v[58:61], v[168:171], v[192:195], v[58:61]
	v_mfma_f32_16x16x32_bf16 v[46:49], v[158:161], v[200:203], v[46:49]
	v_mfma_f32_16x16x32_bf16 v[42:45], v[168:171], v[200:203], v[42:45]
	v_mfma_f32_16x16x32_bf16 v[30:33], v[158:161], v[208:211], v[30:33]
	v_mfma_f32_16x16x32_bf16 v[26:29], v[168:171], v[208:211], v[26:29]
	v_mfma_f32_16x16x32_bf16 v[14:17], v[158:161], v[216:219], v[14:17]
	v_mfma_f32_16x16x32_bf16 v[10:13], v[168:171], v[216:219], v[10:13]
	s_setprio 0
	s_setprio 1
	v_mfma_f32_16x16x32_bf16 v[54:57], v[172:175], v[188:191], v[54:57]
	v_mfma_f32_16x16x32_bf16 v[50:53], v[180:183], v[188:191], v[50:53]
	v_mfma_f32_16x16x32_bf16 v[38:41], v[172:175], v[196:199], v[38:41]
	v_mfma_f32_16x16x32_bf16 v[34:37], v[180:183], v[196:199], v[34:37]
	v_mfma_f32_16x16x32_bf16 v[22:25], v[172:175], v[204:207], v[22:25]
	v_mfma_f32_16x16x32_bf16 v[18:21], v[180:183], v[204:207], v[18:21]
	v_mfma_f32_16x16x32_bf16 v[6:9], v[172:175], v[212:215], v[6:9]
	v_mfma_f32_16x16x32_bf16 v[2:5], v[180:183], v[212:215], v[2:5]
	v_mfma_f32_16x16x32_bf16 v[54:57], v[176:179], v[192:195], v[54:57]
	v_mfma_f32_16x16x32_bf16 v[50:53], v[184:187], v[192:195], v[50:53]
	v_mfma_f32_16x16x32_bf16 v[38:41], v[176:179], v[200:203], v[38:41]
	v_mfma_f32_16x16x32_bf16 v[34:37], v[184:187], v[200:203], v[34:37]
	v_mfma_f32_16x16x32_bf16 v[22:25], v[176:179], v[208:211], v[22:25]
	v_mfma_f32_16x16x32_bf16 v[18:21], v[184:187], v[208:211], v[18:21]
	v_mfma_f32_16x16x32_bf16 v[6:9], v[176:179], v[216:219], v[6:9]
	v_mfma_f32_16x16x32_bf16 v[2:5], v[184:187], v[216:219], v[2:5]
	s_setprio 0
	s_barrier
	s_add_i32 s49, s49, 2
	s_mov_b32 s32, 1
	s_add_u32 s24, s24, 0x100
	s_addc_u32 s25, s25, 0
	s_add_u32 s47, s47, 0x100
	s_addc_u32 s48, s48, 0
	s_cmp_gt_u32 s49, 61
	s_cbranch_scc0 .LBB0_1695
	s_and_b64 vcc, exec, s[10:11]
	s_cbranch_vccz .LBB0_1698
	s_barrier

.LBB0_1839:
	s_lshl_b32 s1, s1, 5
	s_mov_b64 s[8:9], 0x80
	s_and_b32 s1, s1, 0x60
	s_add_i32 m0, s33, 0x18000
	v_lshl_add_u64 v[8:9], v[8:9], 0, s[8:9]
	s_lshl_b32 s12, s0, 13
	s_lshl_b32 s13, s1, 7
	s_waitcnt vmcnt(2)
	s_barrier
	global_load_lds_dwordx4 v[8:9], off
	v_lshl_add_u64 v[6:7], v[6:7], 0, s[8:9]
	s_add_i32 m0, s33, 0x1a000
	s_add_i32 s38, s33, 0x8000
	s_add_i32 s39, s33, 0xa000
	global_load_lds_dwordx4 v[6:7], off
	v_lshl_add_u64 v[2:3], v[2:3], 0, s[8:9]
	s_mov_b32 m0, s38
	s_add_u32 s10, s24, 0x2b0080
	global_load_lds_dwordx4 v[2:3], off
	v_lshl_add_u64 v[2:3], v[4:5], 0, s[8:9]
	s_mov_b32 m0, s39
	s_addc_u32 s11, s25, 0
	global_load_lds_dwordx4 v[2:3], off
	s_add_i32 m0, s33, 0x1c000
	v_lshl_add_u64 v[2:3], s[10:11], 0, v[132:133]
	global_load_lds_dwordx4 v[2:3], off
	v_lshl_add_u64 v[2:3], s[10:11], 0, v[136:137]
	s_add_i32 m0, s33, 0x1e000
	v_lshlrev_b32_e32 v4, 2, v0
	global_load_lds_dwordx4 v[2:3], off
	v_and_b32_e32 v2, 15, v0
	v_lshl_or_b32 v1, s0, 6, v2
	v_lshlrev_b32_e32 v3, 1, v12
	v_lshlrev_b32_e32 v5, 6, v0
	s_movk_i32 s0, 0x3c0
	v_lshl_or_b32 v2, v2, 6, v3
	v_and_b32_e32 v4, 32, v4
	v_and_or_b32 v3, v5, s0, v3
	v_bitop3_b32 v148, s13, v3, v4 bitop3:0xf6
	s_waitcnt vmcnt(6)
	s_cmpk_lt_u32 s4, 0x100
	v_add_u16_e32 v3, v10, v11
	v_bitop3_b32 v2, v2, s12, v4 bitop3:0xde
	s_cselect_b64 s[10:11], -1, 0
	v_lshrrev_b16_e32 v3, 1, v3
	s_add_i32 s41, 0, 0x10000
	s_add_i32 s42, 0, 0x14000
	s_sext_i32_i8 s50, s5
	s_ashr_i32 s40, s96, 31
	v_or_b32_e32 v149, s1, v12
	v_add_lshl_u32 v138, v13, v3, 1
	v_mov_b32_e32 v139, v133
	v_add_lshl_u32 v140, v14, v3, 1
	v_mov_b32_e32 v141, v133
	v_mov_b64_e32 v[142:143], 0x200
	v_mov_b64_e32 v[144:145], 0x1ff
	v_add_u32_e32 v150, s41, v148
	v_add_u32_e32 v151, s42, v148
	v_add_u32_e32 v152, 0, v2
	s_mov_b64 s[12:13], 0x100000
	s_mov_b32 s43, 0x100000
	s_mov_b64 s[14:15], 0x120000
	s_mov_b32 s44, 0x120000
	s_mov_b64 s[16:17], 0x140000
	s_mov_b32 s45, 0x140000
	s_mov_b64 s[18:19], 0x160000
	s_mov_b32 s46, 0x160000
	s_barrier
	s_mov_b32 s32, 0
	s_branch .LBB0_1842

.LBB0_1853:
	ds_read_b128 v[154:157], v150
	ds_read_b128 v[158:161], v150 offset:1024
	ds_read_b128 v[164:167], v150 offset:2048
	ds_read_b128 v[168:171], v150 offset:3072
	ds_read_b128 v[172:175], v151
	ds_read_b128 v[176:179], v151 offset:1024
	ds_read_b128 v[180:183], v151 offset:2048
	ds_read_b128 v[184:187], v151 offset:3072
	s_add_u32 s24, s22, 0xffd50080
	s_addc_u32 s25, s23, -1
	s_cmpk_eq_i32 s53, 0xa8
	s_cselect_b32 s27, s1, s25
	s_cselect_b32 s26, s0, s24
	s_cselect_b32 s25, s21, s52
	s_cselect_b32 s24, s20, s51
	v_lshl_add_u64 v[146:147], s[22:23], 0, v[138:139]
	s_add_i32 m0, s33, 0xc000
	ds_read_b128 v[188:191], v152
	ds_read_b128 v[192:195], v152 offset:1024
	ds_read_b128 v[196:199], v152 offset:2048
	ds_read_b128 v[200:203], v152 offset:3072
	ds_read_b128 v[204:207], v152 offset:4096
	ds_read_b128 v[208:211], v152 offset:5120
	ds_read_b128 v[212:215], v152 offset:6144
	ds_read_b128 v[216:219], v152 offset:7168
	s_cmp_lg_u32 s32, 0
	s_cbranch_scc0 .Lrebal_skip_1853
	s_mov_b32 m0, s38
	s_nop 0
	global_load_lds_dwordx4 v[222:223], off
	s_mov_b32 m0, s39
	s_nop 0
	global_load_lds_dwordx4 v[224:225], off
.Lrebal_skip_1853:
	s_add_i32 m0, s33, 0xc000
	s_nop 0
	global_load_lds_dwordx4 v[146:147], off
	v_lshl_add_u64 v[146:147], s[22:23], 0, v[140:141]
	s_add_i32 m0, s33, 0xe000
	s_nop 0
	global_load_lds_dwordx4 v[146:147], off
	s_waitcnt vmcnt(8)
	s_waitcnt lgkmcnt(0)
	s_barrier
	s_setprio 1
	s_waitcnt lgkmcnt(0)
	v_mfma_f32_16x16x32_bf16 v[126:129], v[154:157], v[188:191], v[126:129]
	v_mfma_f32_16x16x32_bf16 v[122:125], v[164:167], v[188:191], v[122:125]
	v_mfma_f32_16x16x32_bf16 v[118:121], v[154:157], v[196:199], v[118:121]
	v_mfma_f32_16x16x32_bf16 v[110:113], v[164:167], v[196:199], v[110:113]
	v_mfma_f32_16x16x32_bf16 v[102:105], v[154:157], v[204:207], v[102:105]
	v_mfma_f32_16x16x32_bf16 v[94:97], v[164:167], v[204:207], v[94:97]
	v_mfma_f32_16x16x32_bf16 v[82:85], v[154:157], v[212:215], v[82:85]
	v_mfma_f32_16x16x32_bf16 v[74:77], v[164:167], v[212:215], v[74:77]
	v_mfma_f32_16x16x32_bf16 v[126:129], v[158:161], v[192:195], v[126:129]
	v_mfma_f32_16x16x32_bf16 v[122:125], v[168:171], v[192:195], v[122:125]
	v_mfma_f32_16x16x32_bf16 v[118:121], v[158:161], v[200:203], v[118:121]
	v_mfma_f32_16x16x32_bf16 v[110:113], v[168:171], v[200:203], v[110:113]
	v_mfma_f32_16x16x32_bf16 v[102:105], v[158:161], v[208:211], v[102:105]
	v_mfma_f32_16x16x32_bf16 v[94:97], v[168:171], v[208:211], v[94:97]
	v_mfma_f32_16x16x32_bf16 v[82:85], v[158:161], v[216:219], v[82:85]
	v_mfma_f32_16x16x32_bf16 v[74:77], v[168:171], v[216:219], v[74:77]
	s_setprio 0
	s_setprio 1
	v_mfma_f32_16x16x32_bf16 v[114:117], v[172:175], v[188:191], v[114:117]
	v_mfma_f32_16x16x32_bf16 v[106:109], v[180:183], v[188:191], v[106:109]
	v_mfma_f32_16x16x32_bf16 v[98:101], v[172:175], v[196:199], v[98:101]
	v_mfma_f32_16x16x32_bf16 v[90:93], v[180:183], v[196:199], v[90:93]
	v_mfma_f32_16x16x32_bf16 v[86:89], v[172:175], v[204:207], v[86:89]
	v_mfma_f32_16x16x32_bf16 v[78:81], v[180:183], v[204:207], v[78:81]
	v_mfma_f32_16x16x32_bf16 v[70:73], v[172:175], v[212:215], v[70:73]
	v_mfma_f32_16x16x32_bf16 v[66:69], v[180:183], v[212:215], v[66:69]
	v_mfma_f32_16x16x32_bf16 v[114:117], v[176:179], v[192:195], v[114:117]
	v_mfma_f32_16x16x32_bf16 v[106:109], v[184:187], v[192:195], v[106:109]
	v_mfma_f32_16x16x32_bf16 v[98:101], v[176:179], v[200:203], v[98:101]
	v_mfma_f32_16x16x32_bf16 v[90:93], v[184:187], v[200:203], v[90:93]
	v_mfma_f32_16x16x32_bf16 v[86:89], v[176:179], v[208:211], v[86:89]
	v_mfma_f32_16x16x32_bf16 v[78:81], v[184:187], v[208:211], v[78:81]
	v_mfma_f32_16x16x32_bf16 v[70:73], v[176:179], v[216:219], v[70:73]
	v_mfma_f32_16x16x32_bf16 v[66:69], v[184:187], v[216:219], v[66:69]
	s_setprio 0
	s_barrier
	s_add_i32 s54, s41, s31
	v_lshl_add_u64 v[146:147], s[24:25], 0, v[132:133]
	s_mov_b32 m0, s54
	ds_read_b128 v[188:191], v152 offset:16384
	ds_read_b128 v[192:195], v152 offset:17408
	ds_read_b128 v[196:199], v152 offset:18432
	ds_read_b128 v[200:203], v152 offset:19456
	ds_read_b128 v[204:207], v152 offset:20480
	ds_read_b128 v[208:211], v152 offset:21504
	ds_read_b128 v[212:215], v152 offset:22528
	ds_read_b128 v[216:219], v152 offset:23552
	global_load_lds_dwordx4 v[146:147], off
	s_add_i32 m0, s54, 0x2000
	s_add_u32 s54, s24, 0x2b0000
	v_lshl_add_u64 v[220:221], s[24:25], 0, v[136:137]
	s_addc_u32 s55, s25, 0
	s_add_i32 s56, s42, s31
	global_load_lds_dwordx4 v[220:221], off
	v_lshl_add_u64 v[222:223], s[54:55], 0, v[132:133]
	s_mov_b32 m0, s56
	v_lshl_add_u64 v[224:225], s[26:27], 0, v[134:135]
	global_load_lds_dwordx4 v[222:223], off
	v_lshl_add_u64 v[222:223], s[54:55], 0, v[136:137]
	s_add_i32 m0, s56, 0x2000
	s_nop 0
	global_load_lds_dwordx4 v[222:223], off
	v_lshl_add_u64 v[222:223], s[26:27], 0, v[130:131]
	s_waitcnt vmcnt(6)
	s_waitcnt lgkmcnt(0)
	s_barrier
	s_setprio 1
	s_waitcnt lgkmcnt(0)
	v_mfma_f32_16x16x32_bf16 v[62:65], v[154:157], v[188:191], v[62:65]
	v_mfma_f32_16x16x32_bf16 v[58:61], v[164:167], v[188:191], v[58:61]
	v_mfma_f32_16x16x32_bf16 v[54:57], v[154:157], v[196:199], v[54:57]
	v_mfma_f32_16x16x32_bf16 v[46:49], v[164:167], v[196:199], v[46:49]
	v_mfma_f32_16x16x32_bf16 v[38:41], v[154:157], v[204:207], v[38:41]
	v_mfma_f32_16x16x32_bf16 v[30:33], v[164:167], v[204:207], v[30:33]
	v_mfma_f32_16x16x32_bf16 v[22:25], v[154:157], v[212:215], v[22:25]
	v_mfma_f32_16x16x32_bf16 v[14:17], v[164:167], v[212:215], v[14:17]
	v_mfma_f32_16x16x32_bf16 v[62:65], v[158:161], v[192:195], v[62:65]
	v_mfma_f32_16x16x32_bf16 v[58:61], v[168:171], v[192:195], v[58:61]
	v_mfma_f32_16x16x32_bf16 v[54:57], v[158:161], v[200:203], v[54:57]
	v_mfma_f32_16x16x32_bf16 v[46:49], v[168:171], v[200:203], v[46:49]
	v_mfma_f32_16x16x32_bf16 v[38:41], v[158:161], v[208:211], v[38:41]
	v_mfma_f32_16x16x32_bf16 v[30:33], v[168:171], v[208:211], v[30:33]
	v_mfma_f32_16x16x32_bf16 v[22:25], v[158:161], v[216:219], v[22:25]
	v_mfma_f32_16x16x32_bf16 v[14:17], v[168:171], v[216:219], v[14:17]
	s_setprio 0
	s_setprio 1
	v_mfma_f32_16x16x32_bf16 v[50:53], v[172:175], v[188:191], v[50:53]
	v_mfma_f32_16x16x32_bf16 v[42:45], v[180:183], v[188:191], v[42:45]
	v_mfma_f32_16x16x32_bf16 v[34:37], v[172:175], v[196:199], v[34:37]
	v_mfma_f32_16x16x32_bf16 v[26:29], v[180:183], v[196:199], v[26:29]
	v_mfma_f32_16x16x32_bf16 v[18:21], v[172:175], v[204:207], v[18:21]
	v_mfma_f32_16x16x32_bf16 v[10:13], v[180:183], v[204:207], v[10:13]
	v_mfma_f32_16x16x32_bf16 v[6:9], v[172:175], v[212:215], v[6:9]
	v_mfma_f32_16x16x32_bf16 v[2:5], v[180:183], v[212:215], v[2:5]
	v_mfma_f32_16x16x32_bf16 v[50:53], v[176:179], v[192:195], v[50:53]
	v_mfma_f32_16x16x32_bf16 v[42:45], v[184:187], v[192:195], v[42:45]
	v_mfma_f32_16x16x32_bf16 v[34:37], v[176:179], v[200:203], v[34:37]
	v_mfma_f32_16x16x32_bf16 v[26:29], v[184:187], v[200:203], v[26:29]
	v_mfma_f32_16x16x32_bf16 v[18:21], v[176:179], v[208:211], v[18:21]
	v_mfma_f32_16x16x32_bf16 v[10:13], v[184:187], v[208:211], v[10:13]
	v_mfma_f32_16x16x32_bf16 v[6:9], v[176:179], v[216:219], v[6:9]
	v_mfma_f32_16x16x32_bf16 v[2:5], v[184:187], v[216:219], v[2:5]
	s_setprio 0
	s_barrier
	s_add_i32 s54, 0, 0x18000
	v_add_u32_e32 v153, s54, v148
	s_add_i32 s55, 0, 0x1c000
	ds_read_b128 v[154:157], v153
	ds_read_b128 v[158:161], v153 offset:1024
	ds_read_b128 v[164:167], v153 offset:2048
	ds_read_b128 v[168:171], v153 offset:3072
	v_add_u32_e32 v153, s55, v148
	ds_read_b128 v[172:175], v153
	ds_read_b128 v[176:179], v153 offset:1024
	ds_read_b128 v[180:183], v153 offset:2048
	ds_read_b128 v[184:187], v153 offset:3072
	s_add_u32 s26, s26, 0x2b0000
	s_addc_u32 s27, s27, 0
	s_mov_b32 m0, s35
	v_lshl_add_u64 v[226:227], s[26:27], 0, v[130:131]
	ds_read_b128 v[188:191], v152 offset:32768
	ds_read_b128 v[192:195], v152 offset:33792
	ds_read_b128 v[196:199], v152 offset:34816
	ds_read_b128 v[200:203], v152 offset:35840
	ds_read_b128 v[204:207], v152 offset:36864
	ds_read_b128 v[208:211], v152 offset:37888
	ds_read_b128 v[212:215], v152 offset:38912
	ds_read_b128 v[216:219], v152 offset:39936
	s_mov_b32 m0, s33
	s_nop 0
	global_load_lds_dwordx4 v[222:223], off
	s_mov_b32 m0, s34
	s_nop 0
	global_load_lds_dwordx4 v[224:225], off
	s_mov_b32 m0, s35
	s_nop 0
	global_load_lds_dwordx4 v[226:227], off
	v_lshl_add_u64 v[226:227], s[26:27], 0, v[134:135]
	s_mov_b32 m0, s36
	s_nop 0
	global_load_lds_dwordx4 v[226:227], off
	s_waitcnt vmcnt(8)
	s_waitcnt lgkmcnt(0)
	s_barrier
	s_setprio 1
	s_waitcnt lgkmcnt(0)
	v_mfma_f32_16x16x32_bf16 v[126:129], v[154:157], v[188:191], v[126:129]
	v_mfma_f32_16x16x32_bf16 v[122:125], v[164:167], v[188:191], v[122:125]
	v_mfma_f32_16x16x32_bf16 v[118:121], v[154:157], v[196:199], v[118:121]
	v_mfma_f32_16x16x32_bf16 v[110:113], v[164:167], v[196:199], v[110:113]
	v_mfma_f32_16x16x32_bf16 v[102:105], v[154:157], v[204:207], v[102:105]
	v_mfma_f32_16x16x32_bf16 v[94:97], v[164:167], v[204:207], v[94:97]
	v_mfma_f32_16x16x32_bf16 v[82:85], v[154:157], v[212:215], v[82:85]
	v_mfma_f32_16x16x32_bf16 v[74:77], v[164:167], v[212:215], v[74:77]
	v_mfma_f32_16x16x32_bf16 v[126:129], v[158:161], v[192:195], v[126:129]
	v_mfma_f32_16x16x32_bf16 v[122:125], v[168:171], v[192:195], v[122:125]
	v_mfma_f32_16x16x32_bf16 v[118:121], v[158:161], v[200:203], v[118:121]
	v_mfma_f32_16x16x32_bf16 v[110:113], v[168:171], v[200:203], v[110:113]
	v_mfma_f32_16x16x32_bf16 v[102:105], v[158:161], v[208:211], v[102:105]
	v_mfma_f32_16x16x32_bf16 v[94:97], v[168:171], v[208:211], v[94:97]
	v_mfma_f32_16x16x32_bf16 v[82:85], v[158:161], v[216:219], v[82:85]
	v_mfma_f32_16x16x32_bf16 v[74:77], v[168:171], v[216:219], v[74:77]
	s_setprio 0
	s_setprio 1
	v_mfma_f32_16x16x32_bf16 v[114:117], v[172:175], v[188:191], v[114:117]
	v_mfma_f32_16x16x32_bf16 v[106:109], v[180:183], v[188:191], v[106:109]
	v_mfma_f32_16x16x32_bf16 v[98:101], v[172:175], v[196:199], v[98:101]
	v_mfma_f32_16x16x32_bf16 v[90:93], v[180:183], v[196:199], v[90:93]
	v_mfma_f32_16x16x32_bf16 v[86:89], v[172:175], v[204:207], v[86:89]
	v_mfma_f32_16x16x32_bf16 v[78:81], v[180:183], v[204:207], v[78:81]
	v_mfma_f32_16x16x32_bf16 v[70:73], v[172:175], v[212:215], v[70:73]
	v_mfma_f32_16x16x32_bf16 v[66:69], v[180:183], v[212:215], v[66:69]
	v_mfma_f32_16x16x32_bf16 v[114:117], v[176:179], v[192:195], v[114:117]
	v_mfma_f32_16x16x32_bf16 v[106:109], v[184:187], v[192:195], v[106:109]
	v_mfma_f32_16x16x32_bf16 v[98:101], v[176:179], v[200:203], v[98:101]
	v_mfma_f32_16x16x32_bf16 v[90:93], v[184:187], v[200:203], v[90:93]
	v_mfma_f32_16x16x32_bf16 v[86:89], v[176:179], v[208:211], v[86:89]
	v_mfma_f32_16x16x32_bf16 v[78:81], v[184:187], v[208:211], v[78:81]
	v_mfma_f32_16x16x32_bf16 v[70:73], v[176:179], v[216:219], v[70:73]
	v_mfma_f32_16x16x32_bf16 v[66:69], v[184:187], v[216:219], v[66:69]
	s_setprio 0
	s_barrier
	s_add_i32 s26, s54, s31
	v_lshl_add_u64 v[146:147], v[146:147], 0, s[8:9]
	s_mov_b32 m0, s26
	ds_read_b128 v[188:191], v152 offset:49152
	ds_read_b128 v[192:195], v152 offset:50176
	ds_read_b128 v[196:199], v152 offset:51200
	ds_read_b128 v[200:203], v152 offset:52224
	ds_read_b128 v[204:207], v152 offset:53248
	ds_read_b128 v[208:211], v152 offset:54272
	ds_read_b128 v[212:215], v152 offset:55296
	ds_read_b128 v[216:219], v152 offset:56320
	global_load_lds_dwordx4 v[146:147], off
	s_add_i32 m0, s26, 0x2000
	s_add_u32 s24, s24, 0x2b0080
	v_lshl_add_u64 v[146:147], v[220:221], 0, s[8:9]
	s_addc_u32 s25, s25, 0
	s_add_i32 s26, s55, s31
	global_load_lds_dwordx4 v[146:147], off
	v_lshl_add_u64 v[146:147], s[24:25], 0, v[132:133]
	s_mov_b32 m0, s26
	s_nop 0
	global_load_lds_dwordx4 v[146:147], off
	v_lshl_add_u64 v[146:147], s[24:25], 0, v[136:137]
	s_add_i32 m0, s26, 0x2000
	s_nop 0
	global_load_lds_dwordx4 v[146:147], off
	v_lshl_add_u64 v[222:223], v[222:223], 0, s[8:9]
	v_lshl_add_u64 v[224:225], v[224:225], 0, s[8:9]
	s_waitcnt vmcnt(6)
	s_waitcnt lgkmcnt(0)
	s_barrier
	s_setprio 1
	s_waitcnt lgkmcnt(0)
	v_mfma_f32_16x16x32_bf16 v[62:65], v[154:157], v[188:191], v[62:65]
	v_mfma_f32_16x16x32_bf16 v[58:61], v[164:167], v[188:191], v[58:61]
	v_mfma_f32_16x16x32_bf16 v[54:57], v[154:157], v[196:199], v[54:57]
	v_mfma_f32_16x16x32_bf16 v[46:49], v[164:167], v[196:199], v[46:49]
	v_mfma_f32_16x16x32_bf16 v[38:41], v[154:157], v[204:207], v[38:41]
	v_mfma_f32_16x16x32_bf16 v[30:33], v[164:167], v[204:207], v[30:33]
	v_mfma_f32_16x16x32_bf16 v[22:25], v[154:157], v[212:215], v[22:25]
	v_mfma_f32_16x16x32_bf16 v[14:17], v[164:167], v[212:215], v[14:17]
	v_mfma_f32_16x16x32_bf16 v[62:65], v[158:161], v[192:195], v[62:65]
	v_mfma_f32_16x16x32_bf16 v[58:61], v[168:171], v[192:195], v[58:61]
	v_mfma_f32_16x16x32_bf16 v[54:57], v[158:161], v[200:203], v[54:57]
	v_mfma_f32_16x16x32_bf16 v[46:49], v[168:171], v[200:203], v[46:49]
	v_mfma_f32_16x16x32_bf16 v[38:41], v[158:161], v[208:211], v[38:41]
	v_mfma_f32_16x16x32_bf16 v[30:33], v[168:171], v[208:211], v[30:33]
	v_mfma_f32_16x16x32_bf16 v[22:25], v[158:161], v[216:219], v[22:25]
	v_mfma_f32_16x16x32_bf16 v[14:17], v[168:171], v[216:219], v[14:17]
	s_setprio 0
	s_setprio 1
	v_mfma_f32_16x16x32_bf16 v[50:53], v[172:175], v[188:191], v[50:53]
	v_mfma_f32_16x16x32_bf16 v[42:45], v[180:183], v[188:191], v[42:45]
	v_mfma_f32_16x16x32_bf16 v[34:37], v[172:175], v[196:199], v[34:37]
	v_mfma_f32_16x16x32_bf16 v[26:29], v[180:183], v[196:199], v[26:29]
	v_mfma_f32_16x16x32_bf16 v[18:21], v[172:175], v[204:207], v[18:21]
	v_mfma_f32_16x16x32_bf16 v[10:13], v[180:183], v[204:207], v[10:13]
	v_mfma_f32_16x16x32_bf16 v[6:9], v[172:175], v[212:215], v[6:9]
	v_mfma_f32_16x16x32_bf16 v[2:5], v[180:183], v[212:215], v[2:5]
	v_mfma_f32_16x16x32_bf16 v[50:53], v[176:179], v[192:195], v[50:53]
	v_mfma_f32_16x16x32_bf16 v[42:45], v[184:187], v[192:195], v[42:45]
	v_mfma_f32_16x16x32_bf16 v[34:37], v[176:179], v[200:203], v[34:37]
	v_mfma_f32_16x16x32_bf16 v[26:29], v[184:187], v[200:203], v[26:29]
	v_mfma_f32_16x16x32_bf16 v[18:21], v[176:179], v[208:211], v[18:21]
	v_mfma_f32_16x16x32_bf16 v[10:13], v[184:187], v[208:211], v[10:13]
	v_mfma_f32_16x16x32_bf16 v[6:9], v[176:179], v[216:219], v[6:9]
	v_mfma_f32_16x16x32_bf16 v[2:5], v[184:187], v[216:219], v[2:5]
	s_setprio 0
	s_barrier
	s_add_i32 s53, s53, 2
	s_mov_b32 s32, 1
	s_add_u32 s22, s22, 0x100
	s_addc_u32 s23, s23, 0
	s_add_u32 s51, s51, 0x100
	s_addc_u32 s52, s52, 0
	s_cmpk_gt_u32 s53, 0xa9
	s_cbranch_scc0 .LBB0_1853
	s_and_b64 vcc, exec, s[10:11]
	s_cbranch_vccz .LBB0_1856
	s_barrier

.LBB0_1973:
	s_add_u32 s8, s94, 0x3a500000
	s_addc_u32 s9, s95, 0
	s_lshl_b32 s10, s10, 5
	s_and_b32 s16, s10, 0x60
	s_mov_b64 s[10:11], 0x80
	s_add_i32 m0, s29, 0x18000
	v_lshl_add_u64 v[8:9], v[8:9], 0, s[10:11]
	s_lshl_b32 s13, s12, 13
	s_lshl_b32 s17, s16, 7
	s_waitcnt vmcnt(2)
	s_barrier
	global_load_lds_dwordx4 v[8:9], off
	v_lshl_add_u64 v[4:5], v[4:5], 0, s[10:11]
	s_add_i32 m0, s29, 0x1a000
	s_add_i32 s45, s29, 0x8000
	s_add_i32 s46, s29, 0xa000
	global_load_lds_dwordx4 v[4:5], off
	v_lshl_add_u64 v[2:3], v[2:3], 0, s[10:11]
	s_mov_b32 m0, s45
	s_add_u32 s14, s34, 0x100080
	global_load_lds_dwordx4 v[2:3], off
	v_lshl_add_u64 v[2:3], v[6:7], 0, s[10:11]
	s_mov_b32 m0, s46
	s_addc_u32 s15, s35, 0
	global_load_lds_dwordx4 v[2:3], off
	s_add_i32 m0, s29, 0x1c000
	v_lshl_add_u64 v[2:3], s[14:15], 0, v[132:133]
	global_load_lds_dwordx4 v[2:3], off
	v_lshl_add_u64 v[2:3], s[14:15], 0, v[136:137]
	s_add_i32 m0, s29, 0x1e000
	s_sext_i32_i8 s50, s4
	global_load_lds_dwordx4 v[2:3], off
	v_and_b32_e32 v2, 15, v0
	v_lshlrev_b32_e32 v3, 1, v13
	v_lshlrev_b32_e32 v4, 2, v0
	v_lshlrev_b32_e32 v5, 6, v0
	s_movk_i32 s4, 0x3c0
	v_lshl_or_b32 v1, s12, 6, v2
	v_lshl_or_b32 v2, v2, 6, v3
	v_and_b32_e32 v4, 32, v4
	v_and_or_b32 v3, v5, s4, v3
	v_bitop3_b32 v154, s17, v3, v4 bitop3:0xf6
	v_lshlrev_b32_e32 v3, 10, v0
	v_bitop3_b32 v2, v2, s13, v4 bitop3:0xde
	v_and_b32_e32 v3, 0x60000, v3
	v_lshlrev_b32_e32 v4, 13, v12
	v_or3_b32 v3, v10, v3, v4
	v_add_u32_e32 v138, v3, v11
	v_lshlrev_b32_e32 v3, 6, v14
	s_waitcnt vmcnt(6)
	s_cmpk_lt_u32 s5, 0x100
	v_and_b32_e32 v3, 0xe0000, v3
	s_cselect_b64 s[12:13], -1, 0
	v_or3_b32 v3, v10, v3, v4
	s_add_i32 s48, 0, 0x10000
	s_add_i32 s49, 0, 0x14000
	s_ashr_i32 s47, s96, 31
	v_or_b32_e32 v155, s16, v13
	v_mov_b32_e32 v139, v133
	v_add_u32_e32 v140, v3, v11
	v_mov_b32_e32 v141, v133
	v_mov_b64_e32 v[142:143], 0x200
	v_mov_b64_e32 v[144:145], 0x1ff
	v_add_u32_e32 v156, s48, v154
	v_add_u32_e32 v157, s49, v154
	v_add_u32_e32 v158, 0, v2
	s_mov_b64 s[14:15], 0x120000
	s_mov_b64 s[16:17], 0x140000
	s_mov_b64 s[18:19], 0x160000
	s_barrier
	s_mov_b32 s32, 0
	s_branch .LBB0_1976

.LBB0_1983:
	ds_read_b128 v[146:149], v156
	ds_read_b128 v[150:153], v156 offset:1024
	ds_read_b128 v[164:167], v156 offset:2048
	ds_read_b128 v[168:171], v156 offset:3072
	ds_read_b128 v[172:175], v157
	ds_read_b128 v[176:179], v157 offset:1024
	ds_read_b128 v[180:183], v157 offset:2048
	ds_read_b128 v[184:187], v157 offset:3072
	s_add_u32 s34, s30, 0xfff00080
	s_addc_u32 s35, s31, -1
	s_cmp_eq_u32 s55, 60
	s_cselect_b32 s37, s23, s35
	s_cselect_b32 s36, s51, s34
	s_cselect_b32 s35, s21, s54
	s_cselect_b32 s34, s52, s53
	v_lshl_add_u64 v[160:161], s[30:31], 0, v[138:139]
	s_add_i32 m0, s29, 0xc000
	ds_read_b128 v[188:191], v158
	ds_read_b128 v[192:195], v158 offset:1024
	ds_read_b128 v[196:199], v158 offset:2048
	ds_read_b128 v[200:203], v158 offset:3072
	ds_read_b128 v[204:207], v158 offset:4096
	ds_read_b128 v[208:211], v158 offset:5120
	ds_read_b128 v[212:215], v158 offset:6144
	ds_read_b128 v[216:219], v158 offset:7168
	s_cmp_lg_u32 s32, 0
	s_cbranch_scc0 .Lrebal_skip_1983
	s_mov_b32 m0, s45
	s_nop 0
	global_load_lds_dwordx4 v[222:223], off
	s_mov_b32 m0, s46
	s_nop 0
	global_load_lds_dwordx4 v[224:225], off
.Lrebal_skip_1983:
	s_add_i32 m0, s29, 0xc000
	s_nop 0
	global_load_lds_dwordx4 v[160:161], off
	v_lshl_add_u64 v[160:161], s[30:31], 0, v[140:141]
	s_add_i32 m0, s29, 0xe000
	s_nop 0
	global_load_lds_dwordx4 v[160:161], off
	s_waitcnt vmcnt(8)
	s_waitcnt lgkmcnt(0)
	s_barrier
	s_setprio 1
	s_waitcnt lgkmcnt(0)
	v_mfma_f32_16x16x32_bf16 v[126:129], v[146:149], v[188:191], v[126:129]
	v_mfma_f32_16x16x32_bf16 v[122:125], v[164:167], v[188:191], v[122:125]
	v_mfma_f32_16x16x32_bf16 v[110:113], v[146:149], v[196:199], v[110:113]
	v_mfma_f32_16x16x32_bf16 v[106:109], v[164:167], v[196:199], v[106:109]
	v_mfma_f32_16x16x32_bf16 v[94:97], v[146:149], v[204:207], v[94:97]
	v_mfma_f32_16x16x32_bf16 v[90:93], v[164:167], v[204:207], v[90:93]
	v_mfma_f32_16x16x32_bf16 v[78:81], v[146:149], v[212:215], v[78:81]
	v_mfma_f32_16x16x32_bf16 v[74:77], v[164:167], v[212:215], v[74:77]
	v_mfma_f32_16x16x32_bf16 v[126:129], v[150:153], v[192:195], v[126:129]
	v_mfma_f32_16x16x32_bf16 v[122:125], v[168:171], v[192:195], v[122:125]
	v_mfma_f32_16x16x32_bf16 v[110:113], v[150:153], v[200:203], v[110:113]
	v_mfma_f32_16x16x32_bf16 v[106:109], v[168:171], v[200:203], v[106:109]
	v_mfma_f32_16x16x32_bf16 v[94:97], v[150:153], v[208:211], v[94:97]
	v_mfma_f32_16x16x32_bf16 v[90:93], v[168:171], v[208:211], v[90:93]
	v_mfma_f32_16x16x32_bf16 v[78:81], v[150:153], v[216:219], v[78:81]
	v_mfma_f32_16x16x32_bf16 v[74:77], v[168:171], v[216:219], v[74:77]
	s_setprio 0
	s_setprio 1
	v_mfma_f32_16x16x32_bf16 v[118:121], v[172:175], v[188:191], v[118:121]
	v_mfma_f32_16x16x32_bf16 v[114:117], v[180:183], v[188:191], v[114:117]
	v_mfma_f32_16x16x32_bf16 v[102:105], v[172:175], v[196:199], v[102:105]
	v_mfma_f32_16x16x32_bf16 v[98:101], v[180:183], v[196:199], v[98:101]
	v_mfma_f32_16x16x32_bf16 v[86:89], v[172:175], v[204:207], v[86:89]
	v_mfma_f32_16x16x32_bf16 v[82:85], v[180:183], v[204:207], v[82:85]
	v_mfma_f32_16x16x32_bf16 v[70:73], v[172:175], v[212:215], v[70:73]
	v_mfma_f32_16x16x32_bf16 v[66:69], v[180:183], v[212:215], v[66:69]
	v_mfma_f32_16x16x32_bf16 v[118:121], v[176:179], v[192:195], v[118:121]
	v_mfma_f32_16x16x32_bf16 v[114:117], v[184:187], v[192:195], v[114:117]
	v_mfma_f32_16x16x32_bf16 v[102:105], v[176:179], v[200:203], v[102:105]
	v_mfma_f32_16x16x32_bf16 v[98:101], v[184:187], v[200:203], v[98:101]
	v_mfma_f32_16x16x32_bf16 v[86:89], v[176:179], v[208:211], v[86:89]
	v_mfma_f32_16x16x32_bf16 v[82:85], v[184:187], v[208:211], v[82:85]
	v_mfma_f32_16x16x32_bf16 v[70:73], v[176:179], v[216:219], v[70:73]
	v_mfma_f32_16x16x32_bf16 v[66:69], v[184:187], v[216:219], v[66:69]
	s_setprio 0
	s_barrier
	s_add_i32 s56, s48, s40
	v_lshl_add_u64 v[160:161], s[34:35], 0, v[132:133]
	s_mov_b32 m0, s56
	ds_read_b128 v[188:191], v158 offset:16384
	ds_read_b128 v[192:195], v158 offset:17408
	ds_read_b128 v[196:199], v158 offset:18432
	ds_read_b128 v[200:203], v158 offset:19456
	ds_read_b128 v[204:207], v158 offset:20480
	ds_read_b128 v[208:211], v158 offset:21504
	ds_read_b128 v[212:215], v158 offset:22528
	ds_read_b128 v[216:219], v158 offset:23552
	global_load_lds_dwordx4 v[160:161], off
	s_add_i32 m0, s56, 0x2000
	s_add_u32 s56, s34, 0x100000
	v_lshl_add_u64 v[220:221], s[34:35], 0, v[136:137]
	s_addc_u32 s57, s35, 0
	s_add_i32 s58, s49, s40
	global_load_lds_dwordx4 v[220:221], off
	v_lshl_add_u64 v[222:223], s[56:57], 0, v[132:133]
	s_mov_b32 m0, s58
	v_lshl_add_u64 v[224:225], s[36:37], 0, v[134:135]
	global_load_lds_dwordx4 v[222:223], off
	v_lshl_add_u64 v[222:223], s[56:57], 0, v[136:137]
	s_add_i32 m0, s58, 0x2000
	s_nop 0
	global_load_lds_dwordx4 v[222:223], off
	v_lshl_add_u64 v[222:223], s[36:37], 0, v[130:131]
	s_waitcnt vmcnt(6)
	s_waitcnt lgkmcnt(0)
	s_barrier
	s_setprio 1
	s_waitcnt lgkmcnt(0)
	v_mfma_f32_16x16x32_bf16 v[62:65], v[146:149], v[188:191], v[62:65]
	v_mfma_f32_16x16x32_bf16 v[58:61], v[164:167], v[188:191], v[58:61]
	v_mfma_f32_16x16x32_bf16 v[46:49], v[146:149], v[196:199], v[46:49]
	v_mfma_f32_16x16x32_bf16 v[42:45], v[164:167], v[196:199], v[42:45]
	v_mfma_f32_16x16x32_bf16 v[30:33], v[146:149], v[204:207], v[30:33]
	v_mfma_f32_16x16x32_bf16 v[26:29], v[164:167], v[204:207], v[26:29]
	v_mfma_f32_16x16x32_bf16 v[14:17], v[146:149], v[212:215], v[14:17]
	v_mfma_f32_16x16x32_bf16 v[10:13], v[164:167], v[212:215], v[10:13]
	v_mfma_f32_16x16x32_bf16 v[62:65], v[150:153], v[192:195], v[62:65]
	v_mfma_f32_16x16x32_bf16 v[58:61], v[168:171], v[192:195], v[58:61]
	v_mfma_f32_16x16x32_bf16 v[46:49], v[150:153], v[200:203], v[46:49]
	v_mfma_f32_16x16x32_bf16 v[42:45], v[168:171], v[200:203], v[42:45]
	v_mfma_f32_16x16x32_bf16 v[30:33], v[150:153], v[208:211], v[30:33]
	v_mfma_f32_16x16x32_bf16 v[26:29], v[168:171], v[208:211], v[26:29]
	v_mfma_f32_16x16x32_bf16 v[14:17], v[150:153], v[216:219], v[14:17]
	v_mfma_f32_16x16x32_bf16 v[10:13], v[168:171], v[216:219], v[10:13]
	s_setprio 0
	s_setprio 1
	v_mfma_f32_16x16x32_bf16 v[54:57], v[172:175], v[188:191], v[54:57]
	v_mfma_f32_16x16x32_bf16 v[50:53], v[180:183], v[188:191], v[50:53]
	v_mfma_f32_16x16x32_bf16 v[38:41], v[172:175], v[196:199], v[38:41]
	v_mfma_f32_16x16x32_bf16 v[34:37], v[180:183], v[196:199], v[34:37]
	v_mfma_f32_16x16x32_bf16 v[22:25], v[172:175], v[204:207], v[22:25]
	v_mfma_f32_16x16x32_bf16 v[18:21], v[180:183], v[204:207], v[18:21]
	v_mfma_f32_16x16x32_bf16 v[6:9], v[172:175], v[212:215], v[6:9]
	v_mfma_f32_16x16x32_bf16 v[2:5], v[180:183], v[212:215], v[2:5]
	v_mfma_f32_16x16x32_bf16 v[54:57], v[176:179], v[192:195], v[54:57]
	v_mfma_f32_16x16x32_bf16 v[50:53], v[184:187], v[192:195], v[50:53]
	v_mfma_f32_16x16x32_bf16 v[38:41], v[176:179], v[200:203], v[38:41]
	v_mfma_f32_16x16x32_bf16 v[34:37], v[184:187], v[200:203], v[34:37]
	v_mfma_f32_16x16x32_bf16 v[22:25], v[176:179], v[208:211], v[22:25]
	v_mfma_f32_16x16x32_bf16 v[18:21], v[184:187], v[208:211], v[18:21]
	v_mfma_f32_16x16x32_bf16 v[6:9], v[176:179], v[216:219], v[6:9]
	v_mfma_f32_16x16x32_bf16 v[2:5], v[184:187], v[216:219], v[2:5]
	s_setprio 0
	s_barrier
	s_add_i32 s56, 0, 0x18000
	v_add_u32_e32 v159, s56, v154
	s_add_i32 s57, 0, 0x1c000
	ds_read_b128 v[146:149], v159
	ds_read_b128 v[150:153], v159 offset:1024
	ds_read_b128 v[164:167], v159 offset:2048
	ds_read_b128 v[168:171], v159 offset:3072
	v_add_u32_e32 v159, s57, v154
	ds_read_b128 v[172:175], v159
	ds_read_b128 v[176:179], v159 offset:1024
	ds_read_b128 v[180:183], v159 offset:2048
	ds_read_b128 v[184:187], v159 offset:3072
	s_add_u32 s36, s36, 0x100000
	s_addc_u32 s37, s37, 0
	s_mov_b32 m0, s42
	v_lshl_add_u64 v[226:227], s[36:37], 0, v[130:131]
	ds_read_b128 v[188:191], v158 offset:32768
	ds_read_b128 v[192:195], v158 offset:33792
	ds_read_b128 v[196:199], v158 offset:34816
	ds_read_b128 v[200:203], v158 offset:35840
	ds_read_b128 v[204:207], v158 offset:36864
	ds_read_b128 v[208:211], v158 offset:37888
	ds_read_b128 v[212:215], v158 offset:38912
	ds_read_b128 v[216:219], v158 offset:39936
	s_mov_b32 m0, s29
	s_nop 0
	global_load_lds_dwordx4 v[222:223], off
	s_mov_b32 m0, s41
	s_nop 0
	global_load_lds_dwordx4 v[224:225], off
	s_mov_b32 m0, s42
	s_nop 0
	global_load_lds_dwordx4 v[226:227], off
	v_lshl_add_u64 v[226:227], s[36:37], 0, v[134:135]
	s_mov_b32 m0, s43
	s_nop 0
	global_load_lds_dwordx4 v[226:227], off
	s_waitcnt vmcnt(8)
	s_waitcnt lgkmcnt(0)
	s_barrier
	s_setprio 1
	s_waitcnt lgkmcnt(0)
	v_mfma_f32_16x16x32_bf16 v[126:129], v[146:149], v[188:191], v[126:129]
	v_mfma_f32_16x16x32_bf16 v[122:125], v[164:167], v[188:191], v[122:125]
	v_mfma_f32_16x16x32_bf16 v[110:113], v[146:149], v[196:199], v[110:113]
	v_mfma_f32_16x16x32_bf16 v[106:109], v[164:167], v[196:199], v[106:109]
	v_mfma_f32_16x16x32_bf16 v[94:97], v[146:149], v[204:207], v[94:97]
	v_mfma_f32_16x16x32_bf16 v[90:93], v[164:167], v[204:207], v[90:93]
	v_mfma_f32_16x16x32_bf16 v[78:81], v[146:149], v[212:215], v[78:81]
	v_mfma_f32_16x16x32_bf16 v[74:77], v[164:167], v[212:215], v[74:77]
	v_mfma_f32_16x16x32_bf16 v[126:129], v[150:153], v[192:195], v[126:129]
	v_mfma_f32_16x16x32_bf16 v[122:125], v[168:171], v[192:195], v[122:125]
	v_mfma_f32_16x16x32_bf16 v[110:113], v[150:153], v[200:203], v[110:113]
	v_mfma_f32_16x16x32_bf16 v[106:109], v[168:171], v[200:203], v[106:109]
	v_mfma_f32_16x16x32_bf16 v[94:97], v[150:153], v[208:211], v[94:97]
	v_mfma_f32_16x16x32_bf16 v[90:93], v[168:171], v[208:211], v[90:93]
	v_mfma_f32_16x16x32_bf16 v[78:81], v[150:153], v[216:219], v[78:81]
	v_mfma_f32_16x16x32_bf16 v[74:77], v[168:171], v[216:219], v[74:77]
	s_setprio 0
	s_setprio 1
	v_mfma_f32_16x16x32_bf16 v[118:121], v[172:175], v[188:191], v[118:121]
	v_mfma_f32_16x16x32_bf16 v[114:117], v[180:183], v[188:191], v[114:117]
	v_mfma_f32_16x16x32_bf16 v[102:105], v[172:175], v[196:199], v[102:105]
	v_mfma_f32_16x16x32_bf16 v[98:101], v[180:183], v[196:199], v[98:101]
	v_mfma_f32_16x16x32_bf16 v[86:89], v[172:175], v[204:207], v[86:89]
	v_mfma_f32_16x16x32_bf16 v[82:85], v[180:183], v[204:207], v[82:85]
	v_mfma_f32_16x16x32_bf16 v[70:73], v[172:175], v[212:215], v[70:73]
	v_mfma_f32_16x16x32_bf16 v[66:69], v[180:183], v[212:215], v[66:69]
	v_mfma_f32_16x16x32_bf16 v[118:121], v[176:179], v[192:195], v[118:121]
	v_mfma_f32_16x16x32_bf16 v[114:117], v[184:187], v[192:195], v[114:117]
	v_mfma_f32_16x16x32_bf16 v[102:105], v[176:179], v[200:203], v[102:105]
	v_mfma_f32_16x16x32_bf16 v[98:101], v[184:187], v[200:203], v[98:101]
	v_mfma_f32_16x16x32_bf16 v[86:89], v[176:179], v[208:211], v[86:89]
	v_mfma_f32_16x16x32_bf16 v[82:85], v[184:187], v[208:211], v[82:85]
	v_mfma_f32_16x16x32_bf16 v[70:73], v[176:179], v[216:219], v[70:73]
	v_mfma_f32_16x16x32_bf16 v[66:69], v[184:187], v[216:219], v[66:69]
	s_setprio 0
	s_barrier
	s_add_i32 s36, s56, s40
	v_lshl_add_u64 v[160:161], v[160:161], 0, s[10:11]
	s_mov_b32 m0, s36
	ds_read_b128 v[188:191], v158 offset:49152
	ds_read_b128 v[192:195], v158 offset:50176
	ds_read_b128 v[196:199], v158 offset:51200
	ds_read_b128 v[200:203], v158 offset:52224
	ds_read_b128 v[204:207], v158 offset:53248
	ds_read_b128 v[208:211], v158 offset:54272
	ds_read_b128 v[212:215], v158 offset:55296
	ds_read_b128 v[216:219], v158 offset:56320
	global_load_lds_dwordx4 v[160:161], off
	s_add_i32 m0, s36, 0x2000
	s_add_u32 s34, s34, 0x100080
	v_lshl_add_u64 v[160:161], v[220:221], 0, s[10:11]
	s_addc_u32 s35, s35, 0
	s_add_i32 s36, s57, s40
	global_load_lds_dwordx4 v[160:161], off
	v_lshl_add_u64 v[160:161], s[34:35], 0, v[132:133]
	s_mov_b32 m0, s36
	s_nop 0
	global_load_lds_dwordx4 v[160:161], off
	v_lshl_add_u64 v[160:161], s[34:35], 0, v[136:137]
	s_add_i32 m0, s36, 0x2000
	s_nop 0
	global_load_lds_dwordx4 v[160:161], off
	v_lshl_add_u64 v[222:223], v[222:223], 0, s[10:11]
	v_lshl_add_u64 v[224:225], v[224:225], 0, s[10:11]
	s_waitcnt vmcnt(6)
	s_waitcnt lgkmcnt(0)
	s_barrier
	s_setprio 1
	s_waitcnt lgkmcnt(0)
	v_mfma_f32_16x16x32_bf16 v[62:65], v[146:149], v[188:191], v[62:65]
	v_mfma_f32_16x16x32_bf16 v[58:61], v[164:167], v[188:191], v[58:61]
	v_mfma_f32_16x16x32_bf16 v[46:49], v[146:149], v[196:199], v[46:49]
	v_mfma_f32_16x16x32_bf16 v[42:45], v[164:167], v[196:199], v[42:45]
	v_mfma_f32_16x16x32_bf16 v[30:33], v[146:149], v[204:207], v[30:33]
	v_mfma_f32_16x16x32_bf16 v[26:29], v[164:167], v[204:207], v[26:29]
	v_mfma_f32_16x16x32_bf16 v[14:17], v[146:149], v[212:215], v[14:17]
	v_mfma_f32_16x16x32_bf16 v[10:13], v[164:167], v[212:215], v[10:13]
	v_mfma_f32_16x16x32_bf16 v[62:65], v[150:153], v[192:195], v[62:65]
	v_mfma_f32_16x16x32_bf16 v[58:61], v[168:171], v[192:195], v[58:61]
	v_mfma_f32_16x16x32_bf16 v[46:49], v[150:153], v[200:203], v[46:49]
	v_mfma_f32_16x16x32_bf16 v[42:45], v[168:171], v[200:203], v[42:45]
	v_mfma_f32_16x16x32_bf16 v[30:33], v[150:153], v[208:211], v[30:33]
	v_mfma_f32_16x16x32_bf16 v[26:29], v[168:171], v[208:211], v[26:29]
	v_mfma_f32_16x16x32_bf16 v[14:17], v[150:153], v[216:219], v[14:17]
	v_mfma_f32_16x16x32_bf16 v[10:13], v[168:171], v[216:219], v[10:13]
	s_setprio 0
	s_setprio 1
	v_mfma_f32_16x16x32_bf16 v[54:57], v[172:175], v[188:191], v[54:57]
	v_mfma_f32_16x16x32_bf16 v[50:53], v[180:183], v[188:191], v[50:53]
	v_mfma_f32_16x16x32_bf16 v[38:41], v[172:175], v[196:199], v[38:41]
	v_mfma_f32_16x16x32_bf16 v[34:37], v[180:183], v[196:199], v[34:37]
	v_mfma_f32_16x16x32_bf16 v[22:25], v[172:175], v[204:207], v[22:25]
	v_mfma_f32_16x16x32_bf16 v[18:21], v[180:183], v[204:207], v[18:21]
	v_mfma_f32_16x16x32_bf16 v[6:9], v[172:175], v[212:215], v[6:9]
	v_mfma_f32_16x16x32_bf16 v[2:5], v[180:183], v[212:215], v[2:5]
	v_mfma_f32_16x16x32_bf16 v[54:57], v[176:179], v[192:195], v[54:57]
	v_mfma_f32_16x16x32_bf16 v[50:53], v[184:187], v[192:195], v[50:53]
	v_mfma_f32_16x16x32_bf16 v[38:41], v[176:179], v[200:203], v[38:41]
	v_mfma_f32_16x16x32_bf16 v[34:37], v[184:187], v[200:203], v[34:37]
	v_mfma_f32_16x16x32_bf16 v[22:25], v[176:179], v[208:211], v[22:25]
	v_mfma_f32_16x16x32_bf16 v[18:21], v[184:187], v[208:211], v[18:21]
	v_mfma_f32_16x16x32_bf16 v[6:9], v[176:179], v[216:219], v[6:9]
	v_mfma_f32_16x16x32_bf16 v[2:5], v[184:187], v[216:219], v[2:5]
	s_setprio 0
	s_barrier
	s_add_i32 s55, s55, 2
	s_mov_b32 s32, 1
	s_add_u32 s30, s30, 0x100
	s_addc_u32 s31, s31, 0
	s_add_u32 s53, s53, 0x100
	s_addc_u32 s54, s54, 0
	s_cmp_gt_u32 s55, 61
	s_cbranch_scc0 .LBB0_1983
	s_and_b64 vcc, exec, s[12:13]
	s_cbranch_vccz .LBB0_1986
	s_barrier
